# attention loops: drop vmcnt waits inside MFMA groups (Q loads retire before the loop); O-proj epilogue: waits only after its own f32 loads; K-loop: setprio moved outside the barrier pair
# speedup vs baseline: 1.0184x; 1.0075x over previous
; #define PG8_STAGE(bufoff, gbase, voff) do { _Pragma("unroll") for (int _i = 0; _i < 2; ++_i) \
;         __builtin_amdgcn_global_load_lds((const unsigned*)((const char*)(gbase) + (voff)[_i]), (PG8_LAS unsigned*)(lds + (bufoff) + ldsw + _i * 8192), 16, 0, 0); } while (0)
; #define PG8_LDA(dst, b, h) do { _Pragma("unroll") for (int m = 0; m < 4; ++m) _Pragma("unroll") for (int k = 0; k < 2; ++k) dst[m][k] = *(const PG8_LAS bf16x8*)(lds + PG8_SA(b, h) + aoff + m * 2048 + k * 1024); } while (0)
; #define PG8_LDB(dst, b, h) do { _Pragma("unroll") for (int n = 0; n < 2; ++n) _Pragma("unroll") for (int k = 0; k < 2; ++k) dst[n][k] = *(const PG8_LAS bf16x8*)(lds + PG8_SB(b, h) + boff + n * 2048 + k * 1024); } while (0)
; #define PG8_MMA(ai, bj, At, Bt) do { __builtin_amdgcn_s_setprio(1); _Pragma("unroll") for (int m = 0; m < 4; ++m) _Pragma("unroll") for (int n = 0; n < 2; ++n) _Pragma("unroll") for (int k = 0; k < 2; ++k) \
;         acc[ai][bj][m][n] = __builtin_amdgcn_mfma_f32_16x16x32_bf16(Bt[n][k], At[m][k], acc[ai][bj][m][n], 0, 0, 0); __builtin_amdgcn_s_setprio(0); } while (0)
; #define PG8_WAIT_V(n) asm volatile("s_waitcnt vmcnt(" #n ")" ::: "memory")
; #define PG8_WAIT_L(n) asm volatile("s_waitcnt lgkmcnt(" #n ")" ::: "memory")
; #define PG8_BAR __builtin_amdgcn_s_barrier()
; #define PG8_SCHED __builtin_amdgcn_sched_barrier(0)
; template <class Epi, class Sched, bool ALIGN_EPI = false, bool SP2 = false>
; __device__ __forceinline__ void gemm_phase(PG8_LAS unsigned char* lds, const Gemm g, const Sched& S, const Epi& E, const int wave_s) {
;     ...
;             PG8_LDB(B0, 0, 0); PG8_LDB(B1, 0, 1); PG8_SCHED; PG8_LDA(At, 0, 0); PG8_STAGE(PG8_SA(1, 1), a1 + hstep, voffA);
;             PG8_WAIT_V(8); PG8_WAIT_L(0); PG8_BAR; PG8_MMA(0, 0, At, B0); PG8_MMA(0, 1, At, B1); PG8_BAR; PG8_SCHED;
;             PG8_LDA(At, 0, 1); PG8_STAGE(PG8_SB(0, 0), b2, voffB); PG8_STAGE(PG8_SB(0, 1), b2 + hstep, voffB); PG8_STAGE(PG8_SA(0, 0), a2, voffA);
;             PG8_WAIT_V(8); PG8_WAIT_L(0); PG8_BAR; PG8_MMA(1, 0, At, B0); PG8_MMA(1, 1, At, B1); PG8_BAR; PG8_SCHED;
.LBB0_203:
	s_add_u32 s50, s4, 0xfffc0080
	s_addc_u32 s51, s5, -1
	s_add_i32 s58, 0, 0x10000
	s_cmp_eq_u32 s57, 12
	s_cselect_b32 s53, s3, s51
	s_cselect_b32 s52, s43, s50
	v_add_u32_e32 v0, s58, v236
	s_cselect_b32 s51, s41, s56
	s_cselect_b32 s50, s54, s55
	s_add_i32 s60, 0, 0x14000
	ds_read_b128 v[114:117], v0
	ds_read_b128 v[126:129], v0 offset:1024
	ds_read_b128 v[138:141], v0 offset:2048
	ds_read_b128 v[142:145], v0 offset:3072
	v_add_u32_e32 v0, s60, v236
	ds_read_b128 v[146:149], v0
	ds_read_b128 v[150:153], v0 offset:1024
	ds_read_b128 v[154:157], v0 offset:2048
	ds_read_b128 v[158:161], v0 offset:3072
	v_lshl_add_u64 v[208:209], s[4:5], 0, v[186:187]
	s_add_i32 m0, s49, 0xc000
	ds_read_b128 v[162:165], v237
	ds_read_b128 v[166:169], v237 offset:1024
	ds_read_b128 v[170:173], v237 offset:2048
	ds_read_b128 v[174:177], v237 offset:3072
	ds_read_b128 v[190:193], v237 offset:4096
	ds_read_b128 v[194:197], v237 offset:5120
	ds_read_b128 v[198:201], v237 offset:6144
	ds_read_b128 v[204:207], v237 offset:7168
	global_load_lds_dwordx4 v[208:209], off
	v_lshl_add_u64 v[208:209], s[4:5], 0, v[188:189]
	s_add_i32 m0, s49, 0xe000
	s_nop 0
	global_load_lds_dwordx4 v[208:209], off
	s_waitcnt vmcnt(8)
	s_waitcnt lgkmcnt(0)
	s_setprio 1
	s_barrier
	v_mfma_f32_16x16x32_bf16 v[134:137], v[114:117], v[162:165], v[134:137]
	v_mfma_f32_16x16x32_bf16 v[130:133], v[138:141], v[162:165], v[130:133]
	v_mfma_f32_16x16x32_bf16 v[110:113], v[114:117], v[170:173], v[110:113]
	v_mfma_f32_16x16x32_bf16 v[106:109], v[138:141], v[170:173], v[106:109]
	v_mfma_f32_16x16x32_bf16 v[94:97], v[114:117], v[190:193], v[94:97]
	v_mfma_f32_16x16x32_bf16 v[90:93], v[138:141], v[190:193], v[90:93]
	v_mfma_f32_16x16x32_bf16 v[78:81], v[114:117], v[198:201], v[78:81]
	v_mfma_f32_16x16x32_bf16 v[74:77], v[138:141], v[198:201], v[74:77]
	v_mfma_f32_16x16x32_bf16 v[134:137], v[126:129], v[166:169], v[134:137]
	v_mfma_f32_16x16x32_bf16 v[130:133], v[142:145], v[166:169], v[130:133]
	v_mfma_f32_16x16x32_bf16 v[110:113], v[126:129], v[174:177], v[110:113]
	v_mfma_f32_16x16x32_bf16 v[106:109], v[142:145], v[174:177], v[106:109]
	v_mfma_f32_16x16x32_bf16 v[94:97], v[126:129], v[194:197], v[94:97]
	v_mfma_f32_16x16x32_bf16 v[90:93], v[142:145], v[194:197], v[90:93]
	v_mfma_f32_16x16x32_bf16 v[78:81], v[126:129], v[204:207], v[78:81]
	v_mfma_f32_16x16x32_bf16 v[74:77], v[142:145], v[204:207], v[74:77]
	v_mfma_f32_16x16x32_bf16 v[122:125], v[146:149], v[162:165], v[122:125]
	v_mfma_f32_16x16x32_bf16 v[118:121], v[154:157], v[162:165], v[118:121]
	v_mfma_f32_16x16x32_bf16 v[102:105], v[146:149], v[170:173], v[102:105]
	v_mfma_f32_16x16x32_bf16 v[98:101], v[154:157], v[170:173], v[98:101]
	v_mfma_f32_16x16x32_bf16 v[86:89], v[146:149], v[190:193], v[86:89]
	v_mfma_f32_16x16x32_bf16 v[82:85], v[154:157], v[190:193], v[82:85]
	v_mfma_f32_16x16x32_bf16 v[70:73], v[146:149], v[198:201], v[70:73]
	v_mfma_f32_16x16x32_bf16 v[66:69], v[154:157], v[198:201], v[66:69]
	v_mfma_f32_16x16x32_bf16 v[122:125], v[150:153], v[166:169], v[122:125]
	v_mfma_f32_16x16x32_bf16 v[118:121], v[158:161], v[166:169], v[118:121]
	v_mfma_f32_16x16x32_bf16 v[102:105], v[150:153], v[174:177], v[102:105]
	v_mfma_f32_16x16x32_bf16 v[98:101], v[158:161], v[174:177], v[98:101]
	v_mfma_f32_16x16x32_bf16 v[86:89], v[150:153], v[194:197], v[86:89]
	v_mfma_f32_16x16x32_bf16 v[82:85], v[158:161], v[194:197], v[82:85]
	v_mfma_f32_16x16x32_bf16 v[70:73], v[150:153], v[204:207], v[70:73]
	v_mfma_f32_16x16x32_bf16 v[66:69], v[158:161], v[204:207], v[66:69]
	s_barrier
	s_setprio 0
	s_add_i32 s58, s58, s65
	v_lshl_add_u64 v[208:209], s[50:51], 0, v[180:181]
	s_mov_b32 m0, s58
	ds_read_b128 v[162:165], v237 offset:16384
	ds_read_b128 v[166:169], v237 offset:17408
	ds_read_b128 v[170:173], v237 offset:18432
	ds_read_b128 v[174:177], v237 offset:19456
	ds_read_b128 v[190:193], v237 offset:20480
	ds_read_b128 v[194:197], v237 offset:21504
	ds_read_b128 v[198:201], v237 offset:22528
	ds_read_b128 v[204:207], v237 offset:23552
	global_load_lds_dwordx4 v[208:209], off
	s_add_i32 m0, s58, 0x2000
	s_add_u32 s58, s50, 0x40000
	v_lshl_add_u64 v[210:211], s[50:51], 0, v[184:185]
	s_addc_u32 s59, s51, 0
	s_add_i32 s60, s60, s65
	global_load_lds_dwordx4 v[210:211], off
	v_lshl_add_u64 v[212:213], s[58:59], 0, v[180:181]
	s_mov_b32 m0, s60
	v_lshl_add_u64 v[214:215], s[52:53], 0, v[182:183]
	global_load_lds_dwordx4 v[212:213], off
	v_lshl_add_u64 v[212:213], s[58:59], 0, v[184:185]
	s_add_i32 m0, s60, 0x2000
	s_nop 0
	global_load_lds_dwordx4 v[212:213], off
	v_lshl_add_u64 v[212:213], s[52:53], 0, v[178:179]
	s_mov_b32 m0, s49
	s_nop 0
	global_load_lds_dwordx4 v[212:213], off
	s_mov_b32 m0, s66
	s_nop 0
	global_load_lds_dwordx4 v[214:215], off
	s_waitcnt vmcnt(8)
	s_waitcnt lgkmcnt(0)
	s_setprio 1
	s_barrier
; #define PG8_STAGE(bufoff, gbase, voff) do { _Pragma("unroll") for (int _i = 0; _i < 2; ++_i) \
;         __builtin_amdgcn_global_load_lds((const unsigned*)((const char*)(gbase) + (voff)[_i]), (PG8_LAS unsigned*)(lds + (bufoff) + ldsw + _i * 8192), 16, 0, 0); } while (0)
; #define PG8_LDA(dst, b, h) do { _Pragma("unroll") for (int m = 0; m < 4; ++m) _Pragma("unroll") for (int k = 0; k < 2; ++k) dst[m][k] = *(const PG8_LAS bf16x8*)(lds + PG8_SA(b, h) + aoff + m * 2048 + k * 1024); } while (0)
; #define PG8_LDB(dst, b, h) do { _Pragma("unroll") for (int n = 0; n < 2; ++n) _Pragma("unroll") for (int k = 0; k < 2; ++k) dst[n][k] = *(const PG8_LAS bf16x8*)(lds + PG8_SB(b, h) + boff + n * 2048 + k * 1024); } while (0)
; #define PG8_MMA(ai, bj, At, Bt) do { __builtin_amdgcn_s_setprio(1); _Pragma("unroll") for (int m = 0; m < 4; ++m) _Pragma("unroll") for (int n = 0; n < 2; ++n) _Pragma("unroll") for (int k = 0; k < 2; ++k) \
;         acc[ai][bj][m][n] = __builtin_amdgcn_mfma_f32_16x16x32_bf16(Bt[n][k], At[m][k], acc[ai][bj][m][n], 0, 0, 0); __builtin_amdgcn_s_setprio(0); } while (0)
; #define PG8_WAIT_V(n) asm volatile("s_waitcnt vmcnt(" #n ")" ::: "memory")
; #define PG8_WAIT_L(n) asm volatile("s_waitcnt lgkmcnt(" #n ")" ::: "memory")
; #define PG8_BAR __builtin_amdgcn_s_barrier()
; #define PG8_SCHED __builtin_amdgcn_sched_barrier(0)
; template <class Epi, class Sched, bool ALIGN_EPI = false, bool SP2 = false>
; __device__ __forceinline__ void gemm_phase(PG8_LAS unsigned char* lds, const Gemm g, const Sched& S, const Epi& E, const int wave_s) {
;     ...
;             PG8_WAIT_V(8); PG8_WAIT_L(0); PG8_BAR; PG8_MMA(1, 0, At, B0); PG8_MMA(1, 1, At, B1); PG8_BAR; PG8_SCHED;
;             PG8_LDB(B0, 1, 0); PG8_LDB(B1, 1, 1); PG8_SCHED; PG8_LDA(At, 1, 0); PG8_STAGE(PG8_SA(0, 1), a2 + hstep, voffA);
;             PG8_WAIT_V(8); PG8_WAIT_L(0); PG8_BAR; PG8_MMA(0, 0, At, B0); PG8_MMA(0, 1, At, B1); PG8_BAR; PG8_SCHED;
	v_mfma_f32_16x16x32_bf16 v[62:65], v[114:117], v[162:165], v[62:65]
	v_mfma_f32_16x16x32_bf16 v[58:61], v[138:141], v[162:165], v[58:61]
	v_mfma_f32_16x16x32_bf16 v[46:49], v[114:117], v[170:173], v[46:49]
	v_mfma_f32_16x16x32_bf16 v[42:45], v[138:141], v[170:173], v[42:45]
	v_mfma_f32_16x16x32_bf16 v[30:33], v[114:117], v[190:193], v[30:33]
	v_mfma_f32_16x16x32_bf16 v[26:29], v[138:141], v[190:193], v[26:29]
	v_mfma_f32_16x16x32_bf16 v[14:17], v[114:117], v[198:201], v[14:17]
	v_mfma_f32_16x16x32_bf16 v[10:13], v[138:141], v[198:201], v[10:13]
	v_mfma_f32_16x16x32_bf16 v[62:65], v[126:129], v[166:169], v[62:65]
	v_mfma_f32_16x16x32_bf16 v[58:61], v[142:145], v[166:169], v[58:61]
	v_mfma_f32_16x16x32_bf16 v[46:49], v[126:129], v[174:177], v[46:49]
	v_mfma_f32_16x16x32_bf16 v[42:45], v[142:145], v[174:177], v[42:45]
	v_mfma_f32_16x16x32_bf16 v[30:33], v[126:129], v[194:197], v[30:33]
	v_mfma_f32_16x16x32_bf16 v[26:29], v[142:145], v[194:197], v[26:29]
	v_mfma_f32_16x16x32_bf16 v[14:17], v[126:129], v[204:207], v[14:17]
	v_mfma_f32_16x16x32_bf16 v[10:13], v[142:145], v[204:207], v[10:13]
	v_mfma_f32_16x16x32_bf16 v[54:57], v[146:149], v[162:165], v[54:57]
	v_mfma_f32_16x16x32_bf16 v[50:53], v[154:157], v[162:165], v[50:53]
	v_mfma_f32_16x16x32_bf16 v[38:41], v[146:149], v[170:173], v[38:41]
	v_mfma_f32_16x16x32_bf16 v[34:37], v[154:157], v[170:173], v[34:37]
	v_mfma_f32_16x16x32_bf16 v[22:25], v[146:149], v[190:193], v[22:25]
	v_mfma_f32_16x16x32_bf16 v[18:21], v[154:157], v[190:193], v[18:21]
	v_mfma_f32_16x16x32_bf16 v[6:9], v[146:149], v[198:201], v[6:9]
	v_mfma_f32_16x16x32_bf16 v[2:5], v[154:157], v[198:201], v[2:5]
	v_mfma_f32_16x16x32_bf16 v[54:57], v[150:153], v[166:169], v[54:57]
	v_mfma_f32_16x16x32_bf16 v[50:53], v[158:161], v[166:169], v[50:53]
	v_mfma_f32_16x16x32_bf16 v[38:41], v[150:153], v[174:177], v[38:41]
	v_mfma_f32_16x16x32_bf16 v[34:37], v[158:161], v[174:177], v[34:37]
	v_mfma_f32_16x16x32_bf16 v[22:25], v[150:153], v[194:197], v[22:25]
	v_mfma_f32_16x16x32_bf16 v[18:21], v[158:161], v[194:197], v[18:21]
	v_mfma_f32_16x16x32_bf16 v[6:9], v[150:153], v[204:207], v[6:9]
	v_mfma_f32_16x16x32_bf16 v[2:5], v[158:161], v[204:207], v[2:5]
	s_barrier
	s_setprio 0
	s_add_i32 s58, 0, 0x18000
	v_add_u32_e32 v0, s58, v236
	s_add_i32 s59, 0, 0x1c000
	ds_read_b128 v[114:117], v0
	ds_read_b128 v[126:129], v0 offset:1024
	ds_read_b128 v[138:141], v0 offset:2048
	ds_read_b128 v[142:145], v0 offset:3072
	v_add_u32_e32 v0, s59, v236
	ds_read_b128 v[146:149], v0
	ds_read_b128 v[150:153], v0 offset:1024
	ds_read_b128 v[154:157], v0 offset:2048
	ds_read_b128 v[158:161], v0 offset:3072
	s_add_u32 s52, s52, 0x40000
	s_addc_u32 s53, s53, 0
	s_mov_b32 m0, s67
	v_lshl_add_u64 v[216:217], s[52:53], 0, v[178:179]
	ds_read_b128 v[162:165], v237 offset:32768
	ds_read_b128 v[166:169], v237 offset:33792
	ds_read_b128 v[170:173], v237 offset:34816
	ds_read_b128 v[174:177], v237 offset:35840
	ds_read_b128 v[190:193], v237 offset:36864
	ds_read_b128 v[194:197], v237 offset:37888
	ds_read_b128 v[198:201], v237 offset:38912
	ds_read_b128 v[204:207], v237 offset:39936
	global_load_lds_dwordx4 v[216:217], off
	v_lshl_add_u64 v[216:217], s[52:53], 0, v[182:183]
	s_mov_b32 m0, s68
	s_nop 0
	global_load_lds_dwordx4 v[216:217], off
	s_waitcnt vmcnt(8)
	s_waitcnt lgkmcnt(0)
	s_setprio 1
	s_barrier
	v_mfma_f32_16x16x32_bf16 v[134:137], v[114:117], v[162:165], v[134:137]
	v_mfma_f32_16x16x32_bf16 v[130:133], v[138:141], v[162:165], v[130:133]
	v_mfma_f32_16x16x32_bf16 v[110:113], v[114:117], v[170:173], v[110:113]
	v_mfma_f32_16x16x32_bf16 v[106:109], v[138:141], v[170:173], v[106:109]
	v_mfma_f32_16x16x32_bf16 v[94:97], v[114:117], v[190:193], v[94:97]
	v_mfma_f32_16x16x32_bf16 v[90:93], v[138:141], v[190:193], v[90:93]
	v_mfma_f32_16x16x32_bf16 v[78:81], v[114:117], v[198:201], v[78:81]
	v_mfma_f32_16x16x32_bf16 v[74:77], v[138:141], v[198:201], v[74:77]
	v_mfma_f32_16x16x32_bf16 v[134:137], v[126:129], v[166:169], v[134:137]
	v_mfma_f32_16x16x32_bf16 v[130:133], v[142:145], v[166:169], v[130:133]
	v_mfma_f32_16x16x32_bf16 v[110:113], v[126:129], v[174:177], v[110:113]
	v_mfma_f32_16x16x32_bf16 v[106:109], v[142:145], v[174:177], v[106:109]
	v_mfma_f32_16x16x32_bf16 v[94:97], v[126:129], v[194:197], v[94:97]
	v_mfma_f32_16x16x32_bf16 v[90:93], v[142:145], v[194:197], v[90:93]
	v_mfma_f32_16x16x32_bf16 v[78:81], v[126:129], v[204:207], v[78:81]
	v_mfma_f32_16x16x32_bf16 v[74:77], v[142:145], v[204:207], v[74:77]
	v_mfma_f32_16x16x32_bf16 v[122:125], v[146:149], v[162:165], v[122:125]
	v_mfma_f32_16x16x32_bf16 v[118:121], v[154:157], v[162:165], v[118:121]
	v_mfma_f32_16x16x32_bf16 v[102:105], v[146:149], v[170:173], v[102:105]
	v_mfma_f32_16x16x32_bf16 v[98:101], v[154:157], v[170:173], v[98:101]
	v_mfma_f32_16x16x32_bf16 v[86:89], v[146:149], v[190:193], v[86:89]
	v_mfma_f32_16x16x32_bf16 v[82:85], v[154:157], v[190:193], v[82:85]
	v_mfma_f32_16x16x32_bf16 v[70:73], v[146:149], v[198:201], v[70:73]
	v_mfma_f32_16x16x32_bf16 v[66:69], v[154:157], v[198:201], v[66:69]
	v_mfma_f32_16x16x32_bf16 v[122:125], v[150:153], v[166:169], v[122:125]
	v_mfma_f32_16x16x32_bf16 v[118:121], v[158:161], v[166:169], v[118:121]
	v_mfma_f32_16x16x32_bf16 v[102:105], v[150:153], v[174:177], v[102:105]
	v_mfma_f32_16x16x32_bf16 v[98:101], v[158:161], v[174:177], v[98:101]
	v_mfma_f32_16x16x32_bf16 v[86:89], v[150:153], v[194:197], v[86:89]
	v_mfma_f32_16x16x32_bf16 v[82:85], v[158:161], v[194:197], v[82:85]
	v_mfma_f32_16x16x32_bf16 v[70:73], v[150:153], v[204:207], v[70:73]
	v_mfma_f32_16x16x32_bf16 v[66:69], v[158:161], v[204:207], v[66:69]
	s_barrier
; #define PG8_STAGE(bufoff, gbase, voff) do { _Pragma("unroll") for (int _i = 0; _i < 2; ++_i) \
;         __builtin_amdgcn_global_load_lds((const unsigned*)((const char*)(gbase) + (voff)[_i]), (PG8_LAS unsigned*)(lds + (bufoff) + ldsw + _i * 8192), 16, 0, 0); } while (0)
; #define PG8_LDA(dst, b, h) do { _Pragma("unroll") for (int m = 0; m < 4; ++m) _Pragma("unroll") for (int k = 0; k < 2; ++k) dst[m][k] = *(const PG8_LAS bf16x8*)(lds + PG8_SA(b, h) + aoff + m * 2048 + k * 1024); } while (0)
; #define PG8_MMA(ai, bj, At, Bt) do { __builtin_amdgcn_s_setprio(1); _Pragma("unroll") for (int m = 0; m < 4; ++m) _Pragma("unroll") for (int n = 0; n < 2; ++n) _Pragma("unroll") for (int k = 0; k < 2; ++k) \
;         acc[ai][bj][m][n] = __builtin_amdgcn_mfma_f32_16x16x32_bf16(Bt[n][k], At[m][k], acc[ai][bj][m][n], 0, 0, 0); __builtin_amdgcn_s_setprio(0); } while (0)
; #define PG8_WAIT_V(n) asm volatile("s_waitcnt vmcnt(" #n ")" ::: "memory")
; #define PG8_WAIT_L(n) asm volatile("s_waitcnt lgkmcnt(" #n ")" ::: "memory")
; #define PG8_BAR __builtin_amdgcn_s_barrier()
; #define PG8_SCHED __builtin_amdgcn_sched_barrier(0)
; template <class Epi, class Sched, bool ALIGN_EPI = false, bool SP2 = false>
; __device__ __forceinline__ void gemm_phase(PG8_LAS unsigned char* lds, const Gemm g, const Sched& S, const Epi& E, const int wave_s) {
;     ...
;             PG8_LDA(At, 1, 1); PG8_STAGE(PG8_SB(1, 0), b3, voffB); PG8_STAGE(PG8_SB(1, 1), b3 + hstep, voffB); PG8_STAGE(PG8_SA(1, 0), a3, voffA);
;             PG8_WAIT_V(8); PG8_WAIT_L(0); PG8_BAR; PG8_MMA(1, 0, At, B0); PG8_MMA(1, 1, At, B1); PG8_BAR; PG8_SCHED;
	s_setprio 0
	s_add_i32 s52, s58, s65
	v_lshl_add_u64 v[208:209], v[208:209], 0, s[86:87]
	s_mov_b32 m0, s52
	ds_read_b128 v[162:165], v237 offset:49152
	ds_read_b128 v[166:169], v237 offset:50176
	ds_read_b128 v[170:173], v237 offset:51200
	ds_read_b128 v[174:177], v237 offset:52224
	ds_read_b128 v[190:193], v237 offset:53248
	ds_read_b128 v[194:197], v237 offset:54272
	ds_read_b128 v[198:201], v237 offset:55296
	ds_read_b128 v[204:207], v237 offset:56320
	global_load_lds_dwordx4 v[208:209], off
	s_add_i32 m0, s52, 0x2000
	s_add_u32 s50, s50, 0x40080
	v_lshl_add_u64 v[208:209], v[210:211], 0, s[86:87]
	s_addc_u32 s51, s51, 0
	s_add_i32 s52, s59, s65
	global_load_lds_dwordx4 v[208:209], off
	v_lshl_add_u64 v[208:209], s[50:51], 0, v[180:181]
	s_mov_b32 m0, s52
	s_nop 0
	global_load_lds_dwordx4 v[208:209], off
	v_lshl_add_u64 v[208:209], s[50:51], 0, v[184:185]
	s_add_i32 m0, s52, 0x2000
	s_nop 0
	global_load_lds_dwordx4 v[208:209], off
	v_lshl_add_u64 v[208:209], v[212:213], 0, s[86:87]
	s_mov_b32 m0, s71
	s_nop 0
	global_load_lds_dwordx4 v[208:209], off
	v_lshl_add_u64 v[208:209], v[214:215], 0, s[86:87]
	s_mov_b32 m0, s72
	s_nop 0
	global_load_lds_dwordx4 v[208:209], off
	s_waitcnt vmcnt(8)
	s_waitcnt lgkmcnt(0)
	s_setprio 1
	s_barrier
	v_mfma_f32_16x16x32_bf16 v[62:65], v[114:117], v[162:165], v[62:65]
	v_mfma_f32_16x16x32_bf16 v[58:61], v[138:141], v[162:165], v[58:61]
	v_mfma_f32_16x16x32_bf16 v[46:49], v[114:117], v[170:173], v[46:49]
	v_mfma_f32_16x16x32_bf16 v[42:45], v[138:141], v[170:173], v[42:45]
	v_mfma_f32_16x16x32_bf16 v[30:33], v[114:117], v[190:193], v[30:33]
	v_mfma_f32_16x16x32_bf16 v[26:29], v[138:141], v[190:193], v[26:29]
	v_mfma_f32_16x16x32_bf16 v[14:17], v[114:117], v[198:201], v[14:17]
	v_mfma_f32_16x16x32_bf16 v[10:13], v[138:141], v[198:201], v[10:13]
	v_mfma_f32_16x16x32_bf16 v[62:65], v[126:129], v[166:169], v[62:65]
	v_mfma_f32_16x16x32_bf16 v[58:61], v[142:145], v[166:169], v[58:61]
	v_mfma_f32_16x16x32_bf16 v[46:49], v[126:129], v[174:177], v[46:49]
	v_mfma_f32_16x16x32_bf16 v[42:45], v[142:145], v[174:177], v[42:45]
	v_mfma_f32_16x16x32_bf16 v[30:33], v[126:129], v[194:197], v[30:33]
	v_mfma_f32_16x16x32_bf16 v[26:29], v[142:145], v[194:197], v[26:29]
	v_mfma_f32_16x16x32_bf16 v[14:17], v[126:129], v[204:207], v[14:17]
	v_mfma_f32_16x16x32_bf16 v[10:13], v[142:145], v[204:207], v[10:13]
	v_mfma_f32_16x16x32_bf16 v[54:57], v[146:149], v[162:165], v[54:57]
	v_mfma_f32_16x16x32_bf16 v[50:53], v[154:157], v[162:165], v[50:53]
	v_mfma_f32_16x16x32_bf16 v[38:41], v[146:149], v[170:173], v[38:41]
	v_mfma_f32_16x16x32_bf16 v[34:37], v[154:157], v[170:173], v[34:37]
	v_mfma_f32_16x16x32_bf16 v[22:25], v[146:149], v[190:193], v[22:25]
	v_mfma_f32_16x16x32_bf16 v[18:21], v[154:157], v[190:193], v[18:21]
	v_mfma_f32_16x16x32_bf16 v[6:9], v[146:149], v[198:201], v[6:9]
	v_mfma_f32_16x16x32_bf16 v[2:5], v[154:157], v[198:201], v[2:5]
	v_mfma_f32_16x16x32_bf16 v[54:57], v[150:153], v[166:169], v[54:57]
	v_mfma_f32_16x16x32_bf16 v[50:53], v[158:161], v[166:169], v[50:53]
	v_mfma_f32_16x16x32_bf16 v[38:41], v[150:153], v[174:177], v[38:41]
	v_mfma_f32_16x16x32_bf16 v[34:37], v[158:161], v[174:177], v[34:37]
	v_mfma_f32_16x16x32_bf16 v[22:25], v[150:153], v[194:197], v[22:25]
	v_mfma_f32_16x16x32_bf16 v[18:21], v[158:161], v[194:197], v[18:21]
	v_mfma_f32_16x16x32_bf16 v[6:9], v[150:153], v[204:207], v[6:9]
	v_mfma_f32_16x16x32_bf16 v[2:5], v[158:161], v[204:207], v[2:5]
	s_barrier
	s_setprio 0
	s_add_i32 s57, s57, 2
	s_add_u32 s4, s4, 0x100
	s_addc_u32 s5, s5, 0
	s_add_u32 s55, s55, 0x100
	s_addc_u32 s56, s56, 0
	s_cmp_gt_u32 s57, 13
	s_cbranch_scc0 .LBB0_203
	s_and_b64 vcc, exec, s[38:39]
	s_cbranch_vccz .LBB0_206
	s_barrier

; #define PG8_STAGE(bufoff, gbase, voff) do { _Pragma("unroll") for (int _i = 0; _i < 2; ++_i) \
;         __builtin_amdgcn_global_load_lds((const unsigned*)((const char*)(gbase) + (voff)[_i]), (PG8_LAS unsigned*)(lds + (bufoff) + ldsw + _i * 8192), 16, 0, 0); } while (0)
; #define PG8_LDA(dst, b, h) do { _Pragma("unroll") for (int m = 0; m < 4; ++m) _Pragma("unroll") for (int k = 0; k < 2; ++k) dst[m][k] = *(const PG8_LAS bf16x8*)(lds + PG8_SA(b, h) + aoff + m * 2048 + k * 1024); } while (0)
; #define PG8_LDB(dst, b, h) do { _Pragma("unroll") for (int n = 0; n < 2; ++n) _Pragma("unroll") for (int k = 0; k < 2; ++k) dst[n][k] = *(const PG8_LAS bf16x8*)(lds + PG8_SB(b, h) + boff + n * 2048 + k * 1024); } while (0)
; #define PG8_MMA(ai, bj, At, Bt) do { __builtin_amdgcn_s_setprio(1); _Pragma("unroll") for (int m = 0; m < 4; ++m) _Pragma("unroll") for (int n = 0; n < 2; ++n) _Pragma("unroll") for (int k = 0; k < 2; ++k) \
;         acc[ai][bj][m][n] = __builtin_amdgcn_mfma_f32_16x16x32_bf16(Bt[n][k], At[m][k], acc[ai][bj][m][n], 0, 0, 0); __builtin_amdgcn_s_setprio(0); } while (0)
; #define PG8_WAIT_V(n) asm volatile("s_waitcnt vmcnt(" #n ")" ::: "memory")
; #define PG8_WAIT_L(n) asm volatile("s_waitcnt lgkmcnt(" #n ")" ::: "memory")
; #define PG8_BAR __builtin_amdgcn_s_barrier()
; #define PG8_SCHED __builtin_amdgcn_sched_barrier(0)
; template <class Epi, class Sched, bool ALIGN_EPI = false, bool SP2 = false>
; __device__ __forceinline__ void gemm_phase(PG8_LAS unsigned char* lds, const Gemm g, const Sched& S, const Epi& E, const int wave_s) {
;     ...
;             PG8_LDB(B0, 0, 0); PG8_LDB(B1, 0, 1); PG8_SCHED; PG8_LDA(At, 0, 0); PG8_STAGE(PG8_SA(1, 1), a1 + hstep, voffA);
;             PG8_WAIT_V(8); PG8_WAIT_L(0); PG8_BAR; PG8_MMA(0, 0, At, B0); PG8_MMA(0, 1, At, B1); PG8_BAR; PG8_SCHED;
;             PG8_LDA(At, 0, 1); PG8_STAGE(PG8_SB(0, 0), b2, voffB); PG8_STAGE(PG8_SB(0, 1), b2 + hstep, voffB); PG8_STAGE(PG8_SA(0, 0), a2, voffA);
;             PG8_WAIT_V(8); PG8_WAIT_L(0); PG8_BAR; PG8_MMA(1, 0, At, B0); PG8_MMA(1, 1, At, B1); PG8_BAR; PG8_SCHED;
.LBB0_343:
	s_add_u32 s26, s2, 0xfffc0080
	s_addc_u32 s27, s3, -1
	s_add_i32 s52, 0, 0x10000
	s_cmp_eq_u32 s51, 12
	s_cselect_b32 s29, s21, s27
	s_cselect_b32 s28, s47, s26
	s_cselect_b32 s27, s19, s50
	s_cselect_b32 s26, s48, s49
	s_add_i32 s54, 0, 0x14000
	v_add_u32_e32 v142, s52, v162
	v_add_u32_e32 v172, s54, v162
	ds_read_b128 v[130:133], v142
	ds_read_b128 v[134:137], v142 offset:1024
	ds_read_b128 v[138:141], v142 offset:2048
	ds_read_b128 v[142:145], v142 offset:3072
	ds_read_b128 v[156:159], v172
	ds_read_b128 v[164:167], v172 offset:1024
	ds_read_b128 v[168:171], v172 offset:2048
	ds_read_b128 v[172:175], v172 offset:3072
	v_lshl_add_u64 v[200:201], s[2:3], 0, v[152:153]
	s_add_i32 m0, s36, 0xc000
	ds_read_b128 v[176:179], v163
	ds_read_b128 v[180:183], v163 offset:1024
	ds_read_b128 v[184:187], v163 offset:2048
	ds_read_b128 v[188:191], v163 offset:3072
	ds_read_b128 v[192:195], v163 offset:4096
	ds_read_b128 v[196:199], v163 offset:5120
	ds_read_b128 v[204:207], v163 offset:6144
	ds_read_b128 v[208:211], v163 offset:7168
	global_load_lds_dwordx4 v[200:201], off
	v_lshl_add_u64 v[200:201], s[2:3], 0, v[154:155]
	s_add_i32 m0, s36, 0xe000
	s_nop 0
	global_load_lds_dwordx4 v[200:201], off
	s_waitcnt vmcnt(8)
	s_waitcnt lgkmcnt(0)
	s_setprio 1
	s_barrier
	v_mfma_f32_16x16x32_bf16 v[126:129], v[130:133], v[176:179], v[126:129]
	v_mfma_f32_16x16x32_bf16 v[122:125], v[138:141], v[176:179], v[122:125]
	v_mfma_f32_16x16x32_bf16 v[118:121], v[130:133], v[184:187], v[118:121]
	v_mfma_f32_16x16x32_bf16 v[110:113], v[138:141], v[184:187], v[110:113]
	v_mfma_f32_16x16x32_bf16 v[102:105], v[130:133], v[192:195], v[102:105]
	v_mfma_f32_16x16x32_bf16 v[94:97], v[138:141], v[192:195], v[94:97]
	v_mfma_f32_16x16x32_bf16 v[86:89], v[130:133], v[204:207], v[86:89]
	v_mfma_f32_16x16x32_bf16 v[78:81], v[138:141], v[204:207], v[78:81]
	v_mfma_f32_16x16x32_bf16 v[126:129], v[134:137], v[180:183], v[126:129]
	v_mfma_f32_16x16x32_bf16 v[122:125], v[142:145], v[180:183], v[122:125]
	v_mfma_f32_16x16x32_bf16 v[118:121], v[134:137], v[188:191], v[118:121]
	v_mfma_f32_16x16x32_bf16 v[110:113], v[142:145], v[188:191], v[110:113]
	v_mfma_f32_16x16x32_bf16 v[102:105], v[134:137], v[196:199], v[102:105]
	v_mfma_f32_16x16x32_bf16 v[94:97], v[142:145], v[196:199], v[94:97]
	v_mfma_f32_16x16x32_bf16 v[86:89], v[134:137], v[208:211], v[86:89]
	v_mfma_f32_16x16x32_bf16 v[78:81], v[142:145], v[208:211], v[78:81]
	v_mfma_f32_16x16x32_bf16 v[114:117], v[156:159], v[176:179], v[114:117]
	v_mfma_f32_16x16x32_bf16 v[106:109], v[168:171], v[176:179], v[106:109]
	v_mfma_f32_16x16x32_bf16 v[98:101], v[156:159], v[184:187], v[98:101]
	v_mfma_f32_16x16x32_bf16 v[90:93], v[168:171], v[184:187], v[90:93]
	v_mfma_f32_16x16x32_bf16 v[82:85], v[156:159], v[192:195], v[82:85]
	v_mfma_f32_16x16x32_bf16 v[74:77], v[168:171], v[192:195], v[74:77]
	v_mfma_f32_16x16x32_bf16 v[70:73], v[156:159], v[204:207], v[70:73]
	v_mfma_f32_16x16x32_bf16 v[66:69], v[168:171], v[204:207], v[66:69]
	v_mfma_f32_16x16x32_bf16 v[114:117], v[164:167], v[180:183], v[114:117]
	v_mfma_f32_16x16x32_bf16 v[106:109], v[172:175], v[180:183], v[106:109]
	v_mfma_f32_16x16x32_bf16 v[98:101], v[164:167], v[188:191], v[98:101]
	v_mfma_f32_16x16x32_bf16 v[90:93], v[172:175], v[188:191], v[90:93]
	v_mfma_f32_16x16x32_bf16 v[82:85], v[164:167], v[196:199], v[82:85]
	v_mfma_f32_16x16x32_bf16 v[74:77], v[172:175], v[196:199], v[74:77]
	v_mfma_f32_16x16x32_bf16 v[70:73], v[164:167], v[208:211], v[70:73]
	v_mfma_f32_16x16x32_bf16 v[66:69], v[172:175], v[208:211], v[66:69]
	s_barrier
	s_setprio 0
	s_add_i32 s52, s52, s33
	v_lshl_add_u64 v[200:201], s[26:27], 0, v[0:1]
	s_mov_b32 m0, s52
	ds_read_b128 v[176:179], v163 offset:16384
	ds_read_b128 v[180:183], v163 offset:17408
	ds_read_b128 v[184:187], v163 offset:18432
	ds_read_b128 v[188:191], v163 offset:19456
	ds_read_b128 v[192:195], v163 offset:20480
	ds_read_b128 v[196:199], v163 offset:21504
	ds_read_b128 v[204:207], v163 offset:22528
	ds_read_b128 v[208:211], v163 offset:23552
	global_load_lds_dwordx4 v[200:201], off
	s_add_i32 m0, s52, 0x2000
	s_add_u32 s52, s26, 0x40000
	v_lshl_add_u64 v[202:203], s[26:27], 0, v[146:147]
	s_addc_u32 s53, s27, 0
	s_add_i32 s54, s54, s33
	global_load_lds_dwordx4 v[202:203], off
	v_lshl_add_u64 v[212:213], s[52:53], 0, v[0:1]
	s_mov_b32 m0, s54
	v_lshl_add_u64 v[214:215], s[28:29], 0, v[148:149]
	global_load_lds_dwordx4 v[212:213], off
	v_lshl_add_u64 v[212:213], s[52:53], 0, v[146:147]
	s_add_i32 m0, s54, 0x2000
	s_nop 0
	global_load_lds_dwordx4 v[212:213], off
	v_lshl_add_u64 v[212:213], s[28:29], 0, v[150:151]
	s_mov_b32 m0, s36
	s_nop 0
	global_load_lds_dwordx4 v[212:213], off
	s_mov_b32 m0, s37
	s_nop 0
	global_load_lds_dwordx4 v[214:215], off
	s_waitcnt vmcnt(8)
	s_waitcnt lgkmcnt(0)
	s_setprio 1
	s_barrier
; #define PG8_STAGE(bufoff, gbase, voff) do { _Pragma("unroll") for (int _i = 0; _i < 2; ++_i) \
;         __builtin_amdgcn_global_load_lds((const unsigned*)((const char*)(gbase) + (voff)[_i]), (PG8_LAS unsigned*)(lds + (bufoff) + ldsw + _i * 8192), 16, 0, 0); } while (0)
; #define PG8_LDA(dst, b, h) do { _Pragma("unroll") for (int m = 0; m < 4; ++m) _Pragma("unroll") for (int k = 0; k < 2; ++k) dst[m][k] = *(const PG8_LAS bf16x8*)(lds + PG8_SA(b, h) + aoff + m * 2048 + k * 1024); } while (0)
; #define PG8_LDB(dst, b, h) do { _Pragma("unroll") for (int n = 0; n < 2; ++n) _Pragma("unroll") for (int k = 0; k < 2; ++k) dst[n][k] = *(const PG8_LAS bf16x8*)(lds + PG8_SB(b, h) + boff + n * 2048 + k * 1024); } while (0)
; #define PG8_MMA(ai, bj, At, Bt) do { __builtin_amdgcn_s_setprio(1); _Pragma("unroll") for (int m = 0; m < 4; ++m) _Pragma("unroll") for (int n = 0; n < 2; ++n) _Pragma("unroll") for (int k = 0; k < 2; ++k) \
;         acc[ai][bj][m][n] = __builtin_amdgcn_mfma_f32_16x16x32_bf16(Bt[n][k], At[m][k], acc[ai][bj][m][n], 0, 0, 0); __builtin_amdgcn_s_setprio(0); } while (0)
; #define PG8_WAIT_V(n) asm volatile("s_waitcnt vmcnt(" #n ")" ::: "memory")
; #define PG8_WAIT_L(n) asm volatile("s_waitcnt lgkmcnt(" #n ")" ::: "memory")
; #define PG8_BAR __builtin_amdgcn_s_barrier()
; #define PG8_SCHED __builtin_amdgcn_sched_barrier(0)
; template <class Epi, class Sched, bool ALIGN_EPI = false, bool SP2 = false>
; __device__ __forceinline__ void gemm_phase(PG8_LAS unsigned char* lds, const Gemm g, const Sched& S, const Epi& E, const int wave_s) {
;     ...
;             PG8_WAIT_V(8); PG8_WAIT_L(0); PG8_BAR; PG8_MMA(1, 0, At, B0); PG8_MMA(1, 1, At, B1); PG8_BAR; PG8_SCHED;
;             PG8_LDB(B0, 1, 0); PG8_LDB(B1, 1, 1); PG8_SCHED; PG8_LDA(At, 1, 0); PG8_STAGE(PG8_SA(0, 1), a2 + hstep, voffA);
;             PG8_WAIT_V(8); PG8_WAIT_L(0); PG8_BAR; PG8_MMA(0, 0, At, B0); PG8_MMA(0, 1, At, B1); PG8_BAR; PG8_SCHED;
	v_mfma_f32_16x16x32_bf16 v[62:65], v[130:133], v[176:179], v[62:65]
	v_mfma_f32_16x16x32_bf16 v[58:61], v[138:141], v[176:179], v[58:61]
	v_mfma_f32_16x16x32_bf16 v[54:57], v[130:133], v[184:187], v[54:57]
	v_mfma_f32_16x16x32_bf16 v[46:49], v[138:141], v[184:187], v[46:49]
	v_mfma_f32_16x16x32_bf16 v[38:41], v[130:133], v[192:195], v[38:41]
	v_mfma_f32_16x16x32_bf16 v[30:33], v[138:141], v[192:195], v[30:33]
	v_mfma_f32_16x16x32_bf16 v[22:25], v[130:133], v[204:207], v[22:25]
	v_mfma_f32_16x16x32_bf16 v[14:17], v[138:141], v[204:207], v[14:17]
	v_mfma_f32_16x16x32_bf16 v[62:65], v[134:137], v[180:183], v[62:65]
	v_mfma_f32_16x16x32_bf16 v[58:61], v[142:145], v[180:183], v[58:61]
	v_mfma_f32_16x16x32_bf16 v[54:57], v[134:137], v[188:191], v[54:57]
	v_mfma_f32_16x16x32_bf16 v[46:49], v[142:145], v[188:191], v[46:49]
	v_mfma_f32_16x16x32_bf16 v[38:41], v[134:137], v[196:199], v[38:41]
	v_mfma_f32_16x16x32_bf16 v[30:33], v[142:145], v[196:199], v[30:33]
	v_mfma_f32_16x16x32_bf16 v[22:25], v[134:137], v[208:211], v[22:25]
	v_mfma_f32_16x16x32_bf16 v[14:17], v[142:145], v[208:211], v[14:17]
	v_mfma_f32_16x16x32_bf16 v[50:53], v[156:159], v[176:179], v[50:53]
	v_mfma_f32_16x16x32_bf16 v[42:45], v[168:171], v[176:179], v[42:45]
	v_mfma_f32_16x16x32_bf16 v[34:37], v[156:159], v[184:187], v[34:37]
	v_mfma_f32_16x16x32_bf16 v[26:29], v[168:171], v[184:187], v[26:29]
	v_mfma_f32_16x16x32_bf16 v[18:21], v[156:159], v[192:195], v[18:21]
	v_mfma_f32_16x16x32_bf16 v[10:13], v[168:171], v[192:195], v[10:13]
	v_mfma_f32_16x16x32_bf16 v[6:9], v[156:159], v[204:207], v[6:9]
	v_mfma_f32_16x16x32_bf16 v[2:5], v[168:171], v[204:207], v[2:5]
	v_mfma_f32_16x16x32_bf16 v[50:53], v[164:167], v[180:183], v[50:53]
	v_mfma_f32_16x16x32_bf16 v[42:45], v[172:175], v[180:183], v[42:45]
	v_mfma_f32_16x16x32_bf16 v[34:37], v[164:167], v[188:191], v[34:37]
	v_mfma_f32_16x16x32_bf16 v[26:29], v[172:175], v[188:191], v[26:29]
	v_mfma_f32_16x16x32_bf16 v[18:21], v[164:167], v[196:199], v[18:21]
	v_mfma_f32_16x16x32_bf16 v[10:13], v[172:175], v[196:199], v[10:13]
	v_mfma_f32_16x16x32_bf16 v[6:9], v[164:167], v[208:211], v[6:9]
	v_mfma_f32_16x16x32_bf16 v[2:5], v[172:175], v[208:211], v[2:5]
	s_barrier
	s_setprio 0
	s_add_i32 s52, 0, 0x18000
	s_add_i32 s53, 0, 0x1c000
	v_add_u32_e32 v142, s52, v162
	v_add_u32_e32 v172, s53, v162
	ds_read_b128 v[130:133], v142
	ds_read_b128 v[134:137], v142 offset:1024
	ds_read_b128 v[138:141], v142 offset:2048
	ds_read_b128 v[142:145], v142 offset:3072
	ds_read_b128 v[156:159], v172
	ds_read_b128 v[164:167], v172 offset:1024
	ds_read_b128 v[168:171], v172 offset:2048
	ds_read_b128 v[172:175], v172 offset:3072
	s_add_u32 s28, s28, 0x40000
	s_addc_u32 s29, s29, 0
	s_mov_b32 m0, s38
	v_lshl_add_u64 v[216:217], s[28:29], 0, v[150:151]
	ds_read_b128 v[176:179], v163 offset:32768
	ds_read_b128 v[180:183], v163 offset:33792
	ds_read_b128 v[184:187], v163 offset:34816
	ds_read_b128 v[188:191], v163 offset:35840
	ds_read_b128 v[192:195], v163 offset:36864
	ds_read_b128 v[196:199], v163 offset:37888
	ds_read_b128 v[204:207], v163 offset:38912
	ds_read_b128 v[208:211], v163 offset:39936
	global_load_lds_dwordx4 v[216:217], off
	v_lshl_add_u64 v[216:217], s[28:29], 0, v[148:149]
	s_mov_b32 m0, s39
	s_nop 0
	global_load_lds_dwordx4 v[216:217], off
	s_waitcnt vmcnt(8)
	s_waitcnt lgkmcnt(0)
	s_setprio 1
	s_barrier
	v_mfma_f32_16x16x32_bf16 v[126:129], v[130:133], v[176:179], v[126:129]
	v_mfma_f32_16x16x32_bf16 v[122:125], v[138:141], v[176:179], v[122:125]
	v_mfma_f32_16x16x32_bf16 v[118:121], v[130:133], v[184:187], v[118:121]
	v_mfma_f32_16x16x32_bf16 v[110:113], v[138:141], v[184:187], v[110:113]
	v_mfma_f32_16x16x32_bf16 v[102:105], v[130:133], v[192:195], v[102:105]
	v_mfma_f32_16x16x32_bf16 v[94:97], v[138:141], v[192:195], v[94:97]
	v_mfma_f32_16x16x32_bf16 v[86:89], v[130:133], v[204:207], v[86:89]
	v_mfma_f32_16x16x32_bf16 v[78:81], v[138:141], v[204:207], v[78:81]
	v_mfma_f32_16x16x32_bf16 v[126:129], v[134:137], v[180:183], v[126:129]
	v_mfma_f32_16x16x32_bf16 v[122:125], v[142:145], v[180:183], v[122:125]
	v_mfma_f32_16x16x32_bf16 v[118:121], v[134:137], v[188:191], v[118:121]
	v_mfma_f32_16x16x32_bf16 v[110:113], v[142:145], v[188:191], v[110:113]
	v_mfma_f32_16x16x32_bf16 v[102:105], v[134:137], v[196:199], v[102:105]
	v_mfma_f32_16x16x32_bf16 v[94:97], v[142:145], v[196:199], v[94:97]
	v_mfma_f32_16x16x32_bf16 v[86:89], v[134:137], v[208:211], v[86:89]
	v_mfma_f32_16x16x32_bf16 v[78:81], v[142:145], v[208:211], v[78:81]
	v_mfma_f32_16x16x32_bf16 v[114:117], v[156:159], v[176:179], v[114:117]
	v_mfma_f32_16x16x32_bf16 v[106:109], v[168:171], v[176:179], v[106:109]
	v_mfma_f32_16x16x32_bf16 v[98:101], v[156:159], v[184:187], v[98:101]
	v_mfma_f32_16x16x32_bf16 v[90:93], v[168:171], v[184:187], v[90:93]
	v_mfma_f32_16x16x32_bf16 v[82:85], v[156:159], v[192:195], v[82:85]
	v_mfma_f32_16x16x32_bf16 v[74:77], v[168:171], v[192:195], v[74:77]
	v_mfma_f32_16x16x32_bf16 v[70:73], v[156:159], v[204:207], v[70:73]
	v_mfma_f32_16x16x32_bf16 v[66:69], v[168:171], v[204:207], v[66:69]
	v_mfma_f32_16x16x32_bf16 v[114:117], v[164:167], v[180:183], v[114:117]
	v_mfma_f32_16x16x32_bf16 v[106:109], v[172:175], v[180:183], v[106:109]
	v_mfma_f32_16x16x32_bf16 v[98:101], v[164:167], v[188:191], v[98:101]
	v_mfma_f32_16x16x32_bf16 v[90:93], v[172:175], v[188:191], v[90:93]
	v_mfma_f32_16x16x32_bf16 v[82:85], v[164:167], v[196:199], v[82:85]
	v_mfma_f32_16x16x32_bf16 v[74:77], v[172:175], v[196:199], v[74:77]
	v_mfma_f32_16x16x32_bf16 v[70:73], v[164:167], v[208:211], v[70:73]
	v_mfma_f32_16x16x32_bf16 v[66:69], v[172:175], v[208:211], v[66:69]
	s_barrier
; #define PG8_STAGE(bufoff, gbase, voff) do { _Pragma("unroll") for (int _i = 0; _i < 2; ++_i) \
;         __builtin_amdgcn_global_load_lds((const unsigned*)((const char*)(gbase) + (voff)[_i]), (PG8_LAS unsigned*)(lds + (bufoff) + ldsw + _i * 8192), 16, 0, 0); } while (0)
; #define PG8_LDA(dst, b, h) do { _Pragma("unroll") for (int m = 0; m < 4; ++m) _Pragma("unroll") for (int k = 0; k < 2; ++k) dst[m][k] = *(const PG8_LAS bf16x8*)(lds + PG8_SA(b, h) + aoff + m * 2048 + k * 1024); } while (0)
; #define PG8_MMA(ai, bj, At, Bt) do { __builtin_amdgcn_s_setprio(1); _Pragma("unroll") for (int m = 0; m < 4; ++m) _Pragma("unroll") for (int n = 0; n < 2; ++n) _Pragma("unroll") for (int k = 0; k < 2; ++k) \
;         acc[ai][bj][m][n] = __builtin_amdgcn_mfma_f32_16x16x32_bf16(Bt[n][k], At[m][k], acc[ai][bj][m][n], 0, 0, 0); __builtin_amdgcn_s_setprio(0); } while (0)
; #define PG8_WAIT_V(n) asm volatile("s_waitcnt vmcnt(" #n ")" ::: "memory")
; #define PG8_WAIT_L(n) asm volatile("s_waitcnt lgkmcnt(" #n ")" ::: "memory")
; #define PG8_BAR __builtin_amdgcn_s_barrier()
; #define PG8_SCHED __builtin_amdgcn_sched_barrier(0)
; template <class Epi, class Sched, bool ALIGN_EPI = false, bool SP2 = false>
; __device__ __forceinline__ void gemm_phase(PG8_LAS unsigned char* lds, const Gemm g, const Sched& S, const Epi& E, const int wave_s) {
;     ...
;             PG8_LDA(At, 1, 1); PG8_STAGE(PG8_SB(1, 0), b3, voffB); PG8_STAGE(PG8_SB(1, 1), b3 + hstep, voffB); PG8_STAGE(PG8_SA(1, 0), a3, voffA);
;             PG8_WAIT_V(8); PG8_WAIT_L(0); PG8_BAR; PG8_MMA(1, 0, At, B0); PG8_MMA(1, 1, At, B1); PG8_BAR; PG8_SCHED;
	s_setprio 0
	s_add_i32 s28, s52, s33
	v_lshl_add_u64 v[200:201], v[200:201], 0, s[86:87]
	s_mov_b32 m0, s28
	ds_read_b128 v[176:179], v163 offset:49152
	ds_read_b128 v[180:183], v163 offset:50176
	ds_read_b128 v[184:187], v163 offset:51200
	ds_read_b128 v[188:191], v163 offset:52224
	ds_read_b128 v[192:195], v163 offset:53248
	ds_read_b128 v[196:199], v163 offset:54272
	ds_read_b128 v[204:207], v163 offset:55296
	ds_read_b128 v[208:211], v163 offset:56320
	global_load_lds_dwordx4 v[200:201], off
	s_add_i32 m0, s28, 0x2000
	s_add_u32 s26, s26, 0x40080
	v_lshl_add_u64 v[200:201], v[202:203], 0, s[86:87]
	s_addc_u32 s27, s27, 0
	s_add_i32 s28, s53, s33
	global_load_lds_dwordx4 v[200:201], off
	v_lshl_add_u64 v[200:201], s[26:27], 0, v[0:1]
	s_mov_b32 m0, s28
	s_nop 0
	global_load_lds_dwordx4 v[200:201], off
	v_lshl_add_u64 v[200:201], s[26:27], 0, v[146:147]
	s_add_i32 m0, s28, 0x2000
	s_nop 0
	global_load_lds_dwordx4 v[200:201], off
	v_lshl_add_u64 v[200:201], v[212:213], 0, s[86:87]
	s_mov_b32 m0, s42
	s_nop 0
	global_load_lds_dwordx4 v[200:201], off
	v_lshl_add_u64 v[200:201], v[214:215], 0, s[86:87]
	s_mov_b32 m0, s43
	s_nop 0
	global_load_lds_dwordx4 v[200:201], off
	s_waitcnt vmcnt(8)
	s_waitcnt lgkmcnt(0)
	s_setprio 1
	s_barrier
	v_mfma_f32_16x16x32_bf16 v[62:65], v[130:133], v[176:179], v[62:65]
	v_mfma_f32_16x16x32_bf16 v[58:61], v[138:141], v[176:179], v[58:61]
	v_mfma_f32_16x16x32_bf16 v[54:57], v[130:133], v[184:187], v[54:57]
	v_mfma_f32_16x16x32_bf16 v[46:49], v[138:141], v[184:187], v[46:49]
	v_mfma_f32_16x16x32_bf16 v[38:41], v[130:133], v[192:195], v[38:41]
	v_mfma_f32_16x16x32_bf16 v[30:33], v[138:141], v[192:195], v[30:33]
	v_mfma_f32_16x16x32_bf16 v[22:25], v[130:133], v[204:207], v[22:25]
	v_mfma_f32_16x16x32_bf16 v[14:17], v[138:141], v[204:207], v[14:17]
	v_mfma_f32_16x16x32_bf16 v[62:65], v[134:137], v[180:183], v[62:65]
	v_mfma_f32_16x16x32_bf16 v[58:61], v[142:145], v[180:183], v[58:61]
	v_mfma_f32_16x16x32_bf16 v[54:57], v[134:137], v[188:191], v[54:57]
	v_mfma_f32_16x16x32_bf16 v[46:49], v[142:145], v[188:191], v[46:49]
	v_mfma_f32_16x16x32_bf16 v[38:41], v[134:137], v[196:199], v[38:41]
	v_mfma_f32_16x16x32_bf16 v[30:33], v[142:145], v[196:199], v[30:33]
	v_mfma_f32_16x16x32_bf16 v[22:25], v[134:137], v[208:211], v[22:25]
	v_mfma_f32_16x16x32_bf16 v[14:17], v[142:145], v[208:211], v[14:17]
	v_mfma_f32_16x16x32_bf16 v[50:53], v[156:159], v[176:179], v[50:53]
	v_mfma_f32_16x16x32_bf16 v[42:45], v[168:171], v[176:179], v[42:45]
	v_mfma_f32_16x16x32_bf16 v[34:37], v[156:159], v[184:187], v[34:37]
	v_mfma_f32_16x16x32_bf16 v[26:29], v[168:171], v[184:187], v[26:29]
	v_mfma_f32_16x16x32_bf16 v[18:21], v[156:159], v[192:195], v[18:21]
	v_mfma_f32_16x16x32_bf16 v[10:13], v[168:171], v[192:195], v[10:13]
	v_mfma_f32_16x16x32_bf16 v[6:9], v[156:159], v[204:207], v[6:9]
	v_mfma_f32_16x16x32_bf16 v[2:5], v[168:171], v[204:207], v[2:5]
	v_mfma_f32_16x16x32_bf16 v[50:53], v[164:167], v[180:183], v[50:53]
	v_mfma_f32_16x16x32_bf16 v[42:45], v[172:175], v[180:183], v[42:45]
	v_mfma_f32_16x16x32_bf16 v[34:37], v[164:167], v[188:191], v[34:37]
	v_mfma_f32_16x16x32_bf16 v[26:29], v[172:175], v[188:191], v[26:29]
	v_mfma_f32_16x16x32_bf16 v[18:21], v[164:167], v[196:199], v[18:21]
	v_mfma_f32_16x16x32_bf16 v[10:13], v[172:175], v[196:199], v[10:13]
	v_mfma_f32_16x16x32_bf16 v[6:9], v[164:167], v[208:211], v[6:9]
	v_mfma_f32_16x16x32_bf16 v[2:5], v[172:175], v[208:211], v[2:5]
	s_barrier
	s_setprio 0
	s_add_i32 s51, s51, 2
	s_add_u32 s2, s2, 0x100
	s_addc_u32 s3, s3, 0
	s_add_u32 s49, s49, 0x100
	s_addc_u32 s50, s50, 0
	s_cmp_gt_u32 s51, 13
	s_cbranch_scc0 .LBB0_343
	s_and_b64 vcc, exec, s[16:17]
	s_cbranch_vccz .LBB0_346
	s_barrier

; #define LAS __attribute__((address_space(3)))
; __device__ __forceinline__ int pi_row(int i) { return (i & ~12) | ((i & 4) << 1) | ((i & 8) >> 1); }
; #define MFMA32(a, b, c) __builtin_amdgcn_mfma_f32_32x32x16_bf16((a), (b), (c), 0, 0, 0)
; #define MAX3(a, b, c) __builtin_fmaxf(__builtin_fmaxf((a), (b)), (c))
; __device__ __forceinline__ void softmax_step(f32x16& p0, f32x16& p1, float& m, float& l, f32x16& o0, f32x16& o1) {
;     float a = MAX3(p0[0], p0[1], p0[2]), b = MAX3(p1[0], p1[1], p1[2]);
; #pragma unroll
;     for (int r = 3; r < 15; r += 2) { a = MAX3(a, p0[r], p0[r + 1]); b = MAX3(b, p1[r], p1[r + 1]); }
;     float mx = MAX3(a, b, p0[15]); mx = fmaxf(mx, p1[15]);
;     mx = fmaxf(mx, __shfl_xor(mx, 32));
; template <bool INIT = true> __device__ __forceinline__ void qk_lds(f32x16& p0, f32x16& p1, const LAS unsigned char* buf, const bf16x8 (&qr)[4], int r32, int hi) {
;     const LAS unsigned char* kp = buf + pi_row(r32) * TP + hi * 16;
;     if (INIT) { p0 = (f32x16){}; p1 = (f32x16){}; }
;     bf16x8 kf[8];
; #pragma unroll
;     for (int d0 = 0; d0 < 4; ++d0) { kf[2 * d0] = *(const LAS bf16x8*)(kp + d0 * 32); kf[2 * d0 + 1] = *(const LAS bf16x8*)(kp + 32 * TP + d0 * 32); }
;     __builtin_amdgcn_s_setprio(1);
; #pragma unroll
;     for (int d0 = 0; d0 < 4; ++d0) { p0 = MFMA32(kf[2 * d0], qr[d0], p0); p1 = MFMA32(kf[2 * d0 + 1], qr[d0], p1); }
;     __builtin_amdgcn_s_setprio(0);
.LBB0_449:
	v_add3_u32 v0, s34, v103, v105
	ds_read_b128 v[196:199], v0
	ds_read_b128 v[204:207], v0 offset:32
	ds_read_b128 v[208:211], v0 offset:4608
	ds_read_b128 v[212:215], v0 offset:4640
	ds_read_b128 v[216:219], v0 offset:64
	ds_read_b128 v[220:223], v0 offset:96
	ds_read_b128 v[224:227], v0 offset:4672
	ds_read_b128 v[228:231], v0 offset:4704
	s_setprio 1
	s_waitcnt lgkmcnt(7)
	v_mfma_f32_32x32x16_bf16 v[50:65], v[196:199], v[70:73], v[50:65]
	s_waitcnt lgkmcnt(5)
	v_mfma_f32_32x32x16_bf16 v[34:49], v[208:211], v[70:73], v[34:49]
	v_mfma_f32_32x32x16_bf16 v[50:65], v[204:207], v[74:77], v[50:65]
	s_waitcnt lgkmcnt(4)
	v_mfma_f32_32x32x16_bf16 v[34:49], v[212:215], v[74:77], v[34:49]
	s_waitcnt lgkmcnt(3)
	v_mfma_f32_32x32x16_bf16 v[50:65], v[216:219], v[82:85], v[50:65]
	s_waitcnt lgkmcnt(1)
	v_mfma_f32_32x32x16_bf16 v[34:49], v[224:227], v[82:85], v[34:49]
	v_mfma_f32_32x32x16_bf16 v[50:65], v[220:223], v[86:89], v[50:65]
	s_waitcnt lgkmcnt(0)
	v_mfma_f32_32x32x16_bf16 v[34:49], v[228:231], v[86:89], v[34:49]
	s_setprio 0
	s_nop 8
	v_max_f32_e32 v0, v51, v51
	v_max_f32_e32 v195, v50, v50
	v_max_f32_e32 v0, v195, v0
	v_max3_f32 v195, v34, v35, v36
	v_max3_f32 v0, v0, v52, v53
	v_max3_f32 v195, v195, v37, v38
	v_max3_f32 v0, v0, v54, v55
	v_max3_f32 v195, v195, v39, v40
	v_max3_f32 v0, v0, v56, v57
	v_max3_f32 v195, v195, v41, v42
	v_max3_f32 v0, v0, v58, v59
	v_max3_f32 v195, v195, v43, v44
	v_max3_f32 v0, v0, v60, v61
	v_max3_f32 v195, v195, v45, v46
	v_max3_f32 v0, v0, v62, v63
	v_max3_f32 v195, v195, v47, v48
	v_max3_f32 v0, v0, v64, v195
	v_max3_f32 v0, v0, v65, v49
	ds_bpermute_b32 v195, v136, v0
	s_waitcnt lgkmcnt(0)
	v_max3_f32 v195, v194, v0, v195
	v_cmp_eq_f32_e32 vcc, v195, v194
	s_cmp_eq_u64 vcc, exec
	s_cbranch_scc1 .LBB0_451
	v_sub_f32_e32 v0, v194, v195
	v_exp_f32_e32 v0, v0
	v_mov_b32_e32 v194, v195
	v_mul_f32_e32 v192, v192, v0
	v_pk_mul_f32 v[32:33], v[32:33], v[0:1] op_sel_hi:[1,0]
	v_pk_mul_f32 v[30:31], v[30:31], v[0:1] op_sel_hi:[1,0]
	v_pk_mul_f32 v[28:29], v[28:29], v[0:1] op_sel_hi:[1,0]
	v_pk_mul_f32 v[26:27], v[26:27], v[0:1] op_sel_hi:[1,0]
	v_pk_mul_f32 v[24:25], v[24:25], v[0:1] op_sel_hi:[1,0]
	v_pk_mul_f32 v[22:23], v[22:23], v[0:1] op_sel_hi:[1,0]
	v_pk_mul_f32 v[20:21], v[20:21], v[0:1] op_sel_hi:[1,0]
	v_pk_mul_f32 v[18:19], v[18:19], v[0:1] op_sel_hi:[1,0]
	v_pk_mul_f32 v[16:17], v[16:17], v[0:1] op_sel_hi:[1,0]
	v_pk_mul_f32 v[14:15], v[14:15], v[0:1] op_sel_hi:[1,0]
	v_pk_mul_f32 v[12:13], v[12:13], v[0:1] op_sel_hi:[1,0]
	v_pk_mul_f32 v[10:11], v[10:11], v[0:1] op_sel_hi:[1,0]
	v_pk_mul_f32 v[8:9], v[8:9], v[0:1] op_sel_hi:[1,0]
	v_pk_mul_f32 v[6:7], v[6:7], v[0:1] op_sel_hi:[1,0]
	v_pk_mul_f32 v[4:5], v[4:5], v[0:1] op_sel_hi:[1,0]
	v_pk_mul_f32 v[2:3], v[2:3], v[0:1] op_sel_hi:[1,0]

; #define LAS __attribute__((address_space(3)))
; __device__ __forceinline__ int pi_row(int i) { return (i & ~12) | ((i & 4) << 1) | ((i & 8) >> 1); }
; #define MFMA32(a, b, c) __builtin_amdgcn_mfma_f32_32x32x16_bf16((a), (b), (c), 0, 0, 0)
; #define MAX3(a, b, c) __builtin_fmaxf(__builtin_fmaxf((a), (b)), (c))
; __device__ __forceinline__ void softmax_step(f32x16& p0, f32x16& p1, float& m, float& l, f32x16& o0, f32x16& o1) {
;     float a = MAX3(p0[0], p0[1], p0[2]), b = MAX3(p1[0], p1[1], p1[2]);
; #pragma unroll
;     for (int r = 3; r < 15; r += 2) { a = MAX3(a, p0[r], p0[r + 1]); b = MAX3(b, p1[r], p1[r + 1]); }
;     float mx = MAX3(a, b, p0[15]); mx = fmaxf(mx, p1[15]);
;     mx = fmaxf(mx, __shfl_xor(mx, 32));
; template <bool INIT = true> __device__ __forceinline__ void qk_lds(f32x16& p0, f32x16& p1, const LAS unsigned char* buf, const bf16x8 (&qr)[4], int r32, int hi) {
;     const LAS unsigned char* kp = buf + pi_row(r32) * TP + hi * 16;
;     if (INIT) { p0 = (f32x16){}; p1 = (f32x16){}; }
;     bf16x8 kf[8];
; #pragma unroll
;     for (int d0 = 0; d0 < 4; ++d0) { kf[2 * d0] = *(const LAS bf16x8*)(kp + d0 * 32); kf[2 * d0 + 1] = *(const LAS bf16x8*)(kp + 32 * TP + d0 * 32); }
;     __builtin_amdgcn_s_setprio(1);
; #pragma unroll
;     for (int d0 = 0; d0 < 4; ++d0) { p0 = MFMA32(kf[2 * d0], qr[d0], p0); p1 = MFMA32(kf[2 * d0 + 1], qr[d0], p1); }
;     __builtin_amdgcn_s_setprio(0);
.LBB0_462:
	v_add3_u32 v0, s34, v103, v105
	ds_read_b128 v[196:199], v0 offset:18432
	ds_read_b128 v[204:207], v0 offset:18464
	ds_read_b128 v[208:211], v0 offset:23040
	ds_read_b128 v[212:215], v0 offset:23072
	ds_read_b128 v[216:219], v0 offset:18496
	ds_read_b128 v[220:223], v0 offset:18528
	ds_read_b128 v[224:227], v0 offset:23104
	ds_read_b128 v[228:231], v0 offset:23136
	s_setprio 1
	s_waitcnt lgkmcnt(7)
	v_mfma_f32_32x32x16_bf16 v[50:65], v[196:199], v[70:73], v[50:65]
	s_waitcnt lgkmcnt(5)
	v_mfma_f32_32x32x16_bf16 v[34:49], v[208:211], v[70:73], v[34:49]
	v_mfma_f32_32x32x16_bf16 v[50:65], v[204:207], v[74:77], v[50:65]
	s_waitcnt lgkmcnt(4)
	v_mfma_f32_32x32x16_bf16 v[34:49], v[212:215], v[74:77], v[34:49]
	s_waitcnt lgkmcnt(3)
	v_mfma_f32_32x32x16_bf16 v[50:65], v[216:219], v[82:85], v[50:65]
	s_waitcnt lgkmcnt(1)
	v_mfma_f32_32x32x16_bf16 v[34:49], v[224:227], v[82:85], v[34:49]
	v_mfma_f32_32x32x16_bf16 v[50:65], v[220:223], v[86:89], v[50:65]
	s_waitcnt lgkmcnt(0)
	v_mfma_f32_32x32x16_bf16 v[34:49], v[228:231], v[86:89], v[34:49]
	s_setprio 0
	s_nop 8
	v_max_f32_e32 v0, v51, v51
	v_max_f32_e32 v195, v50, v50
	v_max_f32_e32 v0, v195, v0
	v_max3_f32 v195, v34, v35, v36
	v_max3_f32 v0, v0, v52, v53
	v_max3_f32 v195, v195, v37, v38
	v_max3_f32 v0, v0, v54, v55
	v_max3_f32 v195, v195, v39, v40
	v_max3_f32 v0, v0, v56, v57
	v_max3_f32 v195, v195, v41, v42
	v_max3_f32 v0, v0, v58, v59
	v_max3_f32 v195, v195, v43, v44
	v_max3_f32 v0, v0, v60, v61
	v_max3_f32 v195, v195, v45, v46
	v_max3_f32 v0, v0, v62, v63
	v_max3_f32 v195, v195, v47, v48
	v_max3_f32 v0, v0, v64, v195
	v_max3_f32 v0, v0, v65, v49
	ds_bpermute_b32 v195, v136, v0
	s_waitcnt lgkmcnt(0)
	v_max3_f32 v195, v194, v0, v195
	v_cmp_eq_f32_e32 vcc, v195, v194
	s_cmp_eq_u64 vcc, exec
	s_cbranch_scc1 .LBB0_464
	v_sub_f32_e32 v0, v194, v195
	v_exp_f32_e32 v0, v0
	v_mov_b32_e32 v194, v195
	v_mul_f32_e32 v192, v192, v0
	v_pk_mul_f32 v[32:33], v[32:33], v[0:1] op_sel_hi:[1,0]
	v_pk_mul_f32 v[30:31], v[30:31], v[0:1] op_sel_hi:[1,0]
	v_pk_mul_f32 v[28:29], v[28:29], v[0:1] op_sel_hi:[1,0]
	v_pk_mul_f32 v[26:27], v[26:27], v[0:1] op_sel_hi:[1,0]
	v_pk_mul_f32 v[24:25], v[24:25], v[0:1] op_sel_hi:[1,0]
	v_pk_mul_f32 v[22:23], v[22:23], v[0:1] op_sel_hi:[1,0]
	v_pk_mul_f32 v[20:21], v[20:21], v[0:1] op_sel_hi:[1,0]
	v_pk_mul_f32 v[18:19], v[18:19], v[0:1] op_sel_hi:[1,0]
	v_pk_mul_f32 v[16:17], v[16:17], v[0:1] op_sel_hi:[1,0]
	v_pk_mul_f32 v[14:15], v[14:15], v[0:1] op_sel_hi:[1,0]
	v_pk_mul_f32 v[12:13], v[12:13], v[0:1] op_sel_hi:[1,0]
	v_pk_mul_f32 v[10:11], v[10:11], v[0:1] op_sel_hi:[1,0]
	v_pk_mul_f32 v[8:9], v[8:9], v[0:1] op_sel_hi:[1,0]
	v_pk_mul_f32 v[6:7], v[6:7], v[0:1] op_sel_hi:[1,0]
	v_pk_mul_f32 v[4:5], v[4:5], v[0:1] op_sel_hi:[1,0]
	v_pk_mul_f32 v[2:3], v[2:3], v[0:1] op_sel_hi:[1,0]

; #define LAS __attribute__((address_space(3)))
; __device__ __forceinline__ unsigned cvtpk(float lo, float hi) { f32x2_t v = {lo, hi}; bf16x2_t b = __builtin_convertvector(v, bf16x2_t); return __builtin_bit_cast(unsigned, b); }
; __device__ __forceinline__ int pi_row(int i) { return (i & ~12) | ((i & 4) << 1) | ((i & 8) >> 1); }
; #define MFMA32(a, b, c) __builtin_amdgcn_mfma_f32_32x32x16_bf16((a), (b), (c), 0, 0, 0)
; template <bool INIT = true> __device__ __forceinline__ void qk_lds(f32x16& p0, f32x16& p1, const LAS unsigned char* buf, const bf16x8 (&qr)[4], int r32, int hi) {
;     const LAS unsigned char* kp = buf + pi_row(r32) * TP + hi * 16;
;     if (INIT) { p0 = (f32x16){}; p1 = (f32x16){}; }
;     bf16x8 kf[8];
; #pragma unroll
;     for (int d0 = 0; d0 < 4; ++d0) { kf[2 * d0] = *(const LAS bf16x8*)(kp + d0 * 32); kf[2 * d0 + 1] = *(const LAS bf16x8*)(kp + 32 * TP + d0 * 32); }
;     __builtin_amdgcn_s_setprio(1);
; #pragma unroll
;     for (int d0 = 0; d0 < 4; ++d0) { p0 = MFMA32(kf[2 * d0], qr[d0], p0); p1 = MFMA32(kf[2 * d0 + 1], qr[d0], p1); }
;     __builtin_amdgcn_s_setprio(0);
; }
; __device__ __forceinline__ void pv_lds(f32x16& o0, f32x16& o1, const LAS unsigned char* buf, const f32x16& p0, const f32x16& p1, int r32, int hi) {
;     const LAS unsigned char* vp = buf + TILE_B + r32 * TP + hi * 16;
;     bf16x8 pf[4], vf[8];
; #pragma unroll
;     for (int half = 0; half < 2; ++half)
; #pragma unroll
;         for (int s = 0; s < 2; ++s) {
;             const f32x16& p = half ? p1 : p0;
;             u32x4 w; w.x = cvtpk(p[8 * s + 0], p[8 * s + 1]); w.y = cvtpk(p[8 * s + 2], p[8 * s + 3]); w.z = cvtpk(p[8 * s + 4], p[8 * s + 5]); w.w = cvtpk(p[8 * s + 6], p[8 * s + 7]);
;             pf[half * 2 + s] = __builtin_bit_cast(bf16x8, w);
;             vf[(half * 2 + s) * 2] = *(const LAS bf16x8*)(vp + half * 64 + s * 32); vf[(half * 2 + s) * 2 + 1] = *(const LAS bf16x8*)(vp + 32 * TP + half * 64 + s * 32);
;         }
;     __builtin_amdgcn_s_setprio(1);
; #pragma unroll
;     for (int k = 0; k < 4; ++k) { o0 = MFMA32(vf[2 * k], pf[k], o0); o1 = MFMA32(vf[2 * k + 1], pf[k], o1); }
;     __builtin_amdgcn_s_setprio(0);
; }
.LBB0_501:
	v_add3_u32 v0, s28, v137, v138
	ds_read_b128 v[2:5], v0
	ds_read_b128 v[6:9], v0 offset:32
	ds_read_b128 v[10:13], v0 offset:4608
	ds_read_b128 v[204:207], v0 offset:4640
	ds_read_b128 v[208:211], v0 offset:64
	ds_read_b128 v[216:219], v0 offset:96
	ds_read_b128 v[220:223], v0 offset:4672
	ds_read_b128 v[224:227], v0 offset:4704
	s_setprio 1
	s_waitcnt lgkmcnt(7)
	v_mfma_f32_32x32x16_bf16 v[48:63], v[2:5], v[84:87], v[48:63]
	s_waitcnt lgkmcnt(5)
	v_mfma_f32_32x32x16_bf16 v[64:79], v[10:13], v[84:87], v[64:79]
	v_mfma_f32_32x32x16_bf16 v[48:63], v[6:9], v[88:91], v[48:63]
	s_waitcnt lgkmcnt(4)
	v_mfma_f32_32x32x16_bf16 v[64:79], v[204:207], v[88:91], v[64:79]
	s_waitcnt lgkmcnt(3)
	v_mfma_f32_32x32x16_bf16 v[48:63], v[208:211], v[96:99], v[48:63]
	s_waitcnt lgkmcnt(1)
	v_mfma_f32_32x32x16_bf16 v[64:79], v[220:223], v[96:99], v[64:79]
	v_mfma_f32_32x32x16_bf16 v[48:63], v[216:219], v[100:103], v[48:63]
	s_waitcnt lgkmcnt(0)
	v_mfma_f32_32x32x16_bf16 v[64:79], v[224:227], v[100:103], v[64:79]
	s_setprio 0
	s_nop 8
	v_exp_f32_e32 v206, v48
	s_nop 0
	v_exp_f32_e32 v207, v64
	v_exp_f32_e32 v2, v49
	v_exp_f32_e32 v0, v65
	v_exp_f32_e32 v208, v66
	v_add_f32_e32 v3, v206, v207
	v_exp_f32_e32 v72, v72
	v_pk_add_f32 v[4:5], v[2:3], v[0:1]
	v_exp_f32_e32 v3, v50
	v_pk_add_f32 v[14:15], v[4:5], v[4:5] op_sel_hi:[0,1]
	v_exp_f32_e32 v4, v51
	v_exp_f32_e32 v14, v67
	v_add_f32_e32 v5, v3, v208
	v_cvt_pk_bf16_f32 v2, v206, v2
	v_cvt_pk_bf16_f32 v3, v3, v4
	v_pk_add_f32 v[6:7], v[4:5], v[14:15]
	v_exp_f32_e32 v5, v52
	v_pk_add_f32 v[64:65], v[6:7], v[6:7] op_sel_hi:[0,1]
	v_exp_f32_e32 v15, v68
	v_exp_f32_e32 v6, v53
	v_exp_f32_e32 v64, v69
	v_add_f32_e32 v7, v5, v15
	v_cvt_pk_bf16_f32 v4, v5, v6
	v_pk_add_f32 v[8:9], v[6:7], v[64:65]
	v_exp_f32_e32 v7, v54
	v_pk_add_f32 v[66:67], v[8:9], v[8:9] op_sel_hi:[0,1]
	v_exp_f32_e32 v65, v70
	v_exp_f32_e32 v8, v55
	v_exp_f32_e32 v66, v71
	v_exp_f32_e32 v54, v56
	v_add_f32_e32 v9, v7, v65
	v_cvt_pk_bf16_f32 v5, v7, v8
	v_pk_add_f32 v[10:11], v[8:9], v[66:67]
	s_nop 0
	v_pk_add_f32 v[202:203], v[10:11], v[10:11] op_sel_hi:[0,1]
	v_exp_f32_e32 v10, v57
	v_exp_f32_e32 v202, v73
	v_add_f32_e32 v11, v54, v72
	v_exp_f32_e32 v73, v74
	v_pk_add_f32 v[12:13], v[10:11], v[202:203]
	s_nop 0
	v_pk_add_f32 v[204:205], v[12:13], v[12:13] op_sel_hi:[0,1]
	v_exp_f32_e32 v11, v58
	v_exp_f32_e32 v12, v59
	v_exp_f32_e32 v204, v75
	v_exp_f32_e32 v203, v76
	v_add_f32_e32 v13, v11, v73
	v_cvt_pk_bf16_f32 v10, v54, v10
	v_pk_add_f32 v[48:49], v[12:13], v[204:205]
	v_exp_f32_e32 v13, v60
	v_pk_add_f32 v[74:75], v[48:49], v[48:49] op_sel_hi:[0,1]
	v_exp_f32_e32 v48, v61
	v_exp_f32_e32 v74, v77
	v_add_f32_e32 v49, v13, v203
	v_add3_u32 v205, s28, v139, v138
	v_cvt_pk_bf16_f32 v11, v11, v12
	v_pk_add_f32 v[50:51], v[48:49], v[74:75]
	v_exp_f32_e32 v49, v62
	v_pk_add_f32 v[76:77], v[50:51], v[50:51] op_sel_hi:[0,1]
	v_exp_f32_e32 v75, v78
	v_exp_f32_e32 v50, v63
	v_exp_f32_e32 v76, v79
	v_cvt_pk_bf16_f32 v12, v13, v48
	v_add_f32_e32 v51, v49, v75
	v_cvt_pk_bf16_f32 v13, v49, v50
	v_pk_add_f32 v[52:53], v[50:51], v[76:77]
	v_cvt_pk_bf16_f32 v60, v207, v0
	v_add_f32_e32 v9, v52, v53
	v_add_f32_e32 v214, v214, v9
	ds_read_b128 v[6:9], v205 offset:13824
	ds_read_b128 v[48:51], v205 offset:9216
	ds_read_b128 v[52:55], v205 offset:9248
	ds_read_b128 v[56:59], v205 offset:13856
	v_cvt_pk_bf16_f32 v62, v15, v64
	v_cvt_pk_bf16_f32 v63, v65, v66
	ds_read_b128 v[64:67], v205 offset:9280
	ds_read_b128 v[68:71], v205 offset:13888
	v_cvt_pk_bf16_f32 v73, v73, v204
	v_cvt_pk_bf16_f32 v75, v75, v76
	ds_read_b128 v[76:79], v205 offset:9312
	ds_read_b128 v[204:207], v205 offset:13920
	v_cvt_pk_bf16_f32 v61, v208, v14
	v_cvt_pk_bf16_f32 v72, v72, v202
	v_cvt_pk_bf16_f32 v74, v203, v74
	s_setprio 1
	s_waitcnt lgkmcnt(6)
	v_mfma_f32_32x32x16_bf16 v[32:47], v[48:51], v[2:5], v[32:47]
	v_mfma_f32_32x32x16_bf16 v[16:31], v[6:9], v[2:5], v[16:31]
	s_waitcnt lgkmcnt(5)
	v_mfma_f32_32x32x16_bf16 v[32:47], v[52:55], v[10:13], v[32:47]
	s_waitcnt lgkmcnt(4)
	v_mfma_f32_32x32x16_bf16 v[16:31], v[56:59], v[10:13], v[16:31]
	s_waitcnt lgkmcnt(3)
	v_mfma_f32_32x32x16_bf16 v[32:47], v[64:67], v[60:63], v[32:47]
	s_waitcnt lgkmcnt(2)
	v_mfma_f32_32x32x16_bf16 v[16:31], v[68:71], v[60:63], v[16:31]
	s_waitcnt lgkmcnt(1)
	v_mfma_f32_32x32x16_bf16 v[32:47], v[76:79], v[72:75], v[32:47]
	s_waitcnt lgkmcnt(0)
	v_mfma_f32_32x32x16_bf16 v[16:31], v[204:207], v[72:75], v[16:31]
	s_setprio 0

; #define LAS __attribute__((address_space(3)))
; __device__ __forceinline__ unsigned cvtpk(float lo, float hi) { f32x2_t v = {lo, hi}; bf16x2_t b = __builtin_convertvector(v, bf16x2_t); return __builtin_bit_cast(unsigned, b); }
; __device__ __forceinline__ int pi_row(int i) { return (i & ~12) | ((i & 4) << 1) | ((i & 8) >> 1); }
; #define MFMA32(a, b, c) __builtin_amdgcn_mfma_f32_32x32x16_bf16((a), (b), (c), 0, 0, 0)
; template <bool INIT = true> __device__ __forceinline__ void qk_lds(f32x16& p0, f32x16& p1, const LAS unsigned char* buf, const bf16x8 (&qr)[4], int r32, int hi) {
;     const LAS unsigned char* kp = buf + pi_row(r32) * TP + hi * 16;
;     if (INIT) { p0 = (f32x16){}; p1 = (f32x16){}; }
;     bf16x8 kf[8];
; #pragma unroll
;     for (int d0 = 0; d0 < 4; ++d0) { kf[2 * d0] = *(const LAS bf16x8*)(kp + d0 * 32); kf[2 * d0 + 1] = *(const LAS bf16x8*)(kp + 32 * TP + d0 * 32); }
;     __builtin_amdgcn_s_setprio(1);
; #pragma unroll
;     for (int d0 = 0; d0 < 4; ++d0) { p0 = MFMA32(kf[2 * d0], qr[d0], p0); p1 = MFMA32(kf[2 * d0 + 1], qr[d0], p1); }
;     __builtin_amdgcn_s_setprio(0);
; }
; __device__ __forceinline__ void pv_lds(f32x16& o0, f32x16& o1, const LAS unsigned char* buf, const f32x16& p0, const f32x16& p1, int r32, int hi) {
;     const LAS unsigned char* vp = buf + TILE_B + r32 * TP + hi * 16;
;     bf16x8 pf[4], vf[8];
; #pragma unroll
;     for (int half = 0; half < 2; ++half)
; #pragma unroll
;         for (int s = 0; s < 2; ++s) {
;             const f32x16& p = half ? p1 : p0;
;             u32x4 w; w.x = cvtpk(p[8 * s + 0], p[8 * s + 1]); w.y = cvtpk(p[8 * s + 2], p[8 * s + 3]); w.z = cvtpk(p[8 * s + 4], p[8 * s + 5]); w.w = cvtpk(p[8 * s + 6], p[8 * s + 7]);
;             pf[half * 2 + s] = __builtin_bit_cast(bf16x8, w);
;             vf[(half * 2 + s) * 2] = *(const LAS bf16x8*)(vp + half * 64 + s * 32); vf[(half * 2 + s) * 2 + 1] = *(const LAS bf16x8*)(vp + 32 * TP + half * 64 + s * 32);
;         }
;     __builtin_amdgcn_s_setprio(1);
; #pragma unroll
;     for (int k = 0; k < 4; ++k) { o0 = MFMA32(vf[2 * k], pf[k], o0); o1 = MFMA32(vf[2 * k + 1], pf[k], o1); }
;     __builtin_amdgcn_s_setprio(0);
; }
.LBB0_512:
	v_add3_u32 v0, s28, v137, v138
	ds_read_b128 v[2:5], v0 offset:18432
	ds_read_b128 v[6:9], v0 offset:18464
	ds_read_b128 v[10:13], v0 offset:23040
	ds_read_b128 v[204:207], v0 offset:23072
	ds_read_b128 v[208:211], v0 offset:18496
	ds_read_b128 v[216:219], v0 offset:18528
	ds_read_b128 v[220:223], v0 offset:23104
	ds_read_b128 v[224:227], v0 offset:23136
	s_setprio 1
	s_waitcnt lgkmcnt(7)
	v_mfma_f32_32x32x16_bf16 v[64:79], v[2:5], v[84:87], v[64:79]
	s_waitcnt lgkmcnt(5)
	v_mfma_f32_32x32x16_bf16 v[48:63], v[10:13], v[84:87], v[48:63]
	v_mfma_f32_32x32x16_bf16 v[64:79], v[6:9], v[88:91], v[64:79]
	s_waitcnt lgkmcnt(4)
	v_mfma_f32_32x32x16_bf16 v[48:63], v[204:207], v[88:91], v[48:63]
	s_waitcnt lgkmcnt(3)
	v_mfma_f32_32x32x16_bf16 v[64:79], v[208:211], v[96:99], v[64:79]
	s_waitcnt lgkmcnt(1)
	v_mfma_f32_32x32x16_bf16 v[48:63], v[220:223], v[96:99], v[48:63]
	v_mfma_f32_32x32x16_bf16 v[64:79], v[216:219], v[100:103], v[64:79]
	s_waitcnt lgkmcnt(0)
	v_mfma_f32_32x32x16_bf16 v[48:63], v[224:227], v[100:103], v[48:63]
	s_setprio 0
	s_nop 8
	v_exp_f32_e32 v206, v64
	s_nop 0
	v_exp_f32_e32 v207, v48
	v_exp_f32_e32 v2, v65
	v_exp_f32_e32 v0, v49
	v_exp_f32_e32 v208, v50
	v_add_f32_e32 v3, v206, v207
	v_pk_add_f32 v[4:5], v[2:3], v[0:1]
	s_nop 0
	v_pk_add_f32 v[14:15], v[4:5], v[4:5] op_sel_hi:[0,1]
	v_exp_f32_e32 v3, v66
	v_exp_f32_e32 v4, v67
	v_exp_f32_e32 v14, v51
	v_cvt_pk_bf16_f32 v2, v206, v2
	v_add_f32_e32 v5, v3, v208
	v_cvt_pk_bf16_f32 v3, v3, v4
	v_pk_add_f32 v[6:7], v[4:5], v[14:15]
	v_exp_f32_e32 v5, v68
	v_pk_add_f32 v[64:65], v[6:7], v[6:7] op_sel_hi:[0,1]
	v_exp_f32_e32 v15, v52
	v_exp_f32_e32 v6, v69
	v_exp_f32_e32 v64, v53
	v_add_f32_e32 v7, v5, v15
	v_cvt_pk_bf16_f32 v4, v5, v6
	v_pk_add_f32 v[8:9], v[6:7], v[64:65]
	v_exp_f32_e32 v7, v70
	v_pk_add_f32 v[66:67], v[8:9], v[8:9] op_sel_hi:[0,1]
	v_exp_f32_e32 v65, v54
	v_exp_f32_e32 v8, v71
	v_exp_f32_e32 v66, v55
	v_exp_f32_e32 v54, v72
	v_add_f32_e32 v9, v7, v65
	v_exp_f32_e32 v72, v56
	v_pk_add_f32 v[10:11], v[8:9], v[66:67]
	v_cvt_pk_bf16_f32 v5, v7, v8
	v_pk_add_f32 v[202:203], v[10:11], v[10:11] op_sel_hi:[0,1]
	v_exp_f32_e32 v10, v73
	v_exp_f32_e32 v202, v57
	v_add_f32_e32 v11, v54, v72
	v_exp_f32_e32 v73, v58
	v_pk_add_f32 v[12:13], v[10:11], v[202:203]
	s_nop 0
	v_pk_add_f32 v[204:205], v[12:13], v[12:13] op_sel_hi:[0,1]
	v_exp_f32_e32 v11, v74
	v_exp_f32_e32 v12, v75
	v_exp_f32_e32 v204, v59
	v_exp_f32_e32 v203, v60
	v_add_f32_e32 v13, v11, v73
	v_cvt_pk_bf16_f32 v10, v54, v10
	v_pk_add_f32 v[48:49], v[12:13], v[204:205]
	v_exp_f32_e32 v13, v76
	v_pk_add_f32 v[74:75], v[48:49], v[48:49] op_sel_hi:[0,1]
	v_exp_f32_e32 v48, v77
	v_exp_f32_e32 v74, v61
	v_add_f32_e32 v49, v13, v203
	v_add3_u32 v205, s28, v139, v138
	v_cvt_pk_bf16_f32 v11, v11, v12
	v_pk_add_f32 v[50:51], v[48:49], v[74:75]
	v_exp_f32_e32 v49, v78
	v_pk_add_f32 v[76:77], v[50:51], v[50:51] op_sel_hi:[0,1]
	v_exp_f32_e32 v75, v62
	v_exp_f32_e32 v50, v79
	v_exp_f32_e32 v76, v63
	v_cvt_pk_bf16_f32 v12, v13, v48
	v_add_f32_e32 v51, v49, v75
	v_cvt_pk_bf16_f32 v13, v49, v50
	v_pk_add_f32 v[52:53], v[50:51], v[76:77]
	v_cvt_pk_bf16_f32 v60, v207, v0
	v_add_f32_e32 v9, v52, v53
	v_add_f32_e32 v214, v214, v9
	ds_read_b128 v[6:9], v205 offset:32256
	ds_read_b128 v[48:51], v205 offset:27648
	ds_read_b128 v[52:55], v205 offset:27680
	ds_read_b128 v[56:59], v205 offset:32288
	v_cvt_pk_bf16_f32 v62, v15, v64
	v_cvt_pk_bf16_f32 v63, v65, v66
	ds_read_b128 v[64:67], v205 offset:27712
	ds_read_b128 v[68:71], v205 offset:32320
	v_cvt_pk_bf16_f32 v73, v73, v204
	v_cvt_pk_bf16_f32 v75, v75, v76
	ds_read_b128 v[76:79], v205 offset:27744
	ds_read_b128 v[204:207], v205 offset:32352
	v_cvt_pk_bf16_f32 v61, v208, v14
	v_cvt_pk_bf16_f32 v72, v72, v202
	v_cvt_pk_bf16_f32 v74, v203, v74
	s_setprio 1
	s_waitcnt lgkmcnt(6)
	v_mfma_f32_32x32x16_bf16 v[32:47], v[48:51], v[2:5], v[32:47]
	v_mfma_f32_32x32x16_bf16 v[16:31], v[6:9], v[2:5], v[16:31]
	s_waitcnt lgkmcnt(5)
	v_mfma_f32_32x32x16_bf16 v[32:47], v[52:55], v[10:13], v[32:47]
	s_waitcnt lgkmcnt(4)
	v_mfma_f32_32x32x16_bf16 v[16:31], v[56:59], v[10:13], v[16:31]
	s_waitcnt lgkmcnt(3)
	v_mfma_f32_32x32x16_bf16 v[32:47], v[64:67], v[60:63], v[32:47]
	s_waitcnt lgkmcnt(2)
	v_mfma_f32_32x32x16_bf16 v[16:31], v[68:71], v[60:63], v[16:31]
	s_waitcnt lgkmcnt(1)
	v_mfma_f32_32x32x16_bf16 v[32:47], v[76:79], v[72:75], v[32:47]
	s_waitcnt lgkmcnt(0)
	v_mfma_f32_32x32x16_bf16 v[16:31], v[204:207], v[72:75], v[16:31]
	s_setprio 0

; #define LAS __attribute__((address_space(3)))
; __device__ __forceinline__ int pi_row(int i) { return (i & ~12) | ((i & 4) << 1) | ((i & 8) >> 1); }
; #define MFMA32(a, b, c) __builtin_amdgcn_mfma_f32_32x32x16_bf16((a), (b), (c), 0, 0, 0)
; template <bool INIT = true> __device__ __forceinline__ void qk_lds(f32x16& p0, f32x16& p1, const LAS unsigned char* buf, const bf16x8 (&qr)[4], int r32, int hi) {
;     const LAS unsigned char* kp = buf + pi_row(r32) * TP + hi * 16;
;     if (INIT) { p0 = (f32x16){}; p1 = (f32x16){}; }
;     bf16x8 kf[8];
; #pragma unroll
;     for (int d0 = 0; d0 < 4; ++d0) { kf[2 * d0] = *(const LAS bf16x8*)(kp + d0 * 32); kf[2 * d0 + 1] = *(const LAS bf16x8*)(kp + 32 * TP + d0 * 32); }
;     __builtin_amdgcn_s_setprio(1);
; #pragma unroll
;     for (int d0 = 0; d0 < 4; ++d0) { p0 = MFMA32(kf[2 * d0], qr[d0], p0); p1 = MFMA32(kf[2 * d0 + 1], qr[d0], p1); }
;     __builtin_amdgcn_s_setprio(0);
; }
; __device__ __forceinline__ void b_mask_init(f32x16& p0, f32x16& p1, unsigned long long mw, int hi, float ref) {
;     const int n0 = (int)~((unsigned)mw >> (8 * hi)), n1 = (int)~((unsigned)(mw >> 32) >> (8 * hi)); const int nr = __float_as_int(-ref);
; #pragma unroll
;     for (int r = 0; r < 16; ++r) { const int bit = 16 * (r >> 3) + (r & 7);
;         const int e0 = __builtin_amdgcn_sbfe(n0, bit, 1), e1 = __builtin_amdgcn_sbfe(n1, bit, 1);
;         p0[r] = __int_as_float((e0 & (int)0xFF800000) | (~e0 & nr)); p1[r] = __int_as_float((e1 & (int)0xFF800000) | (~e1 & nr)); }
; }
.LBB0_756:
	s_bitcmp1_b32 s18, 0
	s_cselect_b32 s21, 0x9000, 0
	s_add_i32 s21, s21, 0
	s_cmp_gt_i32 s22, s17
	v_add3_u32 v0, s21, v141, v142
	s_cbranch_scc1 .LBB0_764
	v_lshrrev_b32_e32 v2, v118, v2
	v_and_b32_e32 v6, 2, v2
	v_cmp_eq_u32_e32 vcc, 0, v6
	v_lshrrev_b32_e32 v3, v118, v3
	v_and_b32_e32 v7, 1, v2
	v_cndmask_b32_e32 v8, 0, v240, vcc
	v_lshlrev_b32_e32 v6, 30, v6
	v_cmp_eq_u32_e32 vcc, 0, v7
	v_or_b32_e32 v49, v8, v6
	v_and_b32_e32 v6, 2, v3
	v_cndmask_b32_e32 v7, 0, v240, vcc
	v_lshlrev_b32_e32 v9, 31, v2
	v_cmp_eq_u32_e32 vcc, 0, v6
	v_or_b32_e32 v48, v7, v9
	v_and_b32_e32 v7, 1, v3
	v_cndmask_b32_e32 v8, 0, v240, vcc
	v_lshlrev_b32_e32 v6, 30, v6
	v_cmp_eq_u32_e32 vcc, 0, v7
	v_or_b32_e32 v65, v8, v6
	v_and_b32_e32 v6, 8, v2
	v_cndmask_b32_e32 v7, 0, v240, vcc
	v_lshlrev_b32_e32 v9, 31, v3
	v_cmp_eq_u32_e32 vcc, 0, v6
	v_or_b32_e32 v64, v7, v9
	v_and_b32_e32 v7, 4, v2
	v_cndmask_b32_e32 v8, 0, v240, vcc
	v_lshlrev_b32_e32 v6, 28, v6
	v_cmp_eq_u32_e32 vcc, 0, v7
	v_or_b32_e32 v51, v8, v6
	v_and_b32_e32 v6, 8, v3
	v_cndmask_b32_e32 v9, 0, v240, vcc
	v_lshlrev_b32_e32 v7, 29, v7
	v_cmp_eq_u32_e32 vcc, 0, v6
	v_or_b32_e32 v50, v9, v7
	v_and_b32_e32 v7, 4, v3
	v_cndmask_b32_e32 v8, 0, v240, vcc
	v_lshlrev_b32_e32 v6, 28, v6
	v_cmp_eq_u32_e32 vcc, 0, v7
	v_or_b32_e32 v67, v8, v6
	v_and_b32_e32 v6, 32, v2
	v_cndmask_b32_e32 v9, 0, v240, vcc
	v_lshlrev_b32_e32 v7, 29, v7
	v_cmp_eq_u32_e32 vcc, 0, v6
	v_or_b32_e32 v66, v9, v7
	v_and_b32_e32 v7, 16, v2
	v_cndmask_b32_e32 v8, 0, v240, vcc
	v_lshlrev_b32_e32 v6, 26, v6
	v_cmp_eq_u32_e32 vcc, 0, v7
	v_or_b32_e32 v53, v8, v6
	v_and_b32_e32 v6, 32, v3
	v_cndmask_b32_e32 v9, 0, v240, vcc
	v_lshlrev_b32_e32 v7, 27, v7
	v_cmp_eq_u32_e32 vcc, 0, v6
	v_or_b32_e32 v52, v9, v7
	v_and_b32_e32 v7, 16, v3
	v_cndmask_b32_e32 v8, 0, v240, vcc
	v_lshlrev_b32_e32 v6, 26, v6
	v_cmp_eq_u32_e32 vcc, 0, v7
	v_or_b32_e32 v69, v8, v6
	v_and_b32_e32 v6, 0x80, v2
	v_cndmask_b32_e32 v9, 0, v240, vcc
	v_lshlrev_b32_e32 v7, 27, v7
	v_cmp_eq_u32_e32 vcc, 0, v6
	v_or_b32_e32 v68, v9, v7
	v_and_b32_e32 v7, 64, v2
	v_cndmask_b32_e32 v8, 0, v240, vcc
	v_lshlrev_b32_e32 v6, 24, v6
	v_cmp_eq_u32_e32 vcc, 0, v7
	v_or_b32_e32 v55, v8, v6
	v_and_b32_e32 v6, 0x80, v3
	v_cndmask_b32_e32 v9, 0, v240, vcc
	v_lshlrev_b32_e32 v7, 25, v7
	v_cmp_eq_u32_e32 vcc, 0, v6
	v_or_b32_e32 v54, v9, v7
	v_and_b32_e32 v7, 64, v3
	v_cndmask_b32_e32 v8, 0, v240, vcc
	v_lshlrev_b32_e32 v6, 24, v6
	v_cmp_eq_u32_e32 vcc, 0, v7
	v_or_b32_e32 v71, v8, v6
	v_and_b32_e32 v6, 0x20000, v2
	v_cndmask_b32_e32 v9, 0, v240, vcc
	v_lshlrev_b32_e32 v7, 25, v7
	v_cmp_eq_u32_e32 vcc, 0, v6
	v_or_b32_e32 v70, v9, v7
	v_and_b32_e32 v7, 0x10000, v2
	v_cndmask_b32_e32 v8, 0, v240, vcc
	v_lshlrev_b32_e32 v6, 14, v6
	v_cmp_eq_u32_e32 vcc, 0, v7
	v_or_b32_e32 v57, v8, v6
	v_and_b32_e32 v6, 0x20000, v3
	v_cndmask_b32_e32 v9, 0, v240, vcc
	v_lshlrev_b32_e32 v7, 15, v7
	v_cmp_eq_u32_e32 vcc, 0, v6
	v_or_b32_e32 v56, v9, v7
	v_and_b32_e32 v7, 0x10000, v3
	v_cndmask_b32_e32 v8, 0, v240, vcc
	v_lshlrev_b32_e32 v6, 14, v6
	v_cmp_eq_u32_e32 vcc, 0, v7
	v_or_b32_e32 v73, v8, v6
	v_and_b32_e32 v6, 0x80000, v2
	v_cndmask_b32_e32 v9, 0, v240, vcc
	v_lshlrev_b32_e32 v7, 15, v7
	v_cmp_eq_u32_e32 vcc, 0, v6
	v_or_b32_e32 v72, v9, v7
	v_and_b32_e32 v7, 0x40000, v2
	v_cndmask_b32_e32 v8, 0, v240, vcc
	v_lshlrev_b32_e32 v6, 12, v6
	v_cmp_eq_u32_e32 vcc, 0, v7
	v_or_b32_e32 v59, v8, v6
	v_and_b32_e32 v6, 0x80000, v3
	v_cndmask_b32_e32 v9, 0, v240, vcc
	v_lshlrev_b32_e32 v7, 13, v7
	v_cmp_eq_u32_e32 vcc, 0, v6
	v_or_b32_e32 v58, v9, v7
	v_and_b32_e32 v7, 0x40000, v3
	v_cndmask_b32_e32 v8, 0, v240, vcc
	v_lshlrev_b32_e32 v6, 12, v6
	v_cmp_eq_u32_e32 vcc, 0, v7
	v_or_b32_e32 v75, v8, v6
	v_and_b32_e32 v6, 0x200000, v2
	v_cndmask_b32_e32 v9, 0, v240, vcc
	v_lshlrev_b32_e32 v7, 13, v7
	v_cmp_eq_u32_e32 vcc, 0, v6
	v_or_b32_e32 v74, v9, v7
	v_and_b32_e32 v7, 0x100000, v2
	v_cndmask_b32_e32 v8, 0, v240, vcc
	v_lshlrev_b32_e32 v6, 10, v6
	v_cmp_eq_u32_e32 vcc, 0, v7
	v_or_b32_e32 v61, v8, v6
	v_and_b32_e32 v6, 0x200000, v3
	v_cndmask_b32_e32 v9, 0, v240, vcc
	v_lshlrev_b32_e32 v7, 11, v7
	v_cmp_eq_u32_e32 vcc, 0, v6
	v_or_b32_e32 v60, v9, v7
	v_and_b32_e32 v7, 0x100000, v3
	v_cndmask_b32_e32 v8, 0, v240, vcc
	v_lshlrev_b32_e32 v6, 10, v6
	v_cmp_eq_u32_e32 vcc, 0, v7
	v_or_b32_e32 v77, v8, v6
	v_and_b32_e32 v6, 0x800000, v2
	v_cndmask_b32_e32 v9, 0, v240, vcc
	v_lshlrev_b32_e32 v7, 11, v7
	v_and_b32_e32 v2, 0x400000, v2
	v_cmp_eq_u32_e32 vcc, 0, v6
	v_or_b32_e32 v76, v9, v7
	v_lshlrev_b32_e32 v6, 8, v6
	v_cndmask_b32_e32 v7, 0, v240, vcc
	v_cmp_eq_u32_e32 vcc, 0, v2
	v_lshlrev_b32_e32 v2, 9, v2
	v_or_b32_e32 v63, v7, v6
	v_cndmask_b32_e32 v8, 0, v240, vcc
	v_or_b32_e32 v62, v8, v2
	ds_read_b128 v[6:9], v0
	ds_read_b128 v[10:13], v0 offset:32
	ds_read_b128 v[144:147], v0 offset:4608
	ds_read_b128 v[148:151], v0 offset:4640
	ds_read_b128 v[152:155], v0 offset:64
	ds_read_b128 v[158:161], v0 offset:96
	ds_read_b128 v[162:165], v0 offset:4672
	ds_read_b128 v[166:169], v0 offset:4704
	v_and_b32_e32 v2, 0x800000, v3
	v_and_b32_e32 v3, 0x400000, v3
	v_cmp_eq_u32_e32 vcc, 0, v2
	v_lshlrev_b32_e32 v2, 8, v2
	s_nop 0
	v_cndmask_b32_e32 v14, 0, v240, vcc
	v_cmp_eq_u32_e32 vcc, 0, v3
	v_lshlrev_b32_e32 v3, 9, v3
	v_or_b32_e32 v79, v14, v2
	v_cndmask_b32_e32 v15, 0, v240, vcc
	v_or_b32_e32 v78, v15, v3
	s_setprio 1
	s_waitcnt lgkmcnt(7)
	v_mfma_f32_32x32x16_bf16 v[48:63], v[6:9], v[80:83], v[48:63]
	s_waitcnt lgkmcnt(5)
	v_mfma_f32_32x32x16_bf16 v[64:79], v[144:147], v[80:83], v[64:79]
	v_mfma_f32_32x32x16_bf16 v[48:63], v[10:13], v[84:87], v[48:63]
	s_waitcnt lgkmcnt(4)
	v_mfma_f32_32x32x16_bf16 v[64:79], v[148:151], v[84:87], v[64:79]
	s_waitcnt lgkmcnt(3)
	v_mfma_f32_32x32x16_bf16 v[48:63], v[152:155], v[92:95], v[48:63]
	s_waitcnt lgkmcnt(1)
	v_mfma_f32_32x32x16_bf16 v[64:79], v[162:165], v[92:95], v[64:79]
	v_mfma_f32_32x32x16_bf16 v[48:63], v[158:161], v[96:99], v[48:63]
	s_waitcnt lgkmcnt(0)
	v_mfma_f32_32x32x16_bf16 v[64:79], v[166:169], v[96:99], v[64:79]
	s_setprio 0
	s_nop 8
	v_max_f32_e32 v2, v49, v49
	v_max_f32_e32 v3, v48, v48
	v_max_f32_e32 v2, v3, v2
	v_max3_f32 v3, v64, v65, v66
	v_max3_f32 v2, v2, v50, v51
	v_max3_f32 v3, v3, v67, v68
	v_max3_f32 v2, v2, v52, v53
	v_max3_f32 v3, v3, v69, v70
	v_max3_f32 v2, v2, v54, v55
	v_max3_f32 v3, v3, v71, v72
	v_max3_f32 v2, v2, v56, v57
	v_max3_f32 v3, v3, v73, v74
	v_max3_f32 v2, v2, v58, v59
	v_max3_f32 v3, v3, v75, v76
	v_max3_f32 v2, v2, v60, v61
	v_max3_f32 v3, v3, v77, v78
	v_max3_f32 v2, v2, v62, v3
	v_max3_f32 v2, v2, v63, v79
	ds_bpermute_b32 v3, v156, v2
	s_waitcnt lgkmcnt(0)
	v_max3_f32 v2, v131, v2, v3
	v_cmp_eq_f32_e32 vcc, v2, v131
	s_cmp_eq_u64 vcc, exec
	s_cbranch_scc1 .LBB0_759
; __device__ __forceinline__ void softmax_step(f32x16& p0, f32x16& p1, float& m, float& l, f32x16& o0, f32x16& o1) {
;     ...
;     if (!__all(mn == m)) {
;         const float alpha = __builtin_amdgcn_exp2f(m - mn); m = mn; l *= alpha;
; #pragma unroll
;         for (int r = 0; r < 16; ++r) { o0[r] *= alpha; o1[r] *= alpha; }
	v_sub_f32_e32 v3, v131, v2
	v_exp_f32_e32 v6, v3
	v_mov_b32_e32 v131, v2
	v_mul_f32_e32 v129, v129, v6
	v_pk_mul_f32 v[46:47], v[46:47], v[6:7] op_sel_hi:[1,0]
	v_pk_mul_f32 v[44:45], v[44:45], v[6:7] op_sel_hi:[1,0]
	v_pk_mul_f32 v[42:43], v[42:43], v[6:7] op_sel_hi:[1,0]
	v_pk_mul_f32 v[40:41], v[40:41], v[6:7] op_sel_hi:[1,0]
	v_pk_mul_f32 v[38:39], v[38:39], v[6:7] op_sel_hi:[1,0]
	v_pk_mul_f32 v[36:37], v[36:37], v[6:7] op_sel_hi:[1,0]
	v_pk_mul_f32 v[34:35], v[34:35], v[6:7] op_sel_hi:[1,0]
	v_pk_mul_f32 v[32:33], v[32:33], v[6:7] op_sel_hi:[1,0]
	v_pk_mul_f32 v[30:31], v[30:31], v[6:7] op_sel_hi:[1,0]
	v_pk_mul_f32 v[28:29], v[28:29], v[6:7] op_sel_hi:[1,0]
	v_pk_mul_f32 v[26:27], v[26:27], v[6:7] op_sel_hi:[1,0]
	v_pk_mul_f32 v[24:25], v[24:25], v[6:7] op_sel_hi:[1,0]
	v_pk_mul_f32 v[22:23], v[22:23], v[6:7] op_sel_hi:[1,0]
	v_pk_mul_f32 v[20:21], v[20:21], v[6:7] op_sel_hi:[1,0]
	v_pk_mul_f32 v[18:19], v[18:19], v[6:7] op_sel_hi:[1,0]
	v_pk_mul_f32 v[16:17], v[16:17], v[6:7] op_sel_hi:[1,0]

; #define LAS __attribute__((address_space(3)))
; __device__ __forceinline__ int pi_row(int i) { return (i & ~12) | ((i & 4) << 1) | ((i & 8) >> 1); }
; #define MFMA32(a, b, c) __builtin_amdgcn_mfma_f32_32x32x16_bf16((a), (b), (c), 0, 0, 0)
; template <bool INIT = true> __device__ __forceinline__ void qk_lds(f32x16& p0, f32x16& p1, const LAS unsigned char* buf, const bf16x8 (&qr)[4], int r32, int hi) {
;     const LAS unsigned char* kp = buf + pi_row(r32) * TP + hi * 16;
;     if (INIT) { p0 = (f32x16){}; p1 = (f32x16){}; }
;     bf16x8 kf[8];
; #pragma unroll
;     for (int d0 = 0; d0 < 4; ++d0) { kf[2 * d0] = *(const LAS bf16x8*)(kp + d0 * 32); kf[2 * d0 + 1] = *(const LAS bf16x8*)(kp + 32 * TP + d0 * 32); }
;     __builtin_amdgcn_s_setprio(1);
; #pragma unroll
;     for (int d0 = 0; d0 < 4; ++d0) { p0 = MFMA32(kf[2 * d0], qr[d0], p0); p1 = MFMA32(kf[2 * d0 + 1], qr[d0], p1); }
;     __builtin_amdgcn_s_setprio(0);
; }
; __device__ __forceinline__ void b_mask_init(f32x16& p0, f32x16& p1, unsigned long long mw, int hi, float ref) {
;     const int n0 = (int)~((unsigned)mw >> (8 * hi)), n1 = (int)~((unsigned)(mw >> 32) >> (8 * hi)); const int nr = __float_as_int(-ref);
; #pragma unroll
;     for (int r = 0; r < 16; ++r) { const int bit = 16 * (r >> 3) + (r & 7);
;         const int e0 = __builtin_amdgcn_sbfe(n0, bit, 1), e1 = __builtin_amdgcn_sbfe(n1, bit, 1);
;         p0[r] = __int_as_float((e0 & (int)0xFF800000) | (~e0 & nr)); p1[r] = __int_as_float((e1 & (int)0xFF800000) | (~e1 & nr)); }
; }
.LBB0_765:
	v_lshrrev_b32_e32 v2, v118, v4
	v_and_b32_e32 v4, 2, v2
	v_cmp_eq_u32_e32 vcc, 0, v4
	v_lshrrev_b32_e32 v3, v118, v5
	v_and_b32_e32 v5, 1, v2
	v_cndmask_b32_e32 v6, 0, v240, vcc
	v_lshlrev_b32_e32 v4, 30, v4
	v_cmp_eq_u32_e32 vcc, 0, v5
	v_or_b32_e32 v49, v6, v4
	v_and_b32_e32 v4, 2, v3
	v_cndmask_b32_e32 v5, 0, v240, vcc
	v_lshlrev_b32_e32 v7, 31, v2
	v_cmp_eq_u32_e32 vcc, 0, v4
	v_or_b32_e32 v48, v5, v7
	v_and_b32_e32 v5, 1, v3
	v_cndmask_b32_e32 v6, 0, v240, vcc
	v_lshlrev_b32_e32 v4, 30, v4
	v_cmp_eq_u32_e32 vcc, 0, v5
	v_or_b32_e32 v65, v6, v4
	v_and_b32_e32 v4, 8, v2
	v_cndmask_b32_e32 v5, 0, v240, vcc
	v_lshlrev_b32_e32 v7, 31, v3
	v_cmp_eq_u32_e32 vcc, 0, v4
	v_or_b32_e32 v64, v5, v7
	v_and_b32_e32 v5, 4, v2
	v_cndmask_b32_e32 v6, 0, v240, vcc
	v_lshlrev_b32_e32 v4, 28, v4
	v_cmp_eq_u32_e32 vcc, 0, v5
	v_or_b32_e32 v51, v6, v4
	v_and_b32_e32 v4, 8, v3
	v_cndmask_b32_e32 v7, 0, v240, vcc
	v_lshlrev_b32_e32 v5, 29, v5
	v_cmp_eq_u32_e32 vcc, 0, v4
	v_or_b32_e32 v50, v7, v5
	v_and_b32_e32 v5, 4, v3
	v_cndmask_b32_e32 v6, 0, v240, vcc
	v_lshlrev_b32_e32 v4, 28, v4
	v_cmp_eq_u32_e32 vcc, 0, v5
	v_or_b32_e32 v67, v6, v4
	v_and_b32_e32 v4, 32, v2
	v_cndmask_b32_e32 v7, 0, v240, vcc
	v_lshlrev_b32_e32 v5, 29, v5
	v_cmp_eq_u32_e32 vcc, 0, v4
	v_or_b32_e32 v66, v7, v5
	v_and_b32_e32 v5, 16, v2
	v_cndmask_b32_e32 v6, 0, v240, vcc
	v_lshlrev_b32_e32 v4, 26, v4
	v_cmp_eq_u32_e32 vcc, 0, v5
	v_or_b32_e32 v53, v6, v4
	v_and_b32_e32 v4, 32, v3
	v_cndmask_b32_e32 v7, 0, v240, vcc
	v_lshlrev_b32_e32 v5, 27, v5
	v_cmp_eq_u32_e32 vcc, 0, v4
	v_or_b32_e32 v52, v7, v5
	v_and_b32_e32 v5, 16, v3
	v_cndmask_b32_e32 v6, 0, v240, vcc
	v_lshlrev_b32_e32 v4, 26, v4
	v_cmp_eq_u32_e32 vcc, 0, v5
	v_or_b32_e32 v69, v6, v4
	v_and_b32_e32 v4, 0x80, v2
	v_cndmask_b32_e32 v7, 0, v240, vcc
	v_lshlrev_b32_e32 v5, 27, v5
	v_cmp_eq_u32_e32 vcc, 0, v4
	v_or_b32_e32 v68, v7, v5
	v_and_b32_e32 v5, 64, v2
	v_cndmask_b32_e32 v6, 0, v240, vcc
	v_lshlrev_b32_e32 v4, 24, v4
	v_cmp_eq_u32_e32 vcc, 0, v5
	v_or_b32_e32 v55, v6, v4
	v_and_b32_e32 v4, 0x80, v3
	v_cndmask_b32_e32 v7, 0, v240, vcc
	v_lshlrev_b32_e32 v5, 25, v5
	v_cmp_eq_u32_e32 vcc, 0, v4
	v_or_b32_e32 v54, v7, v5
	v_and_b32_e32 v5, 64, v3
	v_cndmask_b32_e32 v6, 0, v240, vcc
	v_lshlrev_b32_e32 v4, 24, v4
	v_cmp_eq_u32_e32 vcc, 0, v5
	v_or_b32_e32 v71, v6, v4
	v_and_b32_e32 v4, 0x20000, v2
	v_cndmask_b32_e32 v7, 0, v240, vcc
	v_lshlrev_b32_e32 v5, 25, v5
	v_cmp_eq_u32_e32 vcc, 0, v4
	v_or_b32_e32 v70, v7, v5
	v_and_b32_e32 v5, 0x10000, v2
	v_cndmask_b32_e32 v6, 0, v240, vcc
	v_lshlrev_b32_e32 v4, 14, v4
	v_cmp_eq_u32_e32 vcc, 0, v5
	v_or_b32_e32 v57, v6, v4
	v_and_b32_e32 v4, 0x20000, v3
	v_cndmask_b32_e32 v7, 0, v240, vcc
	v_lshlrev_b32_e32 v5, 15, v5
	v_cmp_eq_u32_e32 vcc, 0, v4
	v_or_b32_e32 v56, v7, v5
	v_and_b32_e32 v5, 0x10000, v3
	v_cndmask_b32_e32 v6, 0, v240, vcc
	v_lshlrev_b32_e32 v4, 14, v4
	v_cmp_eq_u32_e32 vcc, 0, v5
	v_or_b32_e32 v73, v6, v4
	v_and_b32_e32 v4, 0x80000, v2
	v_cndmask_b32_e32 v7, 0, v240, vcc
	v_lshlrev_b32_e32 v5, 15, v5
	v_cmp_eq_u32_e32 vcc, 0, v4
	v_or_b32_e32 v72, v7, v5
	v_and_b32_e32 v5, 0x40000, v2
	v_cndmask_b32_e32 v6, 0, v240, vcc
	v_lshlrev_b32_e32 v4, 12, v4
	v_cmp_eq_u32_e32 vcc, 0, v5
	v_or_b32_e32 v59, v6, v4
	v_and_b32_e32 v4, 0x80000, v3
	v_cndmask_b32_e32 v7, 0, v240, vcc
	v_lshlrev_b32_e32 v5, 13, v5
	v_cmp_eq_u32_e32 vcc, 0, v4
	v_or_b32_e32 v58, v7, v5
	v_and_b32_e32 v5, 0x40000, v3
	v_cndmask_b32_e32 v6, 0, v240, vcc
	v_lshlrev_b32_e32 v4, 12, v4
	v_cmp_eq_u32_e32 vcc, 0, v5
	v_or_b32_e32 v75, v6, v4
	v_and_b32_e32 v4, 0x200000, v2
	v_cndmask_b32_e32 v7, 0, v240, vcc
	v_lshlrev_b32_e32 v5, 13, v5
	v_cmp_eq_u32_e32 vcc, 0, v4
	v_or_b32_e32 v74, v7, v5
	v_and_b32_e32 v5, 0x100000, v2
	v_cndmask_b32_e32 v6, 0, v240, vcc
	v_lshlrev_b32_e32 v4, 10, v4
	v_cmp_eq_u32_e32 vcc, 0, v5
	v_or_b32_e32 v61, v6, v4
	v_and_b32_e32 v4, 0x200000, v3
	v_cndmask_b32_e32 v7, 0, v240, vcc
	v_lshlrev_b32_e32 v5, 11, v5
	v_cmp_eq_u32_e32 vcc, 0, v4
	v_or_b32_e32 v60, v7, v5
	v_and_b32_e32 v5, 0x100000, v3
	v_cndmask_b32_e32 v6, 0, v240, vcc
	v_lshlrev_b32_e32 v4, 10, v4
	v_cmp_eq_u32_e32 vcc, 0, v5
	v_or_b32_e32 v77, v6, v4
	v_and_b32_e32 v4, 0x800000, v2
	v_cndmask_b32_e32 v7, 0, v240, vcc
	v_lshlrev_b32_e32 v5, 11, v5
	v_and_b32_e32 v2, 0x400000, v2
	v_cmp_eq_u32_e32 vcc, 0, v4
	v_or_b32_e32 v76, v7, v5
	v_lshlrev_b32_e32 v4, 8, v4
	v_cndmask_b32_e32 v5, 0, v240, vcc
	v_cmp_eq_u32_e32 vcc, 0, v2
	v_lshlrev_b32_e32 v2, 9, v2
	v_or_b32_e32 v63, v5, v4
	v_cndmask_b32_e32 v6, 0, v240, vcc
	v_or_b32_e32 v62, v6, v2
	v_and_b32_e32 v14, 0x800000, v3
	v_and_b32_e32 v15, 0x400000, v3
	ds_read_b128 v[2:5], v0 offset:18432
	ds_read_b128 v[6:9], v0 offset:18464
	ds_read_b128 v[10:13], v0 offset:23040
	ds_read_b128 v[144:147], v0 offset:23072
	ds_read_b128 v[148:151], v0 offset:18496
	ds_read_b128 v[152:155], v0 offset:18528
	ds_read_b128 v[158:161], v0 offset:23104
	ds_read_b128 v[162:165], v0 offset:23136
	v_cmp_eq_u32_e32 vcc, 0, v14
	v_lshlrev_b32_e32 v0, 8, v14
	v_lshlrev_b32_e32 v14, 9, v15
	v_cndmask_b32_e32 v78, 0, v240, vcc
	v_cmp_eq_u32_e32 vcc, 0, v15
	v_or_b32_e32 v79, v78, v0
	s_nop 0
	v_cndmask_b32_e32 v157, 0, v240, vcc
	v_or_b32_e32 v78, v157, v14
	s_setprio 1
	s_waitcnt lgkmcnt(7)
	v_mfma_f32_32x32x16_bf16 v[48:63], v[2:5], v[80:83], v[48:63]
	s_waitcnt lgkmcnt(5)
	v_mfma_f32_32x32x16_bf16 v[64:79], v[10:13], v[80:83], v[64:79]
	v_mfma_f32_32x32x16_bf16 v[48:63], v[6:9], v[84:87], v[48:63]
	s_waitcnt lgkmcnt(4)
	v_mfma_f32_32x32x16_bf16 v[64:79], v[144:147], v[84:87], v[64:79]
	s_waitcnt lgkmcnt(3)
	v_mfma_f32_32x32x16_bf16 v[48:63], v[148:151], v[92:95], v[48:63]
	s_waitcnt lgkmcnt(1)
	v_mfma_f32_32x32x16_bf16 v[64:79], v[158:161], v[92:95], v[64:79]
	v_mfma_f32_32x32x16_bf16 v[48:63], v[152:155], v[96:99], v[48:63]
	s_waitcnt lgkmcnt(0)
	v_mfma_f32_32x32x16_bf16 v[64:79], v[162:165], v[96:99], v[64:79]
	s_setprio 0
	s_nop 8
	v_max_f32_e32 v0, v49, v49
	v_max_f32_e32 v2, v48, v48
	v_max_f32_e32 v0, v2, v0
	v_max3_f32 v2, v64, v65, v66
	v_max3_f32 v0, v0, v50, v51
	v_max3_f32 v2, v2, v67, v68
	v_max3_f32 v0, v0, v52, v53
	v_max3_f32 v2, v2, v69, v70
	v_max3_f32 v0, v0, v54, v55
	v_max3_f32 v2, v2, v71, v72
	v_max3_f32 v0, v0, v56, v57
	v_max3_f32 v2, v2, v73, v74
	v_max3_f32 v0, v0, v58, v59
	v_max3_f32 v2, v2, v75, v76
	v_max3_f32 v0, v0, v60, v61
	v_max3_f32 v2, v2, v77, v78
	v_max3_f32 v0, v0, v62, v2
	v_max3_f32 v0, v0, v63, v79
	ds_bpermute_b32 v2, v156, v0
	s_waitcnt lgkmcnt(0)
	v_max3_f32 v0, v131, v0, v2
	v_cmp_eq_f32_e32 vcc, v0, v131
	s_cmp_eq_u64 vcc, exec
	s_cbranch_scc1 .LBB0_767
; __device__ __forceinline__ void softmax_step(f32x16& p0, f32x16& p1, float& m, float& l, f32x16& o0, f32x16& o1) {
;     ...
;     if (!__all(mn == m)) {
;         const float alpha = __builtin_amdgcn_exp2f(m - mn); m = mn; l *= alpha;
; #pragma unroll
;         for (int r = 0; r < 16; ++r) { o0[r] *= alpha; o1[r] *= alpha; }
	v_sub_f32_e32 v2, v131, v0
	v_exp_f32_e32 v2, v2
	v_mov_b32_e32 v131, v0
	v_mul_f32_e32 v129, v129, v2
	v_pk_mul_f32 v[46:47], v[46:47], v[2:3] op_sel_hi:[1,0]
	v_pk_mul_f32 v[44:45], v[44:45], v[2:3] op_sel_hi:[1,0]
	v_pk_mul_f32 v[42:43], v[42:43], v[2:3] op_sel_hi:[1,0]
	v_pk_mul_f32 v[40:41], v[40:41], v[2:3] op_sel_hi:[1,0]
	v_pk_mul_f32 v[38:39], v[38:39], v[2:3] op_sel_hi:[1,0]
	v_pk_mul_f32 v[36:37], v[36:37], v[2:3] op_sel_hi:[1,0]
	v_pk_mul_f32 v[34:35], v[34:35], v[2:3] op_sel_hi:[1,0]
	v_pk_mul_f32 v[32:33], v[32:33], v[2:3] op_sel_hi:[1,0]
	v_pk_mul_f32 v[30:31], v[30:31], v[2:3] op_sel_hi:[1,0]
	v_pk_mul_f32 v[28:29], v[28:29], v[2:3] op_sel_hi:[1,0]
	v_pk_mul_f32 v[26:27], v[26:27], v[2:3] op_sel_hi:[1,0]
	v_pk_mul_f32 v[24:25], v[24:25], v[2:3] op_sel_hi:[1,0]
	v_pk_mul_f32 v[22:23], v[22:23], v[2:3] op_sel_hi:[1,0]
	v_pk_mul_f32 v[20:21], v[20:21], v[2:3] op_sel_hi:[1,0]
	v_pk_mul_f32 v[18:19], v[18:19], v[2:3] op_sel_hi:[1,0]
	v_pk_mul_f32 v[16:17], v[16:17], v[2:3] op_sel_hi:[1,0]

; __device__ __forceinline__ void b_mask_init(f32x16& p0, f32x16& p1, unsigned long long mw, int hi, float ref) {
;     const int n0 = (int)~((unsigned)mw >> (8 * hi)), n1 = (int)~((unsigned)(mw >> 32) >> (8 * hi)); const int nr = __float_as_int(-ref);
; #pragma unroll
;     for (int r = 0; r < 16; ++r) { const int bit = 16 * (r >> 3) + (r & 7);
;         const int e0 = __builtin_amdgcn_sbfe(n0, bit, 1), e1 = __builtin_amdgcn_sbfe(n1, bit, 1);
;         p0[r] = __int_as_float((e0 & (int)0xFF800000) | (~e0 & nr)); p1[r] = __int_as_float((e1 & (int)0xFF800000) | (~e1 & nr)); }
; }
; __device__ __forceinline__ float exp_tile(f32x16& p0, f32x16& p1) {
;     float sacc = 0.f;
; #pragma unroll
;     for (int r = 0; r < 16; ++r) { p0[r] = __builtin_amdgcn_exp2f(p0[r]); p1[r] = __builtin_amdgcn_exp2f(p1[r]);
;     ...
;         p0[r] = __builtin_amdgcn_exp2f(__builtin_amdgcn_logf(p0[r])); p1[r] = __builtin_amdgcn_exp2f(__builtin_amdgcn_logf(p1[r]));
;     ...
;         sacc += p0[r] + p1[r]; }
;     return sacc;
; }
.LBB0_778:
	s_bitcmp1_b32 s18, 0
	s_cselect_b32 s22, 0x9000, 0
	s_add_i32 s22, s22, 0
	s_cmp_gt_i32 s21, s17
	v_add3_u32 v7, s22, v135, v157
	v_add3_u32 v6, s22, v158, v157
	s_cbranch_scc1 .LBB0_784
	v_lshrrev_b32_e32 v0, v134, v2
	v_lshrrev_b32_e32 v2, v134, v3
	v_bfe_i32 v17, v0, 23, 1
	v_bfe_i32 v18, v0, 22, 1
	ds_read_b128 v[8:11], v7 offset:4608
	ds_read_b128 v[12:15], v7
	ds_read_b128 v[160:163], v7 offset:32
	ds_read_b128 v[164:167], v7 offset:4640
	ds_read_b128 v[168:171], v7 offset:64
	ds_read_b128 v[172:175], v7 offset:4672
	ds_read_b128 v[176:179], v7 offset:96
	ds_read_b128 v[180:183], v7 offset:4704
	v_bfi_b32 v79, v17, v16, v240
	v_bfe_i32 v19, v0, 21, 1
	v_bfi_b32 v78, v18, v16, v240
	v_bfe_i32 v20, v0, 20, 1
	v_bfi_b32 v77, v19, v16, v240
	v_bfe_i32 v21, v0, 19, 1
	v_bfi_b32 v76, v20, v16, v240
	v_bfe_i32 v22, v0, 18, 1
	v_bfi_b32 v75, v21, v16, v240
	v_bfe_i32 v23, v0, 17, 1
	v_bfi_b32 v74, v22, v16, v240
	v_bfe_i32 v24, v0, 16, 1
	v_bfi_b32 v73, v23, v16, v240
	v_bfe_i32 v17, v0, 7, 1
	v_bfi_b32 v72, v24, v16, v240
	v_bfe_i32 v18, v0, 6, 1
	v_bfi_b32 v71, v17, v16, v240
	v_bfe_i32 v19, v0, 5, 1
	v_bfi_b32 v70, v18, v16, v240
	v_bfe_i32 v20, v0, 4, 1
	v_bfi_b32 v69, v19, v16, v240
	v_bfe_i32 v21, v0, 3, 1
	v_bfi_b32 v68, v20, v16, v240
	v_bfe_i32 v22, v0, 2, 1
	v_bfi_b32 v67, v21, v16, v240
	v_bfe_i32 v23, v0, 1, 1
	v_bfe_i32 v24, v0, 0, 1
	v_bfi_b32 v66, v22, v16, v240
	v_bfi_b32 v65, v23, v16, v240
	v_bfe_i32 v17, v2, 23, 1
	v_bfi_b32 v64, v24, v16, v240
	v_bfe_i32 v18, v2, 22, 1
	v_bfi_b32 v95, v17, v16, v240
	v_bfe_i32 v19, v2, 21, 1
	v_bfi_b32 v94, v18, v16, v240
	v_bfe_i32 v20, v2, 20, 1
	v_bfi_b32 v93, v19, v16, v240
	v_bfe_i32 v21, v2, 19, 1
	v_bfi_b32 v92, v20, v16, v240
	v_bfe_i32 v22, v2, 18, 1
	v_bfi_b32 v91, v21, v16, v240
	v_bfe_i32 v23, v2, 17, 1
	v_bfi_b32 v90, v22, v16, v240
	v_bfe_i32 v24, v2, 16, 1
	v_bfi_b32 v89, v23, v16, v240
	v_bfe_i32 v17, v2, 7, 1
	v_bfi_b32 v88, v24, v16, v240
	v_bfe_i32 v18, v2, 6, 1
	v_bfi_b32 v87, v17, v16, v240
	v_bfe_i32 v19, v2, 5, 1
	v_bfi_b32 v86, v18, v16, v240
	v_bfe_i32 v20, v2, 4, 1
	v_bfi_b32 v85, v19, v16, v240
	v_bfe_i32 v21, v2, 3, 1
	v_bfi_b32 v84, v20, v16, v240
	v_bfe_i32 v22, v2, 2, 1
	v_bfi_b32 v83, v21, v16, v240
	v_bfe_i32 v23, v2, 1, 1
	v_bfi_b32 v82, v22, v16, v240
	v_bfe_i32 v24, v2, 0, 1
	v_bfi_b32 v81, v23, v16, v240
	v_bfi_b32 v80, v24, v16, v240
	s_setprio 1
	s_waitcnt lgkmcnt(6)
	v_mfma_f32_32x32x16_bf16 v[64:79], v[12:15], v[96:99], v[64:79]
	v_mfma_f32_32x32x16_bf16 v[80:95], v[8:11], v[96:99], v[80:95]
	s_waitcnt lgkmcnt(5)
	v_mfma_f32_32x32x16_bf16 v[64:79], v[160:163], v[100:103], v[64:79]
	s_waitcnt lgkmcnt(4)
	v_mfma_f32_32x32x16_bf16 v[80:95], v[164:167], v[100:103], v[80:95]
	s_waitcnt lgkmcnt(3)
	v_mfma_f32_32x32x16_bf16 v[64:79], v[168:171], v[108:111], v[64:79]
	s_waitcnt lgkmcnt(2)
	v_mfma_f32_32x32x16_bf16 v[80:95], v[172:175], v[108:111], v[80:95]
	s_waitcnt lgkmcnt(1)
	v_mfma_f32_32x32x16_bf16 v[64:79], v[176:179], v[112:115], v[64:79]
	s_waitcnt lgkmcnt(0)
	v_mfma_f32_32x32x16_bf16 v[80:95], v[180:183], v[112:115], v[80:95]
	s_setprio 0
	s_nop 8
	v_exp_f32_e32 v147, v64
	s_nop 0
	v_exp_f32_e32 v80, v80
	v_exp_f32_e32 v2, v65
	v_exp_f32_e32 v0, v81
	v_exp_f32_e32 v81, v82
	v_add_f32_e32 v3, v147, v80
	v_exp_f32_e32 v10, v67
	v_pk_add_f32 v[8:9], v[2:3], v[0:1]
	v_exp_f32_e32 v3, v66
	v_pk_add_f32 v[160:161], v[8:9], v[8:9] op_sel_hi:[0,1]
	v_exp_f32_e32 v160, v83
	v_exp_f32_e32 v159, v84
	v_add_f32_e32 v11, v3, v81
	v_exp_f32_e32 v12, v69
	v_pk_add_f32 v[8:9], v[10:11], v[160:161]
	v_exp_f32_e32 v11, v68
	v_pk_add_f32 v[82:83], v[8:9], v[8:9] op_sel_hi:[0,1]
	v_exp_f32_e32 v82, v85
	v_exp_f32_e32 v14, v71
	v_add_f32_e32 v13, v11, v159
	v_exp_f32_e32 v72, v72
	v_pk_add_f32 v[8:9], v[12:13], v[82:83]
	v_exp_f32_e32 v13, v70
	v_pk_add_f32 v[84:85], v[8:9], v[8:9] op_sel_hi:[0,1]
	v_exp_f32_e32 v83, v86
	v_exp_f32_e32 v84, v87
	v_exp_f32_e32 v161, v88
	v_exp_f32_e32 v64, v73
	v_add_f32_e32 v15, v13, v83
	v_pk_add_f32 v[8:9], v[14:15], v[84:85]
	v_add_f32_e32 v65, v72, v161
	v_pk_add_f32 v[162:163], v[8:9], v[8:9] op_sel_hi:[0,1]
	v_exp_f32_e32 v162, v89
	v_exp_f32_e32 v66, v75
	v_exp_f32_e32 v68, v77
	v_exp_f32_e32 v70, v79
	v_pk_add_f32 v[8:9], v[64:65], v[162:163]
	v_exp_f32_e32 v65, v74
	v_pk_add_f32 v[164:165], v[8:9], v[8:9] op_sel_hi:[0,1]
	v_exp_f32_e32 v163, v90
	v_exp_f32_e32 v164, v91
	v_cvt_pk_bf16_f32 v64, v72, v64
	v_cvt_pk_bf16_f32 v81, v81, v160
	v_add_f32_e32 v67, v65, v163
	v_pk_add_f32 v[8:9], v[66:67], v[164:165]
	v_exp_f32_e32 v67, v76
	v_pk_add_f32 v[166:167], v[8:9], v[8:9] op_sel_hi:[0,1]
	v_exp_f32_e32 v165, v92
	v_exp_f32_e32 v166, v93
	v_cvt_pk_bf16_f32 v65, v65, v66
	v_cvt_pk_bf16_f32 v66, v67, v68
	v_add_f32_e32 v69, v67, v165
	v_pk_add_f32 v[8:9], v[68:69], v[166:167]
	v_exp_f32_e32 v69, v78
	v_pk_add_f32 v[168:169], v[8:9], v[8:9] op_sel_hi:[0,1]
	v_exp_f32_e32 v167, v94
	v_exp_f32_e32 v168, v95
	v_cvt_pk_bf16_f32 v67, v69, v70
	v_cvt_pk_bf16_f32 v83, v83, v84
	v_add_f32_e32 v71, v69, v167
	v_pk_add_f32 v[8:9], v[70:71], v[168:169]
	v_cvt_pk_bf16_f32 v92, v161, v162
	v_add_f32_e32 v8, v8, v9
	v_cvt_pk_bf16_f32 v9, v3, v10
	v_cvt_pk_bf16_f32 v10, v11, v12
	v_cvt_pk_bf16_f32 v11, v13, v14
	ds_read_b128 v[12:15], v6 offset:13824
	ds_read_b128 v[68:71], v6 offset:9216
	ds_read_b128 v[72:75], v6 offset:9248
	ds_read_b128 v[76:79], v6 offset:13856
	ds_read_b128 v[84:87], v6 offset:9280
	ds_read_b128 v[88:91], v6 offset:13888
	v_cvt_pk_bf16_f32 v93, v163, v164
	v_cvt_pk_bf16_f32 v94, v165, v166
	v_cvt_pk_bf16_f32 v95, v167, v168
	ds_read_b128 v[160:163], v6 offset:9312
	ds_read_b128 v[164:167], v6 offset:13920
	v_add_f32_e32 v145, v145, v8
	v_cvt_pk_bf16_f32 v8, v147, v2
	v_cvt_pk_bf16_f32 v80, v80, v0
	v_cvt_pk_bf16_f32 v82, v159, v82
	s_setprio 1
	s_waitcnt lgkmcnt(6)
	v_mfma_f32_32x32x16_bf16 v[48:63], v[68:71], v[8:11], v[48:63]
	v_mfma_f32_32x32x16_bf16 v[32:47], v[12:15], v[8:11], v[32:47]
	s_waitcnt lgkmcnt(5)
	v_mfma_f32_32x32x16_bf16 v[48:63], v[72:75], v[64:67], v[48:63]
	s_waitcnt lgkmcnt(4)
	v_mfma_f32_32x32x16_bf16 v[32:47], v[76:79], v[64:67], v[32:47]
	s_waitcnt lgkmcnt(3)
	v_mfma_f32_32x32x16_bf16 v[48:63], v[84:87], v[80:83], v[48:63]
	s_waitcnt lgkmcnt(2)
	v_mfma_f32_32x32x16_bf16 v[32:47], v[88:91], v[80:83], v[32:47]
	s_waitcnt lgkmcnt(1)
	v_mfma_f32_32x32x16_bf16 v[48:63], v[160:163], v[92:95], v[48:63]
	s_waitcnt lgkmcnt(0)
	v_mfma_f32_32x32x16_bf16 v[32:47], v[164:167], v[92:95], v[32:47]
	s_setprio 0
	s_cmp_ge_i32 s21, s17
	s_cbranch_scc0 .LBB0_785

; __device__ __forceinline__ void b_mask_init(f32x16& p0, f32x16& p1, unsigned long long mw, int hi, float ref) {
;     const int n0 = (int)~((unsigned)mw >> (8 * hi)), n1 = (int)~((unsigned)(mw >> 32) >> (8 * hi)); const int nr = __float_as_int(-ref);
; #pragma unroll
;     for (int r = 0; r < 16; ++r) { const int bit = 16 * (r >> 3) + (r & 7);
;         const int e0 = __builtin_amdgcn_sbfe(n0, bit, 1), e1 = __builtin_amdgcn_sbfe(n1, bit, 1);
;         p0[r] = __int_as_float((e0 & (int)0xFF800000) | (~e0 & nr)); p1[r] = __int_as_float((e1 & (int)0xFF800000) | (~e1 & nr)); }
; }
; __device__ __forceinline__ float exp_tile(f32x16& p0, f32x16& p1) {
;     float sacc = 0.f;
; #pragma unroll
;     for (int r = 0; r < 16; ++r) { p0[r] = __builtin_amdgcn_exp2f(p0[r]); p1[r] = __builtin_amdgcn_exp2f(p1[r]);
;     ...
;         p0[r] = __builtin_amdgcn_exp2f(__builtin_amdgcn_logf(p0[r])); p1[r] = __builtin_amdgcn_exp2f(__builtin_amdgcn_logf(p1[r]));
;     ...
;         sacc += p0[r] + p1[r]; }
;     return sacc;
; }
.LBB0_785:
	v_lshrrev_b32_e32 v0, v134, v4
	v_bfe_i32 v17, v0, 23, 1
	v_bfe_i32 v18, v0, 22, 1
	v_lshrrev_b32_e32 v2, v134, v5
	v_bfi_b32 v79, v17, v16, v240
	v_bfe_i32 v19, v0, 21, 1
	v_bfi_b32 v78, v18, v16, v240
	v_bfe_i32 v20, v0, 20, 1
	v_bfi_b32 v77, v19, v16, v240
	v_bfe_i32 v21, v0, 19, 1
	v_bfi_b32 v76, v20, v16, v240
	v_bfe_i32 v22, v0, 18, 1
	v_bfi_b32 v75, v21, v16, v240
	v_bfe_i32 v23, v0, 17, 1
	v_bfi_b32 v74, v22, v16, v240
	v_bfe_i32 v24, v0, 16, 1
	v_bfi_b32 v73, v23, v16, v240
	v_bfe_i32 v17, v0, 7, 1
	v_bfi_b32 v72, v24, v16, v240
	v_bfe_i32 v18, v0, 6, 1
	v_bfi_b32 v71, v17, v16, v240
	v_bfe_i32 v19, v0, 5, 1
	v_bfi_b32 v70, v18, v16, v240
	v_bfe_i32 v20, v0, 4, 1
	v_bfi_b32 v69, v19, v16, v240
	v_bfe_i32 v21, v0, 3, 1
	v_bfi_b32 v68, v20, v16, v240
	v_bfe_i32 v22, v0, 2, 1
	v_bfi_b32 v67, v21, v16, v240
	v_bfe_i32 v23, v0, 1, 1
	v_bfe_i32 v24, v0, 0, 1
	v_bfi_b32 v66, v22, v16, v240
	v_bfi_b32 v65, v23, v16, v240
	v_bfe_i32 v17, v2, 23, 1
	v_bfi_b32 v64, v24, v16, v240
	v_bfe_i32 v18, v2, 22, 1
	v_bfi_b32 v95, v17, v16, v240
	v_bfe_i32 v19, v2, 21, 1
	v_bfi_b32 v94, v18, v16, v240
	v_bfe_i32 v20, v2, 20, 1
	v_bfi_b32 v93, v19, v16, v240
	v_bfe_i32 v21, v2, 19, 1
	v_bfi_b32 v92, v20, v16, v240
	v_bfe_i32 v22, v2, 18, 1
	v_bfi_b32 v91, v21, v16, v240
	v_bfe_i32 v23, v2, 17, 1
	v_bfi_b32 v90, v22, v16, v240
	v_bfe_i32 v24, v2, 16, 1
	v_bfi_b32 v89, v23, v16, v240
	v_bfe_i32 v17, v2, 7, 1
	v_bfi_b32 v88, v24, v16, v240
	v_bfe_i32 v18, v2, 6, 1
	v_bfi_b32 v87, v17, v16, v240
	v_bfe_i32 v19, v2, 5, 1
	v_bfi_b32 v86, v18, v16, v240
	v_bfe_i32 v20, v2, 4, 1
	v_bfi_b32 v85, v19, v16, v240
	v_bfe_i32 v21, v2, 3, 1
	v_bfi_b32 v84, v20, v16, v240
	v_bfe_i32 v22, v2, 2, 1
	v_bfi_b32 v83, v21, v16, v240
	v_bfe_i32 v23, v2, 1, 1
	v_bfi_b32 v82, v22, v16, v240
	v_bfe_i32 v24, v2, 0, 1
	ds_read_b128 v[2:5], v7 offset:23040
	ds_read_b128 v[8:11], v7 offset:18432
	ds_read_b128 v[12:15], v7 offset:18464
	ds_read_b128 v[160:163], v7 offset:23072
	ds_read_b128 v[164:167], v7 offset:18496
	ds_read_b128 v[168:171], v7 offset:23104
	ds_read_b128 v[172:175], v7 offset:18528
	ds_read_b128 v[176:179], v7 offset:23136
	v_bfi_b32 v81, v23, v16, v240
	v_bfi_b32 v80, v24, v16, v240
	s_setprio 1
	s_waitcnt lgkmcnt(6)
	v_mfma_f32_32x32x16_bf16 v[64:79], v[8:11], v[96:99], v[64:79]
	v_mfma_f32_32x32x16_bf16 v[80:95], v[2:5], v[96:99], v[80:95]
	s_waitcnt lgkmcnt(5)
	v_mfma_f32_32x32x16_bf16 v[64:79], v[12:15], v[100:103], v[64:79]
	s_waitcnt lgkmcnt(4)
	v_mfma_f32_32x32x16_bf16 v[80:95], v[160:163], v[100:103], v[80:95]
	s_waitcnt lgkmcnt(3)
	v_mfma_f32_32x32x16_bf16 v[64:79], v[164:167], v[108:111], v[64:79]
	s_waitcnt lgkmcnt(2)
	v_mfma_f32_32x32x16_bf16 v[80:95], v[168:171], v[108:111], v[80:95]
	s_waitcnt lgkmcnt(1)
	v_mfma_f32_32x32x16_bf16 v[64:79], v[172:175], v[112:115], v[64:79]
	s_waitcnt lgkmcnt(0)
	v_mfma_f32_32x32x16_bf16 v[80:95], v[176:179], v[112:115], v[80:95]
	s_setprio 0
	s_nop 8
	v_exp_f32_e32 v7, v64
	s_nop 0
	v_exp_f32_e32 v147, v80
	v_exp_f32_e32 v2, v65
	v_exp_f32_e32 v0, v81
	v_exp_f32_e32 v159, v82
	v_add_f32_e32 v3, v7, v147
	v_exp_f32_e32 v88, v88
	v_pk_add_f32 v[4:5], v[2:3], v[0:1]
	v_exp_f32_e32 v3, v66
	v_pk_add_f32 v[80:81], v[4:5], v[4:5] op_sel_hi:[0,1]
	v_exp_f32_e32 v4, v67
	v_exp_f32_e32 v80, v83
	v_add_f32_e32 v5, v3, v159
	v_cvt_pk_bf16_f32 v2, v7, v2
	v_cvt_pk_bf16_f32 v3, v3, v4
	v_pk_add_f32 v[8:9], v[4:5], v[80:81]
	v_exp_f32_e32 v5, v68
	v_pk_add_f32 v[82:83], v[8:9], v[8:9] op_sel_hi:[0,1]
	v_exp_f32_e32 v81, v84
	v_exp_f32_e32 v8, v69
	v_exp_f32_e32 v82, v85
	v_add_f32_e32 v9, v5, v81
	v_cvt_pk_bf16_f32 v4, v5, v8
	v_pk_add_f32 v[10:11], v[8:9], v[82:83]
	v_exp_f32_e32 v9, v70
	v_pk_add_f32 v[84:85], v[10:11], v[10:11] op_sel_hi:[0,1]
	v_exp_f32_e32 v83, v86
	v_exp_f32_e32 v10, v71
	v_exp_f32_e32 v84, v87
	v_exp_f32_e32 v70, v72
	v_add_f32_e32 v11, v9, v83
	v_cvt_pk_bf16_f32 v5, v9, v10
	v_pk_add_f32 v[12:13], v[10:11], v[84:85]
	s_nop 0
	v_pk_add_f32 v[160:161], v[12:13], v[12:13] op_sel_hi:[0,1]
	v_exp_f32_e32 v12, v73
	v_exp_f32_e32 v160, v89
	v_add_f32_e32 v13, v70, v88
	v_exp_f32_e32 v89, v90
	v_pk_add_f32 v[14:15], v[12:13], v[160:161]
	s_nop 0
	v_pk_add_f32 v[162:163], v[14:15], v[14:15] op_sel_hi:[0,1]
	v_exp_f32_e32 v13, v74
	v_exp_f32_e32 v14, v75
	v_exp_f32_e32 v162, v91
	v_exp_f32_e32 v161, v92
	v_add_f32_e32 v15, v13, v89
	v_cvt_pk_bf16_f32 v12, v70, v12
	v_pk_add_f32 v[64:65], v[14:15], v[162:163]
	v_exp_f32_e32 v15, v76
	v_pk_add_f32 v[90:91], v[64:65], v[64:65] op_sel_hi:[0,1]
	v_exp_f32_e32 v64, v77
	v_exp_f32_e32 v90, v93
	v_add_f32_e32 v65, v15, v161
	v_cvt_pk_bf16_f32 v13, v13, v14
	v_cvt_pk_bf16_f32 v14, v15, v64
	v_pk_add_f32 v[66:67], v[64:65], v[90:91]
	v_exp_f32_e32 v65, v78
	v_pk_add_f32 v[92:93], v[66:67], v[66:67] op_sel_hi:[0,1]
	v_exp_f32_e32 v91, v94
	v_exp_f32_e32 v66, v79
	v_exp_f32_e32 v92, v95
	v_cvt_pk_bf16_f32 v77, v159, v80
	v_add_f32_e32 v67, v65, v91
	v_cvt_pk_bf16_f32 v15, v65, v66
	v_pk_add_f32 v[68:69], v[66:67], v[92:93]
	v_cvt_pk_bf16_f32 v78, v81, v82
	v_add_f32_e32 v11, v68, v69
	v_add_f32_e32 v145, v145, v11
	ds_read_b128 v[8:11], v6 offset:32256
	ds_read_b128 v[64:67], v6 offset:27648
	ds_read_b128 v[68:71], v6 offset:27680
	ds_read_b128 v[72:75], v6 offset:32288
	v_cvt_pk_bf16_f32 v79, v83, v84
	ds_read_b128 v[80:83], v6 offset:27712
	ds_read_b128 v[84:87], v6 offset:32320
	v_cvt_pk_bf16_f32 v88, v88, v160
	v_cvt_pk_bf16_f32 v89, v89, v162
	v_cvt_pk_bf16_f32 v90, v161, v90
	v_cvt_pk_bf16_f32 v91, v91, v92
	ds_read_b128 v[92:95], v6 offset:27744
	ds_read_b128 v[160:163], v6 offset:32352
	v_cvt_pk_bf16_f32 v76, v147, v0
	s_setprio 1
	s_waitcnt lgkmcnt(6)
	v_mfma_f32_32x32x16_bf16 v[48:63], v[64:67], v[2:5], v[48:63]
	v_mfma_f32_32x32x16_bf16 v[32:47], v[8:11], v[2:5], v[32:47]
	s_waitcnt lgkmcnt(5)
	v_mfma_f32_32x32x16_bf16 v[48:63], v[68:71], v[12:15], v[48:63]
	s_waitcnt lgkmcnt(4)
	v_mfma_f32_32x32x16_bf16 v[32:47], v[72:75], v[12:15], v[32:47]
	s_waitcnt lgkmcnt(3)
	v_mfma_f32_32x32x16_bf16 v[48:63], v[80:83], v[76:79], v[48:63]
	s_waitcnt lgkmcnt(2)
	v_mfma_f32_32x32x16_bf16 v[32:47], v[84:87], v[76:79], v[32:47]
	s_waitcnt lgkmcnt(1)
	v_mfma_f32_32x32x16_bf16 v[48:63], v[92:95], v[88:91], v[48:63]
	s_waitcnt lgkmcnt(0)
	v_mfma_f32_32x32x16_bf16 v[32:47], v[160:163], v[88:91], v[32:47]
	s_setprio 0
	s_andn2_b64 vcc, exec, s[10:11]
	s_cbranch_vccz .LBB0_781
	s_branch .LBB0_782

; __device__ __forceinline__ void attnC_blk(const bf16* Q, const bf16* K, const bf16* Vt, bf16* O, LAS unsigned char* lds, int vcu, int G, int tid) {
;     ...
;                 f32x16 p0, p1; qk_lds(p0, p1, buf, qr, r32, hi);
;                 const int kb = t * 64 + 8 * hi;
;                 const bool diag = (t == t_me);
;                 float lk[32], lb[32];
; #pragma unroll
;                 for (int e = 0; e < 32; ++e) { const int r = e & 15, half = e >> 4; const float z = half ? p1[r] : p0[r];
;                     const float sp = __builtin_amdgcn_logf(1.f + __builtin_amdgcn_exp2f(fminf(z, 80.f)));
;                     lk[e] = -sp; lb[e] = z - sp; }
.LBB0_795:
	s_and_b32 s92, s90, 1
	s_mul_i32 s80, s92, 0x4800
	v_cmp_lt_i32_e32 vcc, s89, v0
	s_add_i32 s93, s80, 0
	s_or_b64 s[80:81], vcc, s[78:79]
	s_and_b64 vcc, exec, s[80:81]
	s_cbranch_vccnz .LBB0_798
	v_add3_u32 v0, s93, v107, v122
	ds_read_b128 v[2:5], v0
	ds_read_b128 v[6:9], v0 offset:32
	ds_read_b128 v[10:13], v0 offset:4608
	ds_read_b128 v[124:127], v0 offset:4640
	ds_read_b128 v[128:131], v0 offset:64
	ds_read_b128 v[132:135], v0 offset:96
	ds_read_b128 v[136:139], v0 offset:4672
	ds_read_b128 v[140:143], v0 offset:4704
	s_add_i32 s78, s91, s96
	s_setprio 1
	s_waitcnt lgkmcnt(7)
	v_mfma_f32_32x32x16_bf16 v[64:79], v[2:5], v[88:91], 0
	s_waitcnt lgkmcnt(5)
	v_mfma_f32_32x32x16_bf16 v[48:63], v[10:13], v[88:91], 0
	v_mfma_f32_32x32x16_bf16 v[64:79], v[6:9], v[92:95], v[64:79]
	s_waitcnt lgkmcnt(4)
	v_mfma_f32_32x32x16_bf16 v[48:63], v[124:127], v[92:95], v[48:63]
	s_waitcnt lgkmcnt(3)
	v_mfma_f32_32x32x16_bf16 v[64:79], v[128:131], v[96:99], v[64:79]
	s_waitcnt lgkmcnt(1)
	v_mfma_f32_32x32x16_bf16 v[48:63], v[136:139], v[96:99], v[48:63]
	v_mfma_f32_32x32x16_bf16 v[64:79], v[132:135], v[100:103], v[64:79]
	s_waitcnt lgkmcnt(0)
	v_mfma_f32_32x32x16_bf16 v[48:63], v[140:143], v[100:103], v[48:63]
	s_setprio 0
	s_nop 8
	v_max_f32_e32 v0, v64, v64
	v_min_f32_e32 v0, 0x42a00000, v0
	v_max_f32_e32 v2, v65, v65
	v_exp_f32_e32 v0, v0
	v_min_f32_e32 v2, 0x42a00000, v2
	v_exp_f32_e32 v2, v2
	v_max_f32_e32 v4, v67, v67
	v_add_f32_e32 v0, 1.0, v0
	v_log_f32_e32 v124, v0
	v_add_f32_e32 v0, 1.0, v2
	v_log_f32_e32 v115, v0
	v_max_f32_e32 v0, v66, v66
	v_min_f32_e32 v0, 0x42a00000, v0
	v_exp_f32_e32 v3, v0
	v_min_f32_e32 v4, 0x42a00000, v4
	v_max_f32_e32 v5, v68, v68
	v_exp_f32_e32 v4, v4
	v_min_f32_e32 v5, 0x42a00000, v5
	v_exp_f32_e32 v5, v5
	v_add_f32_e32 v3, 1.0, v3
	v_log_f32_e32 v127, v3
	v_add_f32_e32 v3, 1.0, v4
	v_log_f32_e32 v126, v3
	v_add_f32_e32 v3, 1.0, v5
	v_log_f32_e32 v125, v3
	v_max_f32_e32 v3, v69, v69
	v_min_f32_e32 v3, 0x42a00000, v3
	v_max_f32_e32 v7, v70, v70
	v_exp_f32_e32 v6, v3
	v_min_f32_e32 v7, 0x42a00000, v7
	v_max_f32_e32 v8, v71, v71
	v_exp_f32_e32 v7, v7
	v_min_f32_e32 v8, 0x42a00000, v8
	v_exp_f32_e32 v8, v8
	v_add_f32_e32 v6, 1.0, v6
	v_log_f32_e32 v130, v6
	v_add_f32_e32 v6, 1.0, v7
	v_log_f32_e32 v129, v6
	v_add_f32_e32 v6, 1.0, v8
	v_log_f32_e32 v128, v6
	v_max_f32_e32 v6, v72, v72
	v_min_f32_e32 v6, 0x42a00000, v6
	v_max_f32_e32 v10, v73, v73
	v_exp_f32_e32 v9, v6
	v_min_f32_e32 v10, 0x42a00000, v10
	v_max_f32_e32 v11, v74, v74
	v_exp_f32_e32 v10, v10
	v_min_f32_e32 v11, 0x42a00000, v11
	v_exp_f32_e32 v11, v11
	v_add_f32_e32 v9, 1.0, v9
	v_sub_f32_e32 v7, v70, v129
	v_log_f32_e32 v70, v9
	v_add_f32_e32 v9, 1.0, v10
	v_log_f32_e32 v132, v9
	v_add_f32_e32 v9, 1.0, v11
	v_log_f32_e32 v131, v9
	v_max_f32_e32 v9, v75, v75
	v_min_f32_e32 v9, 0x42a00000, v9
	v_max_f32_e32 v13, v76, v76
	v_exp_f32_e32 v12, v9
	v_min_f32_e32 v13, 0x42a00000, v13
	v_max_f32_e32 v14, v77, v77
	v_exp_f32_e32 v13, v13
	v_min_f32_e32 v14, 0x42a00000, v14
	v_exp_f32_e32 v14, v14
	v_add_f32_e32 v12, 1.0, v12
	v_log_f32_e32 v135, v12
	v_add_f32_e32 v12, 1.0, v13
	v_log_f32_e32 v134, v12
	v_add_f32_e32 v12, 1.0, v14
	v_log_f32_e32 v133, v12
	v_max_f32_e32 v12, v78, v78
	v_sub_f32_e32 v2, v64, v124
	v_min_f32_e32 v12, 0x42a00000, v12
	v_max_f32_e32 v64, v79, v79
	v_sub_f32_e32 v0, v65, v115
	v_exp_f32_e32 v15, v12
	v_min_f32_e32 v64, 0x42a00000, v64
	v_max_f32_e32 v65, v48, v48
	v_exp_f32_e32 v64, v64
	v_min_f32_e32 v65, 0x42a00000, v65
	v_exp_f32_e32 v65, v65
	v_add_f32_e32 v15, 1.0, v15
	v_log_f32_e32 v138, v15
	v_add_f32_e32 v15, 1.0, v64
	v_log_f32_e32 v137, v15
	v_add_f32_e32 v15, 1.0, v65
	v_log_f32_e32 v136, v15
	v_max_f32_e32 v15, v49, v49
	v_min_f32_e32 v15, 0x42a00000, v15
	v_sub_f32_e32 v5, v66, v127
	v_exp_f32_e32 v66, v15
	v_sub_f32_e32 v15, v48, v136
	v_sub_f32_e32 v4, v67, v126
	v_max_f32_e32 v67, v51, v51
	v_add_f32_e32 v48, 1.0, v66
	v_max_f32_e32 v66, v50, v50
	v_min_f32_e32 v66, 0x42a00000, v66
	v_exp_f32_e32 v66, v66
	v_min_f32_e32 v67, 0x42a00000, v67
	v_exp_f32_e32 v67, v67
	v_log_f32_e32 v141, v48
	v_add_f32_e32 v48, 1.0, v66
	v_log_f32_e32 v140, v48
	v_add_f32_e32 v48, 1.0, v67
	v_log_f32_e32 v139, v48
	v_max_f32_e32 v48, v52, v52
	v_min_f32_e32 v48, 0x42a00000, v48
	v_exp_f32_e32 v67, v48
	v_sub_f32_e32 v48, v51, v139
	v_max_f32_e32 v51, v53, v53
	v_sub_f32_e32 v66, v49, v141
	v_sub_f32_e32 v49, v50, v140
	v_add_f32_e32 v50, 1.0, v67
	v_min_f32_e32 v51, 0x42a00000, v51
	v_max_f32_e32 v67, v54, v54
	v_exp_f32_e32 v51, v51
	v_min_f32_e32 v67, 0x42a00000, v67
	v_exp_f32_e32 v67, v67
	v_log_f32_e32 v144, v50
	v_add_f32_e32 v50, 1.0, v51
	v_log_f32_e32 v143, v50
	v_add_f32_e32 v50, 1.0, v67
	v_log_f32_e32 v142, v50
	v_max_f32_e32 v50, v55, v55
	v_min_f32_e32 v50, 0x42a00000, v50
	v_exp_f32_e32 v67, v50
	v_sub_f32_e32 v50, v54, v142
	v_max_f32_e32 v54, v56, v56
	v_sub_f32_e32 v51, v53, v143
	v_add_f32_e32 v53, 1.0, v67
	v_min_f32_e32 v54, 0x42a00000, v54
	v_max_f32_e32 v67, v57, v57
	v_exp_f32_e32 v54, v54
	v_min_f32_e32 v67, 0x42a00000, v67
	v_exp_f32_e32 v67, v67
	v_log_f32_e32 v147, v53
	v_add_f32_e32 v53, 1.0, v54
	v_log_f32_e32 v146, v53
	v_add_f32_e32 v53, 1.0, v67
	v_log_f32_e32 v145, v53
	v_max_f32_e32 v53, v58, v58
	v_min_f32_e32 v53, 0x42a00000, v53
	v_exp_f32_e32 v67, v53
	v_sub_f32_e32 v53, v57, v145
	v_max_f32_e32 v57, v59, v59
	v_sub_f32_e32 v54, v56, v146
	v_add_f32_e32 v56, 1.0, v67
	v_min_f32_e32 v57, 0x42a00000, v57
	v_max_f32_e32 v67, v60, v60
	v_exp_f32_e32 v57, v57
	v_min_f32_e32 v67, 0x42a00000, v67
	v_exp_f32_e32 v67, v67
	v_log_f32_e32 v150, v56
	v_add_f32_e32 v56, 1.0, v57
	v_log_f32_e32 v149, v56
	v_add_f32_e32 v56, 1.0, v67
	v_log_f32_e32 v148, v56
	v_max_f32_e32 v56, v61, v61
	v_min_f32_e32 v56, 0x42a00000, v56
	v_exp_f32_e32 v67, v56
	v_sub_f32_e32 v56, v60, v148
	v_max_f32_e32 v60, v62, v62
	v_sub_f32_e32 v57, v59, v149
	v_add_f32_e32 v59, 1.0, v67
	v_min_f32_e32 v60, 0x42a00000, v60
	v_max_f32_e32 v67, v63, v63
	v_exp_f32_e32 v60, v60
	v_min_f32_e32 v67, 0x42a00000, v67
	v_exp_f32_e32 v67, v67
	v_log_f32_e32 v153, v59
	v_add_f32_e32 v59, 1.0, v60
	v_log_f32_e32 v152, v59
	v_add_f32_e32 v59, 1.0, v67
	v_log_f32_e32 v151, v59
	v_sub_f32_e32 v3, v68, v125
	v_sub_f32_e32 v8, v69, v130
	v_sub_f32_e32 v6, v71, v128
	v_sub_f32_e32 v11, v72, v70
	v_sub_f32_e32 v10, v73, v132
	v_sub_f32_e32 v9, v74, v131
	v_sub_f32_e32 v14, v75, v135
	v_sub_f32_e32 v13, v76, v134
	v_sub_f32_e32 v12, v77, v133
	v_sub_f32_e32 v65, v78, v138
	v_sub_f32_e32 v64, v79, v137
	v_sub_f32_e32 v52, v52, v144
	v_sub_f32_e32 v55, v55, v147
	v_sub_f32_e32 v58, v58, v150
	v_sub_f32_e32 v61, v61, v153
	v_sub_f32_e32 v59, v62, v152
	s_cmp_lg_u32 s78, -1
	v_sub_f32_e32 v60, v63, v151
	s_cbranch_scc0 .LBB0_800
; __device__ __forceinline__ void attnC_blk(const bf16* Q, const bf16* K, const bf16* Vt, bf16* O, LAS unsigned char* lds, int vcu, int G, int tid) {
;     ...
;                 for (int e = 0; e < 32; ++e) { const int r = e & 15, half = e >> 4; const float z = half ? p1[r] : p0[r];
;                     const float sp = __builtin_amdgcn_logf(1.f + __builtin_amdgcn_exp2f(fminf(z, 80.f)));
;                     lk[e] = -sp; lb[e] = z - sp; }
	v_xor_b32_e32 v62, 0x80000000, v124
	v_xor_b32_e32 v63, 0x80000000, v115
	v_xor_b32_e32 v67, 0x80000000, v127
	v_xor_b32_e32 v68, 0x80000000, v126
	v_xor_b32_e32 v69, 0x80000000, v125
	v_xor_b32_e32 v71, 0x80000000, v130
	v_xor_b32_e32 v73, 0x80000000, v129
	v_xor_b32_e32 v75, 0x80000000, v128
	v_xor_b32_e32 v70, 0x80000000, v70
	v_xor_b32_e32 v72, 0x80000000, v132
	v_xor_b32_e32 v74, 0x80000000, v131
	v_xor_b32_e32 v76, 0x80000000, v135
	v_xor_b32_e32 v77, 0x80000000, v134
	v_xor_b32_e32 v79, 0x80000000, v133
	v_xor_b32_e32 v124, 0x80000000, v138
	v_xor_b32_e32 v126, 0x80000000, v137
	v_xor_b32_e32 v78, 0x80000000, v136
	v_xor_b32_e32 v115, 0x80000000, v141
	v_xor_b32_e32 v125, 0x80000000, v140
	v_xor_b32_e32 v127, 0x80000000, v139
	v_xor_b32_e32 v129, 0x80000000, v144
	v_xor_b32_e32 v131, 0x80000000, v143
	v_xor_b32_e32 v133, 0x80000000, v142
	v_xor_b32_e32 v135, 0x80000000, v147
	v_xor_b32_e32 v128, 0x80000000, v146
	v_xor_b32_e32 v130, 0x80000000, v145
	v_xor_b32_e32 v132, 0x80000000, v150
	v_xor_b32_e32 v134, 0x80000000, v149
	v_xor_b32_e32 v136, 0x80000000, v148
	v_xor_b32_e32 v137, 0x80000000, v153
	v_xor_b32_e32 v138, 0x80000000, v152
	v_xor_b32_e32 v139, 0x80000000, v151
	s_branch .LBB0_801

; #define PG8_STAGE(bufoff, gbase, voff) do { _Pragma("unroll") for (int _i = 0; _i < 2; ++_i) \
;         __builtin_amdgcn_global_load_lds((const unsigned*)((const char*)(gbase) + (voff)[_i]), (PG8_LAS unsigned*)(lds + (bufoff) + ldsw + _i * 8192), 16, 0, 0); } while (0)
; #define PG8_LDA(dst, b, h) do { _Pragma("unroll") for (int m = 0; m < 4; ++m) _Pragma("unroll") for (int k = 0; k < 2; ++k) dst[m][k] = *(const PG8_LAS bf16x8*)(lds + PG8_SA(b, h) + aoff + m * 2048 + k * 1024); } while (0)
; #define PG8_LDB(dst, b, h) do { _Pragma("unroll") for (int n = 0; n < 2; ++n) _Pragma("unroll") for (int k = 0; k < 2; ++k) dst[n][k] = *(const PG8_LAS bf16x8*)(lds + PG8_SB(b, h) + boff + n * 2048 + k * 1024); } while (0)
; #define PG8_MMA(ai, bj, At, Bt) do { __builtin_amdgcn_s_setprio(1); _Pragma("unroll") for (int m = 0; m < 4; ++m) _Pragma("unroll") for (int n = 0; n < 2; ++n) _Pragma("unroll") for (int k = 0; k < 2; ++k) \
;         acc[ai][bj][m][n] = __builtin_amdgcn_mfma_f32_16x16x32_bf16(Bt[n][k], At[m][k], acc[ai][bj][m][n], 0, 0, 0); __builtin_amdgcn_s_setprio(0); } while (0)
; #define PG8_WAIT_V(n) asm volatile("s_waitcnt vmcnt(" #n ")" ::: "memory")
; #define PG8_WAIT_L(n) asm volatile("s_waitcnt lgkmcnt(" #n ")" ::: "memory")
; #define PG8_BAR __builtin_amdgcn_s_barrier()
; #define PG8_SCHED __builtin_amdgcn_sched_barrier(0)
; template <class Epi, class Sched, bool ALIGN_EPI = false, bool SP2 = false>
; __device__ __forceinline__ void gemm_phase(PG8_LAS unsigned char* lds, const Gemm g, const Sched& S, const Epi& E, const int wave_s) {
;     ...
;             PG8_LDB(B0, 0, 0); PG8_LDB(B1, 0, 1); PG8_SCHED; PG8_LDA(At, 0, 0); PG8_STAGE(PG8_SA(1, 1), a1 + hstep, voffA);
;             PG8_WAIT_V(8); PG8_WAIT_L(0); PG8_BAR; PG8_MMA(0, 0, At, B0); PG8_MMA(0, 1, At, B1); PG8_BAR; PG8_SCHED;
;             PG8_LDA(At, 0, 1); PG8_STAGE(PG8_SB(0, 0), b2, voffB); PG8_STAGE(PG8_SB(0, 1), b2 + hstep, voffB); PG8_STAGE(PG8_SA(0, 0), a2, voffA);
;             PG8_WAIT_V(8); PG8_WAIT_L(0); PG8_BAR; PG8_MMA(1, 0, At, B0); PG8_MMA(1, 1, At, B1); PG8_BAR; PG8_SCHED;
.LBB0_874:
	s_add_u32 s4, s2, 0xfffc0080
	s_addc_u32 s5, s3, -1
	s_add_i32 s54, 0, 0x10000
	s_cmp_eq_u32 s53, 12
	s_cselect_b32 s31, s25, s5
	s_cselect_b32 s30, s49, s4
	s_cselect_b32 s5, s23, s52
	s_cselect_b32 s4, s50, s51
	s_add_i32 s56, 0, 0x14000
	v_add_u32_e32 v94, s54, v230
	v_add_u32_e32 v142, s56, v230
	ds_read_b128 v[66:69], v94
	ds_read_b128 v[70:73], v94 offset:1024
	ds_read_b128 v[82:85], v94 offset:2048
	ds_read_b128 v[94:97], v94 offset:3072
	ds_read_b128 v[106:109], v142
	ds_read_b128 v[118:121], v142 offset:1024
	ds_read_b128 v[130:133], v142 offset:2048
	ds_read_b128 v[142:145], v142 offset:3072
	v_lshl_add_u64 v[194:195], s[2:3], 0, v[218:219]
	s_add_i32 m0, s38, 0xc000
	ds_read_b128 v[154:157], v231
	ds_read_b128 v[166:169], v231 offset:1024
	ds_read_b128 v[170:173], v231 offset:2048
	ds_read_b128 v[174:177], v231 offset:3072
	ds_read_b128 v[178:181], v231 offset:4096
	ds_read_b128 v[182:185], v231 offset:5120
	ds_read_b128 v[186:189], v231 offset:6144
	ds_read_b128 v[190:193], v231 offset:7168
	global_load_lds_dwordx4 v[194:195], off
	v_lshl_add_u64 v[194:195], s[2:3], 0, v[220:221]
	s_add_i32 m0, s38, 0xe000
	s_nop 0
	global_load_lds_dwordx4 v[194:195], off
	s_waitcnt vmcnt(8)
	s_waitcnt lgkmcnt(0)
	s_setprio 1
	s_barrier
	v_mfma_f32_16x16x32_bf16 v[162:165], v[66:69], v[154:157], v[162:165]
	v_mfma_f32_16x16x32_bf16 v[158:161], v[82:85], v[154:157], v[158:161]
	v_mfma_f32_16x16x32_bf16 v[138:141], v[66:69], v[170:173], v[138:141]
	v_mfma_f32_16x16x32_bf16 v[134:137], v[82:85], v[170:173], v[134:137]
	v_mfma_f32_16x16x32_bf16 v[114:117], v[66:69], v[178:181], v[114:117]
	v_mfma_f32_16x16x32_bf16 v[110:113], v[82:85], v[178:181], v[110:113]
	v_mfma_f32_16x16x32_bf16 v[90:93], v[66:69], v[186:189], v[90:93]
	v_mfma_f32_16x16x32_bf16 v[86:89], v[82:85], v[186:189], v[86:89]
	v_mfma_f32_16x16x32_bf16 v[162:165], v[70:73], v[166:169], v[162:165]
	v_mfma_f32_16x16x32_bf16 v[158:161], v[94:97], v[166:169], v[158:161]
	v_mfma_f32_16x16x32_bf16 v[138:141], v[70:73], v[174:177], v[138:141]
	v_mfma_f32_16x16x32_bf16 v[134:137], v[94:97], v[174:177], v[134:137]
	v_mfma_f32_16x16x32_bf16 v[114:117], v[70:73], v[182:185], v[114:117]
	v_mfma_f32_16x16x32_bf16 v[110:113], v[94:97], v[182:185], v[110:113]
	v_mfma_f32_16x16x32_bf16 v[90:93], v[70:73], v[190:193], v[90:93]
	v_mfma_f32_16x16x32_bf16 v[86:89], v[94:97], v[190:193], v[86:89]
	v_mfma_f32_16x16x32_bf16 v[150:153], v[106:109], v[154:157], v[150:153]
	v_mfma_f32_16x16x32_bf16 v[146:149], v[130:133], v[154:157], v[146:149]
	v_mfma_f32_16x16x32_bf16 v[126:129], v[106:109], v[170:173], v[126:129]
	v_mfma_f32_16x16x32_bf16 v[122:125], v[130:133], v[170:173], v[122:125]
	v_mfma_f32_16x16x32_bf16 v[102:105], v[106:109], v[178:181], v[102:105]
	v_mfma_f32_16x16x32_bf16 v[98:101], v[130:133], v[178:181], v[98:101]
	v_mfma_f32_16x16x32_bf16 v[78:81], v[106:109], v[186:189], v[78:81]
	v_mfma_f32_16x16x32_bf16 v[74:77], v[130:133], v[186:189], v[74:77]
	v_mfma_f32_16x16x32_bf16 v[150:153], v[118:121], v[166:169], v[150:153]
	v_mfma_f32_16x16x32_bf16 v[146:149], v[142:145], v[166:169], v[146:149]
	v_mfma_f32_16x16x32_bf16 v[126:129], v[118:121], v[174:177], v[126:129]
	v_mfma_f32_16x16x32_bf16 v[122:125], v[142:145], v[174:177], v[122:125]
	v_mfma_f32_16x16x32_bf16 v[102:105], v[118:121], v[182:185], v[102:105]
	v_mfma_f32_16x16x32_bf16 v[98:101], v[142:145], v[182:185], v[98:101]
	v_mfma_f32_16x16x32_bf16 v[78:81], v[118:121], v[190:193], v[78:81]
	v_mfma_f32_16x16x32_bf16 v[74:77], v[142:145], v[190:193], v[74:77]
	s_barrier
	s_setprio 0
	s_add_i32 s54, s54, s35
	v_lshl_add_u64 v[194:195], s[4:5], 0, v[0:1]
	s_mov_b32 m0, s54
	ds_read_b128 v[154:157], v231 offset:16384
	ds_read_b128 v[166:169], v231 offset:17408
	ds_read_b128 v[170:173], v231 offset:18432
	ds_read_b128 v[174:177], v231 offset:19456
	ds_read_b128 v[178:181], v231 offset:20480
	ds_read_b128 v[182:185], v231 offset:21504
	ds_read_b128 v[186:189], v231 offset:22528
	ds_read_b128 v[190:193], v231 offset:23552
	global_load_lds_dwordx4 v[194:195], off
	s_add_i32 m0, s54, 0x2000
	s_add_u32 s54, s4, 0x40000
	v_lshl_add_u64 v[196:197], s[4:5], 0, v[212:213]
	s_addc_u32 s55, s5, 0
	s_add_i32 s56, s56, s35
	global_load_lds_dwordx4 v[196:197], off
	v_lshl_add_u64 v[198:199], s[54:55], 0, v[0:1]
	s_mov_b32 m0, s56
	v_lshl_add_u64 v[200:201], s[30:31], 0, v[214:215]
	global_load_lds_dwordx4 v[198:199], off
	v_lshl_add_u64 v[198:199], s[54:55], 0, v[212:213]
	s_add_i32 m0, s56, 0x2000
	s_nop 0
	global_load_lds_dwordx4 v[198:199], off
	v_lshl_add_u64 v[198:199], s[30:31], 0, v[216:217]
	s_mov_b32 m0, s38
	s_nop 0
	global_load_lds_dwordx4 v[198:199], off
	s_mov_b32 m0, s39
	s_nop 0
	global_load_lds_dwordx4 v[200:201], off
	s_waitcnt vmcnt(8)
	s_waitcnt lgkmcnt(0)
	s_setprio 1
	s_barrier
; #define PG8_STAGE(bufoff, gbase, voff) do { _Pragma("unroll") for (int _i = 0; _i < 2; ++_i) \
;         __builtin_amdgcn_global_load_lds((const unsigned*)((const char*)(gbase) + (voff)[_i]), (PG8_LAS unsigned*)(lds + (bufoff) + ldsw + _i * 8192), 16, 0, 0); } while (0)
; #define PG8_LDA(dst, b, h) do { _Pragma("unroll") for (int m = 0; m < 4; ++m) _Pragma("unroll") for (int k = 0; k < 2; ++k) dst[m][k] = *(const PG8_LAS bf16x8*)(lds + PG8_SA(b, h) + aoff + m * 2048 + k * 1024); } while (0)
; #define PG8_LDB(dst, b, h) do { _Pragma("unroll") for (int n = 0; n < 2; ++n) _Pragma("unroll") for (int k = 0; k < 2; ++k) dst[n][k] = *(const PG8_LAS bf16x8*)(lds + PG8_SB(b, h) + boff + n * 2048 + k * 1024); } while (0)
; #define PG8_MMA(ai, bj, At, Bt) do { __builtin_amdgcn_s_setprio(1); _Pragma("unroll") for (int m = 0; m < 4; ++m) _Pragma("unroll") for (int n = 0; n < 2; ++n) _Pragma("unroll") for (int k = 0; k < 2; ++k) \
;         acc[ai][bj][m][n] = __builtin_amdgcn_mfma_f32_16x16x32_bf16(Bt[n][k], At[m][k], acc[ai][bj][m][n], 0, 0, 0); __builtin_amdgcn_s_setprio(0); } while (0)
; #define PG8_WAIT_V(n) asm volatile("s_waitcnt vmcnt(" #n ")" ::: "memory")
; #define PG8_WAIT_L(n) asm volatile("s_waitcnt lgkmcnt(" #n ")" ::: "memory")
; #define PG8_BAR __builtin_amdgcn_s_barrier()
; #define PG8_SCHED __builtin_amdgcn_sched_barrier(0)
; template <class Epi, class Sched, bool ALIGN_EPI = false, bool SP2 = false>
; __device__ __forceinline__ void gemm_phase(PG8_LAS unsigned char* lds, const Gemm g, const Sched& S, const Epi& E, const int wave_s) {
;     ...
;             PG8_WAIT_V(8); PG8_WAIT_L(0); PG8_BAR; PG8_MMA(1, 0, At, B0); PG8_MMA(1, 1, At, B1); PG8_BAR; PG8_SCHED;
;             PG8_LDB(B0, 1, 0); PG8_LDB(B1, 1, 1); PG8_SCHED; PG8_LDA(At, 1, 0); PG8_STAGE(PG8_SA(0, 1), a2 + hstep, voffA);
;             PG8_WAIT_V(8); PG8_WAIT_L(0); PG8_BAR; PG8_MMA(0, 0, At, B0); PG8_MMA(0, 1, At, B1); PG8_BAR; PG8_SCHED;
	v_mfma_f32_16x16x32_bf16 v[62:65], v[66:69], v[154:157], v[62:65]
	v_mfma_f32_16x16x32_bf16 v[58:61], v[82:85], v[154:157], v[58:61]
	v_mfma_f32_16x16x32_bf16 v[46:49], v[66:69], v[170:173], v[46:49]
	v_mfma_f32_16x16x32_bf16 v[42:45], v[82:85], v[170:173], v[42:45]
	v_mfma_f32_16x16x32_bf16 v[30:33], v[66:69], v[178:181], v[30:33]
	v_mfma_f32_16x16x32_bf16 v[26:29], v[82:85], v[178:181], v[26:29]
	v_mfma_f32_16x16x32_bf16 v[14:17], v[66:69], v[186:189], v[14:17]
	v_mfma_f32_16x16x32_bf16 v[10:13], v[82:85], v[186:189], v[10:13]
	v_mfma_f32_16x16x32_bf16 v[62:65], v[70:73], v[166:169], v[62:65]
	v_mfma_f32_16x16x32_bf16 v[58:61], v[94:97], v[166:169], v[58:61]
	v_mfma_f32_16x16x32_bf16 v[46:49], v[70:73], v[174:177], v[46:49]
	v_mfma_f32_16x16x32_bf16 v[42:45], v[94:97], v[174:177], v[42:45]
	v_mfma_f32_16x16x32_bf16 v[30:33], v[70:73], v[182:185], v[30:33]
	v_mfma_f32_16x16x32_bf16 v[26:29], v[94:97], v[182:185], v[26:29]
	v_mfma_f32_16x16x32_bf16 v[14:17], v[70:73], v[190:193], v[14:17]
	v_mfma_f32_16x16x32_bf16 v[10:13], v[94:97], v[190:193], v[10:13]
	v_mfma_f32_16x16x32_bf16 v[54:57], v[106:109], v[154:157], v[54:57]
	v_mfma_f32_16x16x32_bf16 v[50:53], v[130:133], v[154:157], v[50:53]
	v_mfma_f32_16x16x32_bf16 v[38:41], v[106:109], v[170:173], v[38:41]
	v_mfma_f32_16x16x32_bf16 v[34:37], v[130:133], v[170:173], v[34:37]
	v_mfma_f32_16x16x32_bf16 v[22:25], v[106:109], v[178:181], v[22:25]
	v_mfma_f32_16x16x32_bf16 v[18:21], v[130:133], v[178:181], v[18:21]
	v_mfma_f32_16x16x32_bf16 v[6:9], v[106:109], v[186:189], v[6:9]
	v_mfma_f32_16x16x32_bf16 v[2:5], v[130:133], v[186:189], v[2:5]
	v_mfma_f32_16x16x32_bf16 v[54:57], v[118:121], v[166:169], v[54:57]
	v_mfma_f32_16x16x32_bf16 v[50:53], v[142:145], v[166:169], v[50:53]
	v_mfma_f32_16x16x32_bf16 v[38:41], v[118:121], v[174:177], v[38:41]
	v_mfma_f32_16x16x32_bf16 v[34:37], v[142:145], v[174:177], v[34:37]
	v_mfma_f32_16x16x32_bf16 v[22:25], v[118:121], v[182:185], v[22:25]
	v_mfma_f32_16x16x32_bf16 v[18:21], v[142:145], v[182:185], v[18:21]
	v_mfma_f32_16x16x32_bf16 v[6:9], v[118:121], v[190:193], v[6:9]
	v_mfma_f32_16x16x32_bf16 v[2:5], v[142:145], v[190:193], v[2:5]
	s_barrier
	s_setprio 0
	s_add_i32 s54, 0, 0x18000
	s_add_i32 s55, 0, 0x1c000
	v_add_u32_e32 v94, s54, v230
	v_add_u32_e32 v142, s55, v230
	ds_read_b128 v[66:69], v94
	ds_read_b128 v[70:73], v94 offset:1024
	ds_read_b128 v[82:85], v94 offset:2048
	ds_read_b128 v[94:97], v94 offset:3072
	ds_read_b128 v[106:109], v142
	ds_read_b128 v[118:121], v142 offset:1024
	ds_read_b128 v[130:133], v142 offset:2048
	ds_read_b128 v[142:145], v142 offset:3072
	s_add_u32 s30, s30, 0x40000
	s_addc_u32 s31, s31, 0
	s_mov_b32 m0, s40
	v_lshl_add_u64 v[202:203], s[30:31], 0, v[216:217]
	ds_read_b128 v[154:157], v231 offset:32768
	ds_read_b128 v[166:169], v231 offset:33792
	ds_read_b128 v[170:173], v231 offset:34816
	ds_read_b128 v[174:177], v231 offset:35840
	ds_read_b128 v[178:181], v231 offset:36864
	ds_read_b128 v[182:185], v231 offset:37888
	ds_read_b128 v[186:189], v231 offset:38912
	ds_read_b128 v[190:193], v231 offset:39936
	global_load_lds_dwordx4 v[202:203], off
	v_lshl_add_u64 v[202:203], s[30:31], 0, v[214:215]
	s_mov_b32 m0, s41
	s_nop 0
	global_load_lds_dwordx4 v[202:203], off
	s_waitcnt vmcnt(8)
	s_waitcnt lgkmcnt(0)
	s_setprio 1
	s_barrier
	v_mfma_f32_16x16x32_bf16 v[162:165], v[66:69], v[154:157], v[162:165]
	v_mfma_f32_16x16x32_bf16 v[158:161], v[82:85], v[154:157], v[158:161]
	v_mfma_f32_16x16x32_bf16 v[138:141], v[66:69], v[170:173], v[138:141]
	v_mfma_f32_16x16x32_bf16 v[134:137], v[82:85], v[170:173], v[134:137]
	v_mfma_f32_16x16x32_bf16 v[114:117], v[66:69], v[178:181], v[114:117]
	v_mfma_f32_16x16x32_bf16 v[110:113], v[82:85], v[178:181], v[110:113]
	v_mfma_f32_16x16x32_bf16 v[90:93], v[66:69], v[186:189], v[90:93]
	v_mfma_f32_16x16x32_bf16 v[86:89], v[82:85], v[186:189], v[86:89]
	v_mfma_f32_16x16x32_bf16 v[162:165], v[70:73], v[166:169], v[162:165]
	v_mfma_f32_16x16x32_bf16 v[158:161], v[94:97], v[166:169], v[158:161]
	v_mfma_f32_16x16x32_bf16 v[138:141], v[70:73], v[174:177], v[138:141]
	v_mfma_f32_16x16x32_bf16 v[134:137], v[94:97], v[174:177], v[134:137]
	v_mfma_f32_16x16x32_bf16 v[114:117], v[70:73], v[182:185], v[114:117]
	v_mfma_f32_16x16x32_bf16 v[110:113], v[94:97], v[182:185], v[110:113]
	v_mfma_f32_16x16x32_bf16 v[90:93], v[70:73], v[190:193], v[90:93]
	v_mfma_f32_16x16x32_bf16 v[86:89], v[94:97], v[190:193], v[86:89]
	v_mfma_f32_16x16x32_bf16 v[150:153], v[106:109], v[154:157], v[150:153]
	v_mfma_f32_16x16x32_bf16 v[146:149], v[130:133], v[154:157], v[146:149]
	v_mfma_f32_16x16x32_bf16 v[126:129], v[106:109], v[170:173], v[126:129]
	v_mfma_f32_16x16x32_bf16 v[122:125], v[130:133], v[170:173], v[122:125]
	v_mfma_f32_16x16x32_bf16 v[102:105], v[106:109], v[178:181], v[102:105]
	v_mfma_f32_16x16x32_bf16 v[98:101], v[130:133], v[178:181], v[98:101]
	v_mfma_f32_16x16x32_bf16 v[78:81], v[106:109], v[186:189], v[78:81]
	v_mfma_f32_16x16x32_bf16 v[74:77], v[130:133], v[186:189], v[74:77]
	v_mfma_f32_16x16x32_bf16 v[150:153], v[118:121], v[166:169], v[150:153]
	v_mfma_f32_16x16x32_bf16 v[146:149], v[142:145], v[166:169], v[146:149]
	v_mfma_f32_16x16x32_bf16 v[126:129], v[118:121], v[174:177], v[126:129]
	v_mfma_f32_16x16x32_bf16 v[122:125], v[142:145], v[174:177], v[122:125]
	v_mfma_f32_16x16x32_bf16 v[102:105], v[118:121], v[182:185], v[102:105]
	v_mfma_f32_16x16x32_bf16 v[98:101], v[142:145], v[182:185], v[98:101]
	v_mfma_f32_16x16x32_bf16 v[78:81], v[118:121], v[190:193], v[78:81]
	v_mfma_f32_16x16x32_bf16 v[74:77], v[142:145], v[190:193], v[74:77]
	s_barrier
; #define PG8_STAGE(bufoff, gbase, voff) do { _Pragma("unroll") for (int _i = 0; _i < 2; ++_i) \
;         __builtin_amdgcn_global_load_lds((const unsigned*)((const char*)(gbase) + (voff)[_i]), (PG8_LAS unsigned*)(lds + (bufoff) + ldsw + _i * 8192), 16, 0, 0); } while (0)
; #define PG8_LDA(dst, b, h) do { _Pragma("unroll") for (int m = 0; m < 4; ++m) _Pragma("unroll") for (int k = 0; k < 2; ++k) dst[m][k] = *(const PG8_LAS bf16x8*)(lds + PG8_SA(b, h) + aoff + m * 2048 + k * 1024); } while (0)
; #define PG8_MMA(ai, bj, At, Bt) do { __builtin_amdgcn_s_setprio(1); _Pragma("unroll") for (int m = 0; m < 4; ++m) _Pragma("unroll") for (int n = 0; n < 2; ++n) _Pragma("unroll") for (int k = 0; k < 2; ++k) \
;         acc[ai][bj][m][n] = __builtin_amdgcn_mfma_f32_16x16x32_bf16(Bt[n][k], At[m][k], acc[ai][bj][m][n], 0, 0, 0); __builtin_amdgcn_s_setprio(0); } while (0)
; #define PG8_WAIT_V(n) asm volatile("s_waitcnt vmcnt(" #n ")" ::: "memory")
; #define PG8_WAIT_L(n) asm volatile("s_waitcnt lgkmcnt(" #n ")" ::: "memory")
; #define PG8_BAR __builtin_amdgcn_s_barrier()
; #define PG8_SCHED __builtin_amdgcn_sched_barrier(0)
; template <class Epi, class Sched, bool ALIGN_EPI = false, bool SP2 = false>
; __device__ __forceinline__ void gemm_phase(PG8_LAS unsigned char* lds, const Gemm g, const Sched& S, const Epi& E, const int wave_s) {
;     ...
;             PG8_LDA(At, 1, 1); PG8_STAGE(PG8_SB(1, 0), b3, voffB); PG8_STAGE(PG8_SB(1, 1), b3 + hstep, voffB); PG8_STAGE(PG8_SA(1, 0), a3, voffA);
;             PG8_WAIT_V(8); PG8_WAIT_L(0); PG8_BAR; PG8_MMA(1, 0, At, B0); PG8_MMA(1, 1, At, B1); PG8_BAR; PG8_SCHED;
	s_setprio 0
	s_add_i32 s30, s54, s35
	v_lshl_add_u64 v[194:195], v[194:195], 0, s[86:87]
	s_mov_b32 m0, s30
	ds_read_b128 v[154:157], v231 offset:49152
	ds_read_b128 v[166:169], v231 offset:50176
	ds_read_b128 v[170:173], v231 offset:51200
	ds_read_b128 v[174:177], v231 offset:52224
	ds_read_b128 v[178:181], v231 offset:53248
	ds_read_b128 v[182:185], v231 offset:54272
	ds_read_b128 v[186:189], v231 offset:55296
	ds_read_b128 v[190:193], v231 offset:56320
	global_load_lds_dwordx4 v[194:195], off
	s_add_i32 m0, s30, 0x2000
	s_add_u32 s4, s4, 0x40080
	v_lshl_add_u64 v[194:195], v[196:197], 0, s[86:87]
	s_addc_u32 s5, s5, 0
	s_add_i32 s30, s55, s35
	global_load_lds_dwordx4 v[194:195], off
	v_lshl_add_u64 v[194:195], s[4:5], 0, v[0:1]
	s_mov_b32 m0, s30
	s_nop 0
	global_load_lds_dwordx4 v[194:195], off
	v_lshl_add_u64 v[194:195], s[4:5], 0, v[212:213]
	s_add_i32 m0, s30, 0x2000
	s_nop 0
	global_load_lds_dwordx4 v[194:195], off
	v_lshl_add_u64 v[194:195], v[198:199], 0, s[86:87]
	s_mov_b32 m0, s45
	s_nop 0
	global_load_lds_dwordx4 v[194:195], off
	v_lshl_add_u64 v[194:195], v[200:201], 0, s[86:87]
	s_mov_b32 m0, s46
	s_nop 0
	global_load_lds_dwordx4 v[194:195], off
	s_waitcnt vmcnt(8)
	s_waitcnt lgkmcnt(0)
	s_setprio 1
	s_barrier
	v_mfma_f32_16x16x32_bf16 v[62:65], v[66:69], v[154:157], v[62:65]
	v_mfma_f32_16x16x32_bf16 v[58:61], v[82:85], v[154:157], v[58:61]
	v_mfma_f32_16x16x32_bf16 v[46:49], v[66:69], v[170:173], v[46:49]
	v_mfma_f32_16x16x32_bf16 v[42:45], v[82:85], v[170:173], v[42:45]
	v_mfma_f32_16x16x32_bf16 v[30:33], v[66:69], v[178:181], v[30:33]
	v_mfma_f32_16x16x32_bf16 v[26:29], v[82:85], v[178:181], v[26:29]
	v_mfma_f32_16x16x32_bf16 v[14:17], v[66:69], v[186:189], v[14:17]
	v_mfma_f32_16x16x32_bf16 v[10:13], v[82:85], v[186:189], v[10:13]
	v_mfma_f32_16x16x32_bf16 v[62:65], v[70:73], v[166:169], v[62:65]
	v_mfma_f32_16x16x32_bf16 v[58:61], v[94:97], v[166:169], v[58:61]
	v_mfma_f32_16x16x32_bf16 v[46:49], v[70:73], v[174:177], v[46:49]
	v_mfma_f32_16x16x32_bf16 v[42:45], v[94:97], v[174:177], v[42:45]
	v_mfma_f32_16x16x32_bf16 v[30:33], v[70:73], v[182:185], v[30:33]
	v_mfma_f32_16x16x32_bf16 v[26:29], v[94:97], v[182:185], v[26:29]
	v_mfma_f32_16x16x32_bf16 v[14:17], v[70:73], v[190:193], v[14:17]
	v_mfma_f32_16x16x32_bf16 v[10:13], v[94:97], v[190:193], v[10:13]
	v_mfma_f32_16x16x32_bf16 v[54:57], v[106:109], v[154:157], v[54:57]
	v_mfma_f32_16x16x32_bf16 v[50:53], v[130:133], v[154:157], v[50:53]
	v_mfma_f32_16x16x32_bf16 v[38:41], v[106:109], v[170:173], v[38:41]
	v_mfma_f32_16x16x32_bf16 v[34:37], v[130:133], v[170:173], v[34:37]
	v_mfma_f32_16x16x32_bf16 v[22:25], v[106:109], v[178:181], v[22:25]
	v_mfma_f32_16x16x32_bf16 v[18:21], v[130:133], v[178:181], v[18:21]
	v_mfma_f32_16x16x32_bf16 v[6:9], v[106:109], v[186:189], v[6:9]
	v_mfma_f32_16x16x32_bf16 v[2:5], v[130:133], v[186:189], v[2:5]
	v_mfma_f32_16x16x32_bf16 v[54:57], v[118:121], v[166:169], v[54:57]
	v_mfma_f32_16x16x32_bf16 v[50:53], v[142:145], v[166:169], v[50:53]
	v_mfma_f32_16x16x32_bf16 v[38:41], v[118:121], v[174:177], v[38:41]
	v_mfma_f32_16x16x32_bf16 v[34:37], v[142:145], v[174:177], v[34:37]
	v_mfma_f32_16x16x32_bf16 v[22:25], v[118:121], v[182:185], v[22:25]
	v_mfma_f32_16x16x32_bf16 v[18:21], v[142:145], v[182:185], v[18:21]
	v_mfma_f32_16x16x32_bf16 v[6:9], v[118:121], v[190:193], v[6:9]
	v_mfma_f32_16x16x32_bf16 v[2:5], v[142:145], v[190:193], v[2:5]
	s_barrier
	s_setprio 0
	s_add_i32 s53, s53, 2
	s_add_u32 s2, s2, 0x100
	s_addc_u32 s3, s3, 0
	s_add_u32 s51, s51, 0x100
	s_addc_u32 s52, s52, 0
	s_cmp_gt_u32 s53, 13
	s_cbranch_scc0 .LBB0_874
	s_and_b64 vcc, exec, s[16:17]
	s_cbranch_vccz .LBB0_877
	s_barrier

;     __device__ __forceinline__ void operator()(const f32x4 (&acc)[2][2][4][2], const Unit& u, int wr, int wc, int fr_in, int fq_in) const {
;     ...
;             for (int m = 0; m < 4; ++m) { const int rl = ai * HALF + wr * 64 + m * 16 + fr; const size_t off = (size_t)(u.pm * BM + rl) * ldc + col0;
;                 float ss = 0.f;
; #pragma unroll
;                 for (int bj = 0; bj < 2; ++bj) {
;                     f32x4 b0, b1;
;                     if (base32) { b0 = *(const f32x4*)(base32 + off + bj * HALF); b1 = *(const f32x4*)(base32 + off + bj * HALF + 4); }
.LBB0_880:
	v_lshlrev_b64 v[194:195], 10, v[194:195]
	v_lshl_add_u64 v[226:227], v[222:223], 0, v[194:195]
	s_and_b64 vcc, exec, s[2:3]
	v_lshl_add_u64 v[224:225], v[226:227], 2, s[8:9]
	s_cbranch_vccnz .LBB0_899
	global_load_dwordx4 v[198:201], v[224:225], off offset:16
	global_load_dwordx4 v[194:197], v[224:225], off
	s_waitcnt vmcnt(0)
	s_cbranch_execnz .LBB0_883

; __device__ __forceinline__ unsigned cvt_pk_bf16(float lo, float hi) { unsigned r; asm volatile("v_cvt_pk_bf16_f32 %0, %1, %2" : "=v"(r) : "v"(lo), "v"(hi)); return r; }
;     __device__ __forceinline__ void operator()(const f32x4 (&acc)[2][2][4][2], const Unit& u, int wr, int wc, int fr_in, int fq_in) const {
;     ...
;                 for (int bj = 0; bj < 2; ++bj) {
;                     f32x4 b0, b1;
;                     if (base32) { b0 = *(const f32x4*)(base32 + off + bj * HALF); b1 = *(const f32x4*)(base32 + off + bj * HALF + 4); }
;                     else { const u32x4 r = pre[ai][m][bj];
;                         b0 = (f32x4){__uint_as_float(r.x << 16), __uint_as_float(r.x & 0xFFFF0000u), __uint_as_float(r.y << 16), __uint_as_float(r.y & 0xFFFF0000u)};
;                         b1 = (f32x4){__uint_as_float(r.z << 16), __uint_as_float(r.z & 0xFFFF0000u), __uint_as_float(r.w << 16), __uint_as_float(r.w & 0xFFFF0000u)}; }
;                     const f32x4 v0 = b0 + acc[ai][bj][m][0], v1 = b1 + acc[ai][bj][m][1];
;                     if (out32) { *(f32x4*)(out32 + off + bj * HALF) = v0; *(f32x4*)(out32 + off + bj * HALF + 4) = v1; }
;                     if (XB) { u32x4 w; w.x = cvt_pk_bf16(v0[0], v0[1]); w.y = cvt_pk_bf16(v0[2], v0[3]); w.z = cvt_pk_bf16(v1[0], v1[1]); w.w = cvt_pk_bf16(v1[2], v1[3]); *(u32x4*)(XB + off + bj * HALF) = w;
;                         const f32x4 q0 = (f32x4){__uint_as_float(w.x << 16), __uint_as_float(w.x & 0xFFFF0000u), __uint_as_float(w.y << 16), __uint_as_float(w.y & 0xFFFF0000u)};
;                         const f32x4 q1 = (f32x4){__uint_as_float(w.z << 16), __uint_as_float(w.z & 0xFFFF0000u), __uint_as_float(w.w << 16), __uint_as_float(w.w & 0xFFFF0000u)};
;                         ss += ((q0[0] * q0[0] + q0[1] * q0[1]) + (q0[2] * q0[2] + q0[3] * q0[3])) + ((q1[0] * q1[0] + q1[1] * q1[1]) + (q1[2] * q1[2] + q1[3] * q1[3])); } }
;                 ss += __shfl_xor(ss, 16); ss += __shfl_xor(ss, 32);
;                 if (fq == 0) part[rl * 4 + wc] = ss;
.LBB0_883:
	v_pk_add_f32 v[162:163], v[162:163], v[194:195]
	v_pk_add_f32 v[190:191], v[160:161], v[200:201]
	v_pk_add_f32 v[160:161], v[158:159], v[198:199]
	v_lshl_add_u64 v[194:195], v[226:227], 1, s[12:13]
	s_and_b64 vcc, exec, s[2:3]
	v_pk_add_f32 v[164:165], v[164:165], v[196:197]
	v_cvt_pk_bf16_f32 v158, v162, v163
	s_nop 0
	v_cvt_pk_bf16_f32 v159, v164, v165
	v_cvt_pk_bf16_f32 v160, v160, v161
	v_cvt_pk_bf16_f32 v161, v190, v191
	global_store_dwordx4 v[194:195], v[158:161], off
	s_cbranch_vccnz .LBB0_900
	global_load_dwordx4 v[190:193], v[224:225], off offset:528
	global_load_dwordx4 v[162:165], v[224:225], off offset:512
	s_waitcnt vmcnt(0)
	s_cbranch_execnz .LBB0_886
.LBB0_885:
	v_lshlrev_b32_e32 v162, 16, v186
	v_and_b32_e32 v163, 0xffff0000, v186
	v_lshlrev_b32_e32 v164, 16, v187
	v_and_b32_e32 v165, 0xffff0000, v187
	v_lshlrev_b32_e32 v190, 16, v188
	v_and_b32_e32 v191, 0xffff0000, v188
	v_lshlrev_b32_e32 v192, 16, v189
	v_and_b32_e32 v193, 0xffff0000, v189
.LBB0_886:
	v_lshlrev_b32_e32 v186, 16, v158
	v_and_b32_e32 v158, 0xffff0000, v158
	v_lshlrev_b32_e32 v187, 16, v159
	v_and_b32_e32 v159, 0xffff0000, v159
	v_mul_f32_e32 v158, v158, v158
	v_mul_f32_e32 v159, v159, v159
	v_lshlrev_b32_e32 v188, 16, v160
	v_and_b32_e32 v160, 0xffff0000, v160
	v_lshlrev_b32_e32 v189, 16, v161
	v_and_b32_e32 v161, 0xffff0000, v161
	v_fmac_f32_e32 v158, v186, v186
	v_fmac_f32_e32 v159, v187, v187
	v_add_f32_e32 v158, v158, v159
	v_mul_f32_e32 v159, v160, v160
	v_mul_f32_e32 v160, v161, v161
	v_fmac_f32_e32 v159, v188, v188
	v_fmac_f32_e32 v160, v189, v189
	v_add_f32_e32 v159, v159, v160
	v_pk_add_f32 v[150:151], v[150:151], v[162:163]
	v_pk_add_f32 v[146:147], v[146:147], v[190:191]
	v_add_f32_e32 v160, v158, v159
	v_pk_add_f32 v[152:153], v[152:153], v[164:165]
	v_pk_add_f32 v[158:159], v[148:149], v[192:193]
	v_cvt_pk_bf16_f32 v148, v150, v151
	v_cvt_pk_bf16_f32 v149, v152, v153
	v_cvt_pk_bf16_f32 v150, v146, v147
	v_cmp_eq_u32_e64 s[4:5], 0, v233
	v_and_b32_e32 v147, 0xffff0000, v148
	v_lshlrev_b32_e32 v146, 16, v148
	v_and_b32_e32 v153, 0xffff0000, v149
	v_mul_f32_e32 v147, v147, v147
	v_lshlrev_b32_e32 v152, 16, v149
	v_fmac_f32_e32 v147, v146, v146
	v_mul_f32_e32 v146, v153, v153
	v_cvt_pk_bf16_f32 v151, v158, v159
	v_and_b32_e32 v159, 0xffff0000, v150
	v_and_b32_e32 v162, 0xffff0000, v151
	v_fmac_f32_e32 v146, v152, v152
	v_lshlrev_b32_e32 v158, 16, v150
	v_lshlrev_b32_e32 v161, 16, v151
	v_add_f32_e32 v146, v147, v146
	v_mul_f32_e32 v147, v159, v159
	v_mul_f32_e32 v152, v162, v162
	v_fmac_f32_e32 v147, v158, v158
	v_fmac_f32_e32 v152, v161, v161
	v_add_f32_e32 v147, v147, v152
	v_and_b32_e32 v152, 64, v238
	v_add_f32_e32 v146, v146, v147
	v_xor_b32_e32 v147, 16, v238
	v_add_u32_e32 v152, 64, v152
	v_cmp_lt_i32_e32 vcc, v147, v152
	v_add_f32_e32 v146, v160, v146
	global_store_dwordx4 v[194:195], v[148:151], off offset:256
	v_cndmask_b32_e32 v147, v238, v147, vcc
	v_lshlrev_b32_e32 v162, 2, v147
	ds_bpermute_b32 v147, v162, v146
	s_waitcnt lgkmcnt(0)
	v_add_f32_e32 v146, v146, v147
	v_xor_b32_e32 v147, 32, v238
	v_cmp_lt_i32_e32 vcc, v147, v152
	s_nop 1
	v_cndmask_b32_e32 v147, v238, v147, vcc
	v_lshlrev_b32_e32 v163, 2, v147
	ds_bpermute_b32 v147, v163, v146
	s_and_saveexec_b64 s[30:31], s[4:5]
	s_cbranch_execz .LBB0_888
	v_lshl_add_u32 v148, v234, 4, s48
	s_waitcnt lgkmcnt(0)
	v_add_f32_e32 v146, v146, v147
	ds_write_b32 v148, v146
; __device__ __forceinline__ unsigned cvt_pk_bf16(float lo, float hi) { unsigned r; asm volatile("v_cvt_pk_bf16_f32 %0, %1, %2" : "=v"(r) : "v"(lo), "v"(hi)); return r; }
;     __device__ __forceinline__ void operator()(const f32x4 (&acc)[2][2][4][2], const Unit& u, int wr, int wc, int fr_in, int fq_in) const {
;     ...
;             for (int m = 0; m < 4; ++m) { const int rl = ai * HALF + wr * 64 + m * 16 + fr; const size_t off = (size_t)(u.pm * BM + rl) * ldc + col0;
;                 float ss = 0.f;
; #pragma unroll
;                 for (int bj = 0; bj < 2; ++bj) {
;                     f32x4 b0, b1;
;                     if (base32) { b0 = *(const f32x4*)(base32 + off + bj * HALF); b1 = *(const f32x4*)(base32 + off + bj * HALF + 4); }
;                     else { const u32x4 r = pre[ai][m][bj];
;                         b0 = (f32x4){__uint_as_float(r.x << 16), __uint_as_float(r.x & 0xFFFF0000u), __uint_as_float(r.y << 16), __uint_as_float(r.y & 0xFFFF0000u)};
;                         b1 = (f32x4){__uint_as_float(r.z << 16), __uint_as_float(r.z & 0xFFFF0000u), __uint_as_float(r.w << 16), __uint_as_float(r.w & 0xFFFF0000u)}; }
;                     const f32x4 v0 = b0 + acc[ai][bj][m][0], v1 = b1 + acc[ai][bj][m][1];
;                     if (out32) { *(f32x4*)(out32 + off + bj * HALF) = v0; *(f32x4*)(out32 + off + bj * HALF + 4) = v1; }
;                     if (XB) { u32x4 w; w.x = cvt_pk_bf16(v0[0], v0[1]); w.y = cvt_pk_bf16(v0[2], v0[3]); w.z = cvt_pk_bf16(v1[0], v1[1]); w.w = cvt_pk_bf16(v1[2], v1[3]); *(u32x4*)(XB + off + bj * HALF) = w;
;                         const f32x4 q0 = (f32x4){__uint_as_float(w.x << 16), __uint_as_float(w.x & 0xFFFF0000u), __uint_as_float(w.y << 16), __uint_as_float(w.y & 0xFFFF0000u)};
;                         const f32x4 q1 = (f32x4){__uint_as_float(w.z << 16), __uint_as_float(w.z & 0xFFFF0000u), __uint_as_float(w.w << 16), __uint_as_float(w.w & 0xFFFF0000u)};
;                         ss += ((q0[0] * q0[0] + q0[1] * q0[1]) + (q0[2] * q0[2] + q0[3] * q0[3])) + ((q1[0] * q1[0] + q1[1] * q1[1]) + (q1[2] * q1[2] + q1[3] * q1[3])); } }
;                 ss += __shfl_xor(ss, 16); ss += __shfl_xor(ss, 32);
;                 if (fq == 0) part[rl * 4 + wc] = ss;
.LBB0_888:
	s_or_b64 exec, exec, s[30:31]
	v_add_u32_e32 v164, 16, v234
	v_add_u32_e32 v146, s21, v164
	s_waitcnt lgkmcnt(0)
	v_ashrrev_i32_e32 v147, 31, v146
	v_lshlrev_b64 v[146:147], 10, v[146:147]
	v_lshl_add_u64 v[160:161], v[222:223], 0, v[146:147]
	s_and_b64 vcc, exec, s[2:3]
	v_lshl_add_u64 v[158:159], v[160:161], 2, s[8:9]
	s_cbranch_vccnz .LBB0_901
	global_load_dwordx4 v[150:153], v[158:159], off offset:16
	global_load_dwordx4 v[146:149], v[158:159], off
	s_waitcnt vmcnt(0)
	s_cbranch_execnz .LBB0_891
.LBB0_890:
	v_lshlrev_b32_e32 v146, 16, v182
	v_and_b32_e32 v147, 0xffff0000, v182
	v_lshlrev_b32_e32 v148, 16, v183
	v_and_b32_e32 v149, 0xffff0000, v183
	v_lshlrev_b32_e32 v150, 16, v184
	v_and_b32_e32 v151, 0xffff0000, v184
	v_lshlrev_b32_e32 v152, 16, v185
	v_and_b32_e32 v153, 0xffff0000, v185
.LBB0_891:
	v_pk_add_f32 v[138:139], v[138:139], v[146:147]
	v_pk_add_f32 v[146:147], v[136:137], v[152:153]
	v_pk_add_f32 v[136:137], v[134:135], v[150:151]
	v_lshl_add_u64 v[150:151], v[160:161], 1, s[12:13]
	s_and_b64 vcc, exec, s[2:3]
	v_pk_add_f32 v[140:141], v[140:141], v[148:149]
	v_cvt_pk_bf16_f32 v134, v138, v139
	s_nop 0
	v_cvt_pk_bf16_f32 v135, v140, v141
	v_cvt_pk_bf16_f32 v136, v136, v137
	v_cvt_pk_bf16_f32 v137, v146, v147
	global_store_dwordx4 v[150:151], v[134:137], off
	s_cbranch_vccnz .LBB0_902
	global_load_dwordx4 v[146:149], v[158:159], off offset:528
	global_load_dwordx4 v[138:141], v[158:159], off offset:512
	s_waitcnt vmcnt(0)
	s_cbranch_execnz .LBB0_894
.LBB0_893:
	v_lshlrev_b32_e32 v138, 16, v178
	v_and_b32_e32 v139, 0xffff0000, v178
	v_lshlrev_b32_e32 v140, 16, v179
	v_and_b32_e32 v141, 0xffff0000, v179
	v_lshlrev_b32_e32 v146, 16, v180
	v_and_b32_e32 v147, 0xffff0000, v180
	v_lshlrev_b32_e32 v148, 16, v181
	v_and_b32_e32 v149, 0xffff0000, v181
.LBB0_894:
	v_lshlrev_b32_e32 v152, 16, v134
	v_and_b32_e32 v134, 0xffff0000, v134
	v_lshlrev_b32_e32 v153, 16, v135
	v_and_b32_e32 v135, 0xffff0000, v135
	v_mul_f32_e32 v134, v134, v134
	v_mul_f32_e32 v135, v135, v135
	v_lshlrev_b32_e32 v158, 16, v136
	v_and_b32_e32 v136, 0xffff0000, v136
	v_lshlrev_b32_e32 v159, 16, v137
	v_and_b32_e32 v137, 0xffff0000, v137
	v_fmac_f32_e32 v134, v152, v152
	v_fmac_f32_e32 v135, v153, v153
	v_add_f32_e32 v134, v134, v135
	v_mul_f32_e32 v135, v136, v136
	v_mul_f32_e32 v136, v137, v137
	v_fmac_f32_e32 v135, v158, v158
	v_fmac_f32_e32 v136, v159, v159
	v_add_f32_e32 v135, v135, v136
	v_pk_add_f32 v[126:127], v[126:127], v[138:139]
	v_pk_add_f32 v[122:123], v[122:123], v[146:147]
	v_add_f32_e32 v136, v134, v135
	v_pk_add_f32 v[128:129], v[128:129], v[140:141]
	v_pk_add_f32 v[134:135], v[124:125], v[148:149]
	v_cvt_pk_bf16_f32 v124, v126, v127
	v_cvt_pk_bf16_f32 v125, v128, v129
	v_cvt_pk_bf16_f32 v126, v122, v123
	s_nop 0
	v_and_b32_e32 v123, 0xffff0000, v124
	v_lshlrev_b32_e32 v122, 16, v124
	v_and_b32_e32 v129, 0xffff0000, v125
	v_mul_f32_e32 v123, v123, v123
	v_lshlrev_b32_e32 v128, 16, v125
	v_fmac_f32_e32 v123, v122, v122
	v_mul_f32_e32 v122, v129, v129
	v_cvt_pk_bf16_f32 v127, v134, v135
	v_and_b32_e32 v135, 0xffff0000, v126
	v_and_b32_e32 v138, 0xffff0000, v127
	v_fmac_f32_e32 v122, v128, v128
	v_lshlrev_b32_e32 v134, 16, v126
	v_lshlrev_b32_e32 v137, 16, v127
	v_add_f32_e32 v122, v123, v122
	v_mul_f32_e32 v123, v135, v135
	v_mul_f32_e32 v128, v138, v138
	v_fmac_f32_e32 v123, v134, v134
	v_fmac_f32_e32 v128, v137, v137
	v_add_f32_e32 v123, v123, v128
	v_add_f32_e32 v122, v122, v123
	v_add_f32_e32 v122, v136, v122
	ds_bpermute_b32 v123, v162, v122
	global_store_dwordx4 v[150:151], v[124:127], off offset:256
	s_waitcnt lgkmcnt(0)
	v_add_f32_e32 v122, v122, v123
	ds_bpermute_b32 v123, v163, v122
	s_and_saveexec_b64 s[30:31], s[4:5]
	s_cbranch_execz .LBB0_896
	v_lshl_add_u32 v124, v164, 4, s48
	s_waitcnt lgkmcnt(0)
	v_add_f32_e32 v122, v122, v123
	ds_write_b32 v124, v122

; __device__ __forceinline__ unsigned cvt_pk_bf16(float lo, float hi) { unsigned r; asm volatile("v_cvt_pk_bf16_f32 %0, %1, %2" : "=v"(r) : "v"(lo), "v"(hi)); return r; }
;     __device__ __forceinline__ void operator()(const f32x4 (&acc)[2][2][4][2], const Unit& u, int wr, int wc, int fr_in, int fq_in) const {
;     ...
;             for (int m = 0; m < 4; ++m) { const int rl = ai * HALF + wr * 64 + m * 16 + fr; const size_t off = (size_t)(u.pm * BM + rl) * ldc + col0;
;                 float ss = 0.f;
; #pragma unroll
;                 for (int bj = 0; bj < 2; ++bj) {
;                     f32x4 b0, b1;
;                     if (base32) { b0 = *(const f32x4*)(base32 + off + bj * HALF); b1 = *(const f32x4*)(base32 + off + bj * HALF + 4); }
;                     else { const u32x4 r = pre[ai][m][bj];
;                         b0 = (f32x4){__uint_as_float(r.x << 16), __uint_as_float(r.x & 0xFFFF0000u), __uint_as_float(r.y << 16), __uint_as_float(r.y & 0xFFFF0000u)};
;                         b1 = (f32x4){__uint_as_float(r.z << 16), __uint_as_float(r.z & 0xFFFF0000u), __uint_as_float(r.w << 16), __uint_as_float(r.w & 0xFFFF0000u)}; }
;                     const f32x4 v0 = b0 + acc[ai][bj][m][0], v1 = b1 + acc[ai][bj][m][1];
;                     if (out32) { *(f32x4*)(out32 + off + bj * HALF) = v0; *(f32x4*)(out32 + off + bj * HALF + 4) = v1; }
;                     if (XB) { u32x4 w; w.x = cvt_pk_bf16(v0[0], v0[1]); w.y = cvt_pk_bf16(v0[2], v0[3]); w.z = cvt_pk_bf16(v1[0], v1[1]); w.w = cvt_pk_bf16(v1[2], v1[3]); *(u32x4*)(XB + off + bj * HALF) = w;
;                         const f32x4 q0 = (f32x4){__uint_as_float(w.x << 16), __uint_as_float(w.x & 0xFFFF0000u), __uint_as_float(w.y << 16), __uint_as_float(w.y & 0xFFFF0000u)};
;                         const f32x4 q1 = (f32x4){__uint_as_float(w.z << 16), __uint_as_float(w.z & 0xFFFF0000u), __uint_as_float(w.w << 16), __uint_as_float(w.w & 0xFFFF0000u)};
;                         ss += ((q0[0] * q0[0] + q0[1] * q0[1]) + (q0[2] * q0[2] + q0[3] * q0[3])) + ((q1[0] * q1[0] + q1[1] * q1[1]) + (q1[2] * q1[2] + q1[3] * q1[3])); } }
;                 ss += __shfl_xor(ss, 16); ss += __shfl_xor(ss, 32);
;                 if (fq == 0) part[rl * 4 + wc] = ss;
.LBB0_904:
	v_add_u32_e32 v136, 32, v234
	v_add_u32_e32 v122, s21, v136
	s_waitcnt lgkmcnt(0)
	v_ashrrev_i32_e32 v123, 31, v122
	v_lshlrev_b64 v[122:123], 10, v[122:123]
	s_cmp_eq_u64 s[30:31], 0
	v_lshl_add_u64 v[134:135], v[222:223], 0, v[122:123]
	s_cbranch_scc1 .LBB0_922
	v_lshl_add_u64 v[122:123], v[134:135], 2, s[30:31]
	global_load_dwordx4 v[126:129], v[122:123], off offset:16
	s_nop 0
	global_load_dwordx4 v[122:125], v[122:123], off
	s_waitcnt vmcnt(0)
	s_cbranch_execnz .LBB0_907
.LBB0_906:
	v_lshlrev_b32_e32 v122, 16, v174
	v_and_b32_e32 v123, 0xffff0000, v174
	v_lshlrev_b32_e32 v124, 16, v175
	v_and_b32_e32 v125, 0xffff0000, v175
	v_lshlrev_b32_e32 v126, 16, v176
	v_and_b32_e32 v127, 0xffff0000, v176
	v_lshlrev_b32_e32 v128, 16, v177
	v_and_b32_e32 v129, 0xffff0000, v177
.LBB0_907:
	v_pk_add_f32 v[114:115], v[114:115], v[122:123]
	v_pk_add_f32 v[122:123], v[112:113], v[128:129]
	v_pk_add_f32 v[112:113], v[110:111], v[126:127]
	v_lshl_add_u64 v[126:127], v[134:135], 1, s[12:13]
	s_and_b64 vcc, exec, s[2:3]
	v_pk_add_f32 v[116:117], v[116:117], v[124:125]
	v_cvt_pk_bf16_f32 v110, v114, v115
	s_nop 0
	v_cvt_pk_bf16_f32 v111, v116, v117
	v_cvt_pk_bf16_f32 v112, v112, v113
	v_cvt_pk_bf16_f32 v113, v122, v123
	global_store_dwordx4 v[126:127], v[110:113], off
	s_cbranch_vccnz .LBB0_923
	v_lshl_add_u64 v[114:115], v[134:135], 2, s[8:9]
	global_load_dwordx4 v[122:125], v[114:115], off offset:528
	s_nop 0
	global_load_dwordx4 v[114:117], v[114:115], off offset:512
	s_waitcnt vmcnt(0)
	s_cbranch_execnz .LBB0_910
.LBB0_909:
	v_lshlrev_b32_e32 v114, 16, v170
	v_and_b32_e32 v115, 0xffff0000, v170
	v_lshlrev_b32_e32 v116, 16, v171
	v_and_b32_e32 v117, 0xffff0000, v171
	v_lshlrev_b32_e32 v122, 16, v172
	v_and_b32_e32 v123, 0xffff0000, v172
	v_lshlrev_b32_e32 v124, 16, v173
	v_and_b32_e32 v125, 0xffff0000, v173
.LBB0_910:
	v_lshlrev_b32_e32 v128, 16, v110
	v_and_b32_e32 v110, 0xffff0000, v110
	v_lshlrev_b32_e32 v129, 16, v111
	v_and_b32_e32 v111, 0xffff0000, v111
	v_mul_f32_e32 v110, v110, v110
	v_mul_f32_e32 v111, v111, v111
	v_lshlrev_b32_e32 v134, 16, v112
	v_and_b32_e32 v112, 0xffff0000, v112
	v_lshlrev_b32_e32 v135, 16, v113
	v_and_b32_e32 v113, 0xffff0000, v113
	v_fmac_f32_e32 v110, v128, v128
	v_fmac_f32_e32 v111, v129, v129
	v_add_f32_e32 v110, v110, v111
	v_mul_f32_e32 v111, v112, v112
	v_mul_f32_e32 v112, v113, v113
	v_fmac_f32_e32 v111, v134, v134
	v_fmac_f32_e32 v112, v135, v135
	v_add_f32_e32 v111, v111, v112
	v_pk_add_f32 v[102:103], v[102:103], v[114:115]
	v_pk_add_f32 v[98:99], v[98:99], v[122:123]
	v_add_f32_e32 v112, v110, v111
	v_pk_add_f32 v[104:105], v[104:105], v[116:117]
	v_pk_add_f32 v[110:111], v[100:101], v[124:125]
	v_cvt_pk_bf16_f32 v100, v102, v103
	v_cvt_pk_bf16_f32 v101, v104, v105
	v_cvt_pk_bf16_f32 v102, v98, v99
	s_nop 0
	v_and_b32_e32 v99, 0xffff0000, v100
	v_lshlrev_b32_e32 v98, 16, v100
	v_and_b32_e32 v105, 0xffff0000, v101
	v_mul_f32_e32 v99, v99, v99
	v_lshlrev_b32_e32 v104, 16, v101
	v_fmac_f32_e32 v99, v98, v98
	v_mul_f32_e32 v98, v105, v105
	v_cvt_pk_bf16_f32 v103, v110, v111
	v_and_b32_e32 v111, 0xffff0000, v102
	v_and_b32_e32 v114, 0xffff0000, v103
	v_fmac_f32_e32 v98, v104, v104
	v_lshlrev_b32_e32 v110, 16, v102
	v_lshlrev_b32_e32 v113, 16, v103
	v_add_f32_e32 v98, v99, v98
	v_mul_f32_e32 v99, v111, v111
	v_mul_f32_e32 v104, v114, v114
	v_fmac_f32_e32 v99, v110, v110
	v_fmac_f32_e32 v104, v113, v113
	v_add_f32_e32 v99, v99, v104
	v_add_f32_e32 v98, v98, v99
	v_add_f32_e32 v98, v112, v98
	ds_bpermute_b32 v99, v162, v98
	global_store_dwordx4 v[126:127], v[100:103], off offset:256
	s_waitcnt lgkmcnt(0)
	v_add_f32_e32 v98, v98, v99
	ds_bpermute_b32 v99, v163, v98
	s_and_saveexec_b64 s[30:31], s[4:5]
	s_cbranch_execz .LBB0_912
	v_lshl_add_u32 v100, v136, 4, s48
	s_waitcnt lgkmcnt(0)
	v_add_f32_e32 v98, v98, v99
	ds_write_b32 v100, v98
; __device__ __forceinline__ unsigned cvt_pk_bf16(float lo, float hi) { unsigned r; asm volatile("v_cvt_pk_bf16_f32 %0, %1, %2" : "=v"(r) : "v"(lo), "v"(hi)); return r; }
;     __device__ __forceinline__ void operator()(const f32x4 (&acc)[2][2][4][2], const Unit& u, int wr, int wc, int fr_in, int fq_in) const {
;     ...
;             for (int m = 0; m < 4; ++m) { const int rl = ai * HALF + wr * 64 + m * 16 + fr; const size_t off = (size_t)(u.pm * BM + rl) * ldc + col0;
;                 float ss = 0.f;
; #pragma unroll
;                 for (int bj = 0; bj < 2; ++bj) {
;                     f32x4 b0, b1;
;                     if (base32) { b0 = *(const f32x4*)(base32 + off + bj * HALF); b1 = *(const f32x4*)(base32 + off + bj * HALF + 4); }
;                     else { const u32x4 r = pre[ai][m][bj];
;                         b0 = (f32x4){__uint_as_float(r.x << 16), __uint_as_float(r.x & 0xFFFF0000u), __uint_as_float(r.y << 16), __uint_as_float(r.y & 0xFFFF0000u)};
;                         b1 = (f32x4){__uint_as_float(r.z << 16), __uint_as_float(r.z & 0xFFFF0000u), __uint_as_float(r.w << 16), __uint_as_float(r.w & 0xFFFF0000u)}; }
;                     const f32x4 v0 = b0 + acc[ai][bj][m][0], v1 = b1 + acc[ai][bj][m][1];
;                     if (out32) { *(f32x4*)(out32 + off + bj * HALF) = v0; *(f32x4*)(out32 + off + bj * HALF + 4) = v1; }
;                     if (XB) { u32x4 w; w.x = cvt_pk_bf16(v0[0], v0[1]); w.y = cvt_pk_bf16(v0[2], v0[3]); w.z = cvt_pk_bf16(v1[0], v1[1]); w.w = cvt_pk_bf16(v1[2], v1[3]); *(u32x4*)(XB + off + bj * HALF) = w;
;                         const f32x4 q0 = (f32x4){__uint_as_float(w.x << 16), __uint_as_float(w.x & 0xFFFF0000u), __uint_as_float(w.y << 16), __uint_as_float(w.y & 0xFFFF0000u)};
;                         const f32x4 q1 = (f32x4){__uint_as_float(w.z << 16), __uint_as_float(w.z & 0xFFFF0000u), __uint_as_float(w.w << 16), __uint_as_float(w.w & 0xFFFF0000u)};
;                         ss += ((q0[0] * q0[0] + q0[1] * q0[1]) + (q0[2] * q0[2] + q0[3] * q0[3])) + ((q1[0] * q1[0] + q1[1] * q1[1]) + (q1[2] * q1[2] + q1[3] * q1[3])); } }
;                 ss += __shfl_xor(ss, 16); ss += __shfl_xor(ss, 32);
;                 if (fq == 0) part[rl * 4 + wc] = ss;
.LBB0_912:
	s_or_b64 exec, exec, s[30:31]
	v_add_u32_e32 v114, 48, v234
	v_add_u32_e32 v98, s21, v114
	s_waitcnt lgkmcnt(0)
	v_ashrrev_i32_e32 v99, 31, v98
	v_lshlrev_b64 v[98:99], 10, v[98:99]
	v_lshl_add_u64 v[112:113], v[222:223], 0, v[98:99]
	s_and_b64 vcc, exec, s[2:3]
	v_lshl_add_u64 v[110:111], v[112:113], 2, s[8:9]
	s_cbranch_vccnz .LBB0_924
	global_load_dwordx4 v[102:105], v[110:111], off offset:16
	global_load_dwordx4 v[98:101], v[110:111], off
	s_waitcnt vmcnt(0)
	s_cbranch_execnz .LBB0_915
.LBB0_914:
	v_lshlrev_b32_e32 v98, 16, v166
	v_and_b32_e32 v99, 0xffff0000, v166
	v_lshlrev_b32_e32 v100, 16, v167
	v_and_b32_e32 v101, 0xffff0000, v167
	v_lshlrev_b32_e32 v102, 16, v168
	v_and_b32_e32 v103, 0xffff0000, v168
	v_lshlrev_b32_e32 v104, 16, v169
	v_and_b32_e32 v105, 0xffff0000, v169
.LBB0_915:
	v_pk_add_f32 v[90:91], v[90:91], v[98:99]
	v_pk_add_f32 v[98:99], v[88:89], v[104:105]
	v_pk_add_f32 v[88:89], v[86:87], v[102:103]
	v_lshl_add_u64 v[102:103], v[112:113], 1, s[12:13]
	s_and_b64 vcc, exec, s[2:3]
	v_pk_add_f32 v[92:93], v[92:93], v[100:101]
	v_cvt_pk_bf16_f32 v86, v90, v91
	s_nop 0
	v_cvt_pk_bf16_f32 v87, v92, v93
	v_cvt_pk_bf16_f32 v88, v88, v89
	v_cvt_pk_bf16_f32 v89, v98, v99
	global_store_dwordx4 v[102:103], v[86:89], off
	s_cbranch_vccnz .LBB0_925
	global_load_dwordx4 v[98:101], v[110:111], off offset:528
	global_load_dwordx4 v[90:93], v[110:111], off offset:512
	s_waitcnt vmcnt(0)
	s_cbranch_execnz .LBB0_918
.LBB0_917:
	v_lshlrev_b32_e32 v90, 16, v154
	v_and_b32_e32 v91, 0xffff0000, v154
	v_lshlrev_b32_e32 v92, 16, v155
	v_and_b32_e32 v93, 0xffff0000, v155
	v_lshlrev_b32_e32 v98, 16, v156
	v_and_b32_e32 v99, 0xffff0000, v156
	v_lshlrev_b32_e32 v100, 16, v157
	v_and_b32_e32 v101, 0xffff0000, v157
.LBB0_918:
	v_lshlrev_b32_e32 v104, 16, v86
	v_and_b32_e32 v86, 0xffff0000, v86
	v_lshlrev_b32_e32 v105, 16, v87
	v_and_b32_e32 v87, 0xffff0000, v87
	v_mul_f32_e32 v86, v86, v86
	v_mul_f32_e32 v87, v87, v87
	v_lshlrev_b32_e32 v110, 16, v88
	v_and_b32_e32 v88, 0xffff0000, v88
	v_lshlrev_b32_e32 v111, 16, v89
	v_and_b32_e32 v89, 0xffff0000, v89
	v_fmac_f32_e32 v86, v104, v104
	v_fmac_f32_e32 v87, v105, v105
	v_add_f32_e32 v86, v86, v87
	v_mul_f32_e32 v87, v88, v88
	v_mul_f32_e32 v88, v89, v89
	v_fmac_f32_e32 v87, v110, v110
	v_fmac_f32_e32 v88, v111, v111
	v_add_f32_e32 v87, v87, v88
	v_pk_add_f32 v[78:79], v[78:79], v[90:91]
	v_pk_add_f32 v[74:75], v[74:75], v[98:99]
	v_add_f32_e32 v88, v86, v87
	v_pk_add_f32 v[80:81], v[80:81], v[92:93]
	v_pk_add_f32 v[86:87], v[76:77], v[100:101]
	v_cvt_pk_bf16_f32 v76, v78, v79
	v_cvt_pk_bf16_f32 v77, v80, v81
	v_cvt_pk_bf16_f32 v78, v74, v75
	s_nop 0
	v_and_b32_e32 v75, 0xffff0000, v76
	v_lshlrev_b32_e32 v74, 16, v76
	v_and_b32_e32 v81, 0xffff0000, v77
	v_mul_f32_e32 v75, v75, v75
	v_lshlrev_b32_e32 v80, 16, v77
	v_fmac_f32_e32 v75, v74, v74
	v_mul_f32_e32 v74, v81, v81
	v_cvt_pk_bf16_f32 v79, v86, v87
	v_and_b32_e32 v87, 0xffff0000, v78
	v_and_b32_e32 v90, 0xffff0000, v79
	v_fmac_f32_e32 v74, v80, v80
	v_lshlrev_b32_e32 v86, 16, v78
	v_lshlrev_b32_e32 v89, 16, v79
	v_add_f32_e32 v74, v75, v74
	v_mul_f32_e32 v75, v87, v87
	v_mul_f32_e32 v80, v90, v90
	v_fmac_f32_e32 v75, v86, v86
	v_fmac_f32_e32 v80, v89, v89
	v_add_f32_e32 v75, v75, v80
	v_add_f32_e32 v74, v74, v75
	v_add_f32_e32 v74, v88, v74
	ds_bpermute_b32 v75, v162, v74
	global_store_dwordx4 v[102:103], v[76:79], off offset:256
	s_waitcnt lgkmcnt(0)
	v_add_f32_e32 v74, v74, v75
	ds_bpermute_b32 v75, v163, v74
	s_and_saveexec_b64 s[30:31], s[4:5]
	s_cbranch_execz .LBB0_920
	v_lshl_add_u32 v76, v114, 4, s48
	s_waitcnt lgkmcnt(0)
	v_add_f32_e32 v74, v74, v75
	ds_write_b32 v76, v74

; __device__ __forceinline__ unsigned cvt_pk_bf16(float lo, float hi) { unsigned r; asm volatile("v_cvt_pk_bf16_f32 %0, %1, %2" : "=v"(r) : "v"(lo), "v"(hi)); return r; }
;     __device__ __forceinline__ void operator()(const f32x4 (&acc)[2][2][4][2], const Unit& u, int wr, int wc, int fr_in, int fq_in) const {
;     ...
;             for (int m = 0; m < 4; ++m) { const int rl = ai * HALF + wr * 64 + m * 16 + fr; const size_t off = (size_t)(u.pm * BM + rl) * ldc + col0;
;                 float ss = 0.f;
; #pragma unroll
;                 for (int bj = 0; bj < 2; ++bj) {
;                     f32x4 b0, b1;
;                     if (base32) { b0 = *(const f32x4*)(base32 + off + bj * HALF); b1 = *(const f32x4*)(base32 + off + bj * HALF + 4); }
;                     else { const u32x4 r = pre[ai][m][bj];
;                         b0 = (f32x4){__uint_as_float(r.x << 16), __uint_as_float(r.x & 0xFFFF0000u), __uint_as_float(r.y << 16), __uint_as_float(r.y & 0xFFFF0000u)};
;                         b1 = (f32x4){__uint_as_float(r.z << 16), __uint_as_float(r.z & 0xFFFF0000u), __uint_as_float(r.w << 16), __uint_as_float(r.w & 0xFFFF0000u)}; }
;                     const f32x4 v0 = b0 + acc[ai][bj][m][0], v1 = b1 + acc[ai][bj][m][1];
;                     if (out32) { *(f32x4*)(out32 + off + bj * HALF) = v0; *(f32x4*)(out32 + off + bj * HALF + 4) = v1; }
;                     if (XB) { u32x4 w; w.x = cvt_pk_bf16(v0[0], v0[1]); w.y = cvt_pk_bf16(v0[2], v0[3]); w.z = cvt_pk_bf16(v1[0], v1[1]); w.w = cvt_pk_bf16(v1[2], v1[3]); *(u32x4*)(XB + off + bj * HALF) = w;
;                         const f32x4 q0 = (f32x4){__uint_as_float(w.x << 16), __uint_as_float(w.x & 0xFFFF0000u), __uint_as_float(w.y << 16), __uint_as_float(w.y & 0xFFFF0000u)};
;                         const f32x4 q1 = (f32x4){__uint_as_float(w.z << 16), __uint_as_float(w.z & 0xFFFF0000u), __uint_as_float(w.w << 16), __uint_as_float(w.w & 0xFFFF0000u)};
;                         ss += ((q0[0] * q0[0] + q0[1] * q0[1]) + (q0[2] * q0[2] + q0[3] * q0[3])) + ((q1[0] * q1[0] + q1[1] * q1[1]) + (q1[2] * q1[2] + q1[3] * q1[3])); } }
;                 ss += __shfl_xor(ss, 16); ss += __shfl_xor(ss, 32);
;                 if (fq == 0) part[rl * 4 + wc] = ss;
.LBB0_927:
	v_add_u32_e32 v88, 0x80, v234
	v_add_u32_e32 v74, s21, v88
	s_waitcnt lgkmcnt(0)
	v_ashrrev_i32_e32 v75, 31, v74
	v_lshlrev_b64 v[74:75], 10, v[74:75]
	s_cmp_eq_u64 s[30:31], 0
	v_lshl_add_u64 v[86:87], v[222:223], 0, v[74:75]
	s_cbranch_scc1 .LBB0_945
	v_lshl_add_u64 v[74:75], v[86:87], 2, s[30:31]
	global_load_dwordx4 v[78:81], v[74:75], off offset:16
	s_nop 0
	global_load_dwordx4 v[74:77], v[74:75], off
	s_waitcnt vmcnt(0)
	s_cbranch_execnz .LBB0_930
.LBB0_929:
	v_lshlrev_b32_e32 v74, 16, v142
	v_and_b32_e32 v75, 0xffff0000, v142
	v_lshlrev_b32_e32 v76, 16, v143
	v_and_b32_e32 v77, 0xffff0000, v143
	v_lshlrev_b32_e32 v78, 16, v144
	v_and_b32_e32 v79, 0xffff0000, v144
	v_lshlrev_b32_e32 v80, 16, v145
	v_and_b32_e32 v81, 0xffff0000, v145
.LBB0_930:
	v_pk_add_f32 v[62:63], v[62:63], v[74:75]
	v_pk_add_f32 v[74:75], v[60:61], v[80:81]
	v_pk_add_f32 v[60:61], v[58:59], v[78:79]
	v_lshl_add_u64 v[78:79], v[86:87], 1, s[12:13]
	s_and_b64 vcc, exec, s[2:3]
	v_pk_add_f32 v[64:65], v[64:65], v[76:77]
	v_cvt_pk_bf16_f32 v58, v62, v63
	s_nop 0
	v_cvt_pk_bf16_f32 v59, v64, v65
	v_cvt_pk_bf16_f32 v60, v60, v61
	v_cvt_pk_bf16_f32 v61, v74, v75
	global_store_dwordx4 v[78:79], v[58:61], off
	s_cbranch_vccnz .LBB0_946
	v_lshl_add_u64 v[62:63], v[86:87], 2, s[8:9]
	global_load_dwordx4 v[74:77], v[62:63], off offset:528
	s_nop 0
	global_load_dwordx4 v[62:65], v[62:63], off offset:512
	s_waitcnt vmcnt(0)
	s_cbranch_execnz .LBB0_933
.LBB0_932:
	v_lshlrev_b32_e32 v62, 16, v130
	v_and_b32_e32 v63, 0xffff0000, v130
	v_lshlrev_b32_e32 v64, 16, v131
	v_and_b32_e32 v65, 0xffff0000, v131
	v_lshlrev_b32_e32 v74, 16, v132
	v_and_b32_e32 v75, 0xffff0000, v132
	v_lshlrev_b32_e32 v76, 16, v133
	v_and_b32_e32 v77, 0xffff0000, v133
.LBB0_933:
	v_lshlrev_b32_e32 v80, 16, v58
	v_and_b32_e32 v58, 0xffff0000, v58
	v_lshlrev_b32_e32 v81, 16, v59
	v_and_b32_e32 v59, 0xffff0000, v59
	v_mul_f32_e32 v58, v58, v58
	v_mul_f32_e32 v59, v59, v59
	v_lshlrev_b32_e32 v86, 16, v60
	v_and_b32_e32 v60, 0xffff0000, v60
	v_lshlrev_b32_e32 v87, 16, v61
	v_and_b32_e32 v61, 0xffff0000, v61
	v_fmac_f32_e32 v58, v80, v80
	v_fmac_f32_e32 v59, v81, v81
	v_add_f32_e32 v58, v58, v59
	v_mul_f32_e32 v59, v60, v60
	v_mul_f32_e32 v60, v61, v61
	v_fmac_f32_e32 v59, v86, v86
	v_fmac_f32_e32 v60, v87, v87
	v_add_f32_e32 v59, v59, v60
	v_pk_add_f32 v[54:55], v[54:55], v[62:63]
	v_pk_add_f32 v[50:51], v[50:51], v[74:75]
	v_add_f32_e32 v60, v58, v59
	v_pk_add_f32 v[56:57], v[56:57], v[64:65]
	v_pk_add_f32 v[58:59], v[52:53], v[76:77]
	v_cvt_pk_bf16_f32 v52, v54, v55
	v_cvt_pk_bf16_f32 v53, v56, v57
	v_cvt_pk_bf16_f32 v54, v50, v51
	s_nop 0
	v_and_b32_e32 v51, 0xffff0000, v52
	v_lshlrev_b32_e32 v50, 16, v52
	v_and_b32_e32 v57, 0xffff0000, v53
	v_mul_f32_e32 v51, v51, v51
	v_lshlrev_b32_e32 v56, 16, v53
	v_fmac_f32_e32 v51, v50, v50
	v_mul_f32_e32 v50, v57, v57
	v_cvt_pk_bf16_f32 v55, v58, v59
	v_and_b32_e32 v59, 0xffff0000, v54
	v_and_b32_e32 v62, 0xffff0000, v55
	v_fmac_f32_e32 v50, v56, v56
	v_lshlrev_b32_e32 v58, 16, v54
	v_lshlrev_b32_e32 v61, 16, v55
	v_add_f32_e32 v50, v51, v50
	v_mul_f32_e32 v51, v59, v59
	v_mul_f32_e32 v56, v62, v62
	v_fmac_f32_e32 v51, v58, v58
	v_fmac_f32_e32 v56, v61, v61
	v_add_f32_e32 v51, v51, v56
	v_add_f32_e32 v50, v50, v51
	v_add_f32_e32 v50, v60, v50
	ds_bpermute_b32 v51, v162, v50
	global_store_dwordx4 v[78:79], v[52:55], off offset:256
	s_waitcnt lgkmcnt(0)
	v_add_f32_e32 v50, v50, v51
	ds_bpermute_b32 v51, v163, v50
	s_and_saveexec_b64 s[30:31], s[4:5]
	s_cbranch_execz .LBB0_935
	v_lshl_add_u32 v52, v88, 4, s48
	s_waitcnt lgkmcnt(0)
	v_add_f32_e32 v50, v50, v51
	ds_write_b32 v52, v50
; __device__ __forceinline__ unsigned cvt_pk_bf16(float lo, float hi) { unsigned r; asm volatile("v_cvt_pk_bf16_f32 %0, %1, %2" : "=v"(r) : "v"(lo), "v"(hi)); return r; }
;     __device__ __forceinline__ void operator()(const f32x4 (&acc)[2][2][4][2], const Unit& u, int wr, int wc, int fr_in, int fq_in) const {
;     ...
;             for (int m = 0; m < 4; ++m) { const int rl = ai * HALF + wr * 64 + m * 16 + fr; const size_t off = (size_t)(u.pm * BM + rl) * ldc + col0;
;                 float ss = 0.f;
; #pragma unroll
;                 for (int bj = 0; bj < 2; ++bj) {
;                     f32x4 b0, b1;
;                     if (base32) { b0 = *(const f32x4*)(base32 + off + bj * HALF); b1 = *(const f32x4*)(base32 + off + bj * HALF + 4); }
;                     else { const u32x4 r = pre[ai][m][bj];
;                         b0 = (f32x4){__uint_as_float(r.x << 16), __uint_as_float(r.x & 0xFFFF0000u), __uint_as_float(r.y << 16), __uint_as_float(r.y & 0xFFFF0000u)};
;                         b1 = (f32x4){__uint_as_float(r.z << 16), __uint_as_float(r.z & 0xFFFF0000u), __uint_as_float(r.w << 16), __uint_as_float(r.w & 0xFFFF0000u)}; }
;                     const f32x4 v0 = b0 + acc[ai][bj][m][0], v1 = b1 + acc[ai][bj][m][1];
;                     if (out32) { *(f32x4*)(out32 + off + bj * HALF) = v0; *(f32x4*)(out32 + off + bj * HALF + 4) = v1; }
;                     if (XB) { u32x4 w; w.x = cvt_pk_bf16(v0[0], v0[1]); w.y = cvt_pk_bf16(v0[2], v0[3]); w.z = cvt_pk_bf16(v1[0], v1[1]); w.w = cvt_pk_bf16(v1[2], v1[3]); *(u32x4*)(XB + off + bj * HALF) = w;
;                         const f32x4 q0 = (f32x4){__uint_as_float(w.x << 16), __uint_as_float(w.x & 0xFFFF0000u), __uint_as_float(w.y << 16), __uint_as_float(w.y & 0xFFFF0000u)};
;                         const f32x4 q1 = (f32x4){__uint_as_float(w.z << 16), __uint_as_float(w.z & 0xFFFF0000u), __uint_as_float(w.w << 16), __uint_as_float(w.w & 0xFFFF0000u)};
;                         ss += ((q0[0] * q0[0] + q0[1] * q0[1]) + (q0[2] * q0[2] + q0[3] * q0[3])) + ((q1[0] * q1[0] + q1[1] * q1[1]) + (q1[2] * q1[2] + q1[3] * q1[3])); } }
;                 ss += __shfl_xor(ss, 16); ss += __shfl_xor(ss, 32);
;                 if (fq == 0) part[rl * 4 + wc] = ss;
.LBB0_935:
	s_or_b64 exec, exec, s[30:31]
	v_add_u32_e32 v62, 0x90, v234
	v_add_u32_e32 v50, s21, v62
	s_waitcnt lgkmcnt(0)
	v_ashrrev_i32_e32 v51, 31, v50
	v_lshlrev_b64 v[50:51], 10, v[50:51]
	v_lshl_add_u64 v[60:61], v[222:223], 0, v[50:51]
	s_and_b64 vcc, exec, s[2:3]
	v_lshl_add_u64 v[58:59], v[60:61], 2, s[8:9]
	s_cbranch_vccnz .LBB0_947
	global_load_dwordx4 v[54:57], v[58:59], off offset:16
	global_load_dwordx4 v[50:53], v[58:59], off
	s_waitcnt vmcnt(0)
	s_cbranch_execnz .LBB0_938
.LBB0_937:
	v_lshlrev_b32_e32 v50, 16, v118
	v_and_b32_e32 v51, 0xffff0000, v118
	v_lshlrev_b32_e32 v52, 16, v119
	v_and_b32_e32 v53, 0xffff0000, v119
	v_lshlrev_b32_e32 v54, 16, v120
	v_and_b32_e32 v55, 0xffff0000, v120
	v_lshlrev_b32_e32 v56, 16, v121
	v_and_b32_e32 v57, 0xffff0000, v121
.LBB0_938:
	v_pk_add_f32 v[46:47], v[46:47], v[50:51]
	v_pk_add_f32 v[50:51], v[44:45], v[56:57]
	v_pk_add_f32 v[44:45], v[42:43], v[54:55]
	v_lshl_add_u64 v[54:55], v[60:61], 1, s[12:13]
	s_and_b64 vcc, exec, s[2:3]
	v_pk_add_f32 v[48:49], v[48:49], v[52:53]
	v_cvt_pk_bf16_f32 v42, v46, v47
	s_nop 0
	v_cvt_pk_bf16_f32 v43, v48, v49
	v_cvt_pk_bf16_f32 v44, v44, v45
	v_cvt_pk_bf16_f32 v45, v50, v51
	global_store_dwordx4 v[54:55], v[42:45], off
	s_cbranch_vccnz .LBB0_948
	global_load_dwordx4 v[50:53], v[58:59], off offset:528
	global_load_dwordx4 v[46:49], v[58:59], off offset:512
	s_waitcnt vmcnt(0)
	s_cbranch_execnz .LBB0_941
.LBB0_940:
	v_lshlrev_b32_e32 v46, 16, v106
	v_and_b32_e32 v47, 0xffff0000, v106
	v_lshlrev_b32_e32 v48, 16, v107
	v_and_b32_e32 v49, 0xffff0000, v107
	v_lshlrev_b32_e32 v50, 16, v108
	v_and_b32_e32 v51, 0xffff0000, v108
	v_lshlrev_b32_e32 v52, 16, v109
	v_and_b32_e32 v53, 0xffff0000, v109
.LBB0_941:
	v_lshlrev_b32_e32 v56, 16, v42
	v_and_b32_e32 v42, 0xffff0000, v42
	v_lshlrev_b32_e32 v57, 16, v43
	v_and_b32_e32 v43, 0xffff0000, v43
	v_mul_f32_e32 v42, v42, v42
	v_mul_f32_e32 v43, v43, v43
	v_lshlrev_b32_e32 v58, 16, v44
	v_and_b32_e32 v44, 0xffff0000, v44
	v_lshlrev_b32_e32 v59, 16, v45
	v_and_b32_e32 v45, 0xffff0000, v45
	v_fmac_f32_e32 v42, v56, v56
	v_fmac_f32_e32 v43, v57, v57
	v_add_f32_e32 v42, v42, v43
	v_mul_f32_e32 v43, v44, v44
	v_mul_f32_e32 v44, v45, v45
	v_fmac_f32_e32 v43, v58, v58
	v_fmac_f32_e32 v44, v59, v59
	v_add_f32_e32 v43, v43, v44
	v_pk_add_f32 v[38:39], v[38:39], v[46:47]
	v_pk_add_f32 v[34:35], v[34:35], v[50:51]
	v_add_f32_e32 v44, v42, v43
	v_pk_add_f32 v[40:41], v[40:41], v[48:49]
	v_pk_add_f32 v[42:43], v[36:37], v[52:53]
	v_cvt_pk_bf16_f32 v36, v38, v39
	v_cvt_pk_bf16_f32 v37, v40, v41
	v_cvt_pk_bf16_f32 v38, v34, v35
	s_nop 0
	v_and_b32_e32 v35, 0xffff0000, v36
	v_lshlrev_b32_e32 v34, 16, v36
	v_and_b32_e32 v41, 0xffff0000, v37
	v_mul_f32_e32 v35, v35, v35
	v_lshlrev_b32_e32 v40, 16, v37
	v_fmac_f32_e32 v35, v34, v34
	v_mul_f32_e32 v34, v41, v41
	v_cvt_pk_bf16_f32 v39, v42, v43
	v_and_b32_e32 v43, 0xffff0000, v38
	v_and_b32_e32 v46, 0xffff0000, v39
	v_fmac_f32_e32 v34, v40, v40
	v_lshlrev_b32_e32 v42, 16, v38
	v_lshlrev_b32_e32 v45, 16, v39
	v_add_f32_e32 v34, v35, v34
	v_mul_f32_e32 v35, v43, v43
	v_mul_f32_e32 v40, v46, v46
	v_fmac_f32_e32 v35, v42, v42
	v_fmac_f32_e32 v40, v45, v45
	v_add_f32_e32 v35, v35, v40
	v_add_f32_e32 v34, v34, v35
	v_add_f32_e32 v34, v44, v34
	ds_bpermute_b32 v35, v162, v34
	global_store_dwordx4 v[54:55], v[36:39], off offset:256
	s_waitcnt lgkmcnt(0)
	v_add_f32_e32 v34, v34, v35
	ds_bpermute_b32 v35, v163, v34
	s_and_saveexec_b64 s[30:31], s[4:5]
	s_cbranch_execz .LBB0_943
	v_lshl_add_u32 v36, v62, 4, s48
	s_waitcnt lgkmcnt(0)
	v_add_f32_e32 v34, v34, v35
	ds_write_b32 v36, v34

; __device__ __forceinline__ unsigned cvt_pk_bf16(float lo, float hi) { unsigned r; asm volatile("v_cvt_pk_bf16_f32 %0, %1, %2" : "=v"(r) : "v"(lo), "v"(hi)); return r; }
;     __device__ __forceinline__ void operator()(const f32x4 (&acc)[2][2][4][2], const Unit& u, int wr, int wc, int fr_in, int fq_in) const {
;     ...
;             for (int m = 0; m < 4; ++m) { const int rl = ai * HALF + wr * 64 + m * 16 + fr; const size_t off = (size_t)(u.pm * BM + rl) * ldc + col0;
;                 float ss = 0.f;
; #pragma unroll
;                 for (int bj = 0; bj < 2; ++bj) {
;                     f32x4 b0, b1;
;                     if (base32) { b0 = *(const f32x4*)(base32 + off + bj * HALF); b1 = *(const f32x4*)(base32 + off + bj * HALF + 4); }
;                     else { const u32x4 r = pre[ai][m][bj];
;                         b0 = (f32x4){__uint_as_float(r.x << 16), __uint_as_float(r.x & 0xFFFF0000u), __uint_as_float(r.y << 16), __uint_as_float(r.y & 0xFFFF0000u)};
;                         b1 = (f32x4){__uint_as_float(r.z << 16), __uint_as_float(r.z & 0xFFFF0000u), __uint_as_float(r.w << 16), __uint_as_float(r.w & 0xFFFF0000u)}; }
;                     const f32x4 v0 = b0 + acc[ai][bj][m][0], v1 = b1 + acc[ai][bj][m][1];
;                     if (out32) { *(f32x4*)(out32 + off + bj * HALF) = v0; *(f32x4*)(out32 + off + bj * HALF + 4) = v1; }
;                     if (XB) { u32x4 w; w.x = cvt_pk_bf16(v0[0], v0[1]); w.y = cvt_pk_bf16(v0[2], v0[3]); w.z = cvt_pk_bf16(v1[0], v1[1]); w.w = cvt_pk_bf16(v1[2], v1[3]); *(u32x4*)(XB + off + bj * HALF) = w;
;                         const f32x4 q0 = (f32x4){__uint_as_float(w.x << 16), __uint_as_float(w.x & 0xFFFF0000u), __uint_as_float(w.y << 16), __uint_as_float(w.y & 0xFFFF0000u)};
;                         const f32x4 q1 = (f32x4){__uint_as_float(w.z << 16), __uint_as_float(w.z & 0xFFFF0000u), __uint_as_float(w.w << 16), __uint_as_float(w.w & 0xFFFF0000u)};
;                         ss += ((q0[0] * q0[0] + q0[1] * q0[1]) + (q0[2] * q0[2] + q0[3] * q0[3])) + ((q1[0] * q1[0] + q1[1] * q1[1]) + (q1[2] * q1[2] + q1[3] * q1[3])); } }
;                 ss += __shfl_xor(ss, 16); ss += __shfl_xor(ss, 32);
;                 if (fq == 0) part[rl * 4 + wc] = ss;
.LBB0_950:
	v_add_u32_e32 v44, 0xa0, v234
	v_add_u32_e32 v34, s21, v44
	s_waitcnt lgkmcnt(0)
	v_ashrrev_i32_e32 v35, 31, v34
	v_lshlrev_b64 v[34:35], 10, v[34:35]
	s_cmp_eq_u64 s[30:31], 0
	v_lshl_add_u64 v[42:43], v[222:223], 0, v[34:35]
	s_cbranch_scc1 .LBB0_973
	v_lshl_add_u64 v[34:35], v[42:43], 2, s[30:31]
	global_load_dwordx4 v[38:41], v[34:35], off offset:16
	s_nop 0
	global_load_dwordx4 v[34:37], v[34:35], off
	s_waitcnt vmcnt(0)
	s_cbranch_execnz .LBB0_953
.LBB0_952:
	v_lshlrev_b32_e32 v34, 16, v94
	v_and_b32_e32 v35, 0xffff0000, v94
	v_lshlrev_b32_e32 v36, 16, v95
	v_and_b32_e32 v37, 0xffff0000, v95
	v_lshlrev_b32_e32 v38, 16, v96
	v_and_b32_e32 v39, 0xffff0000, v96
	v_lshlrev_b32_e32 v40, 16, v97
	v_and_b32_e32 v41, 0xffff0000, v97
.LBB0_953:
	v_pk_add_f32 v[30:31], v[30:31], v[34:35]
	v_pk_add_f32 v[34:35], v[28:29], v[40:41]
	v_pk_add_f32 v[28:29], v[26:27], v[38:39]
	v_lshl_add_u64 v[38:39], v[42:43], 1, s[12:13]
	s_and_b64 vcc, exec, s[2:3]
	v_pk_add_f32 v[32:33], v[32:33], v[36:37]
	v_cvt_pk_bf16_f32 v26, v30, v31
	s_nop 0
	v_cvt_pk_bf16_f32 v27, v32, v33
	v_cvt_pk_bf16_f32 v28, v28, v29
	v_cvt_pk_bf16_f32 v29, v34, v35
	global_store_dwordx4 v[38:39], v[26:29], off
	s_cbranch_vccnz .LBB0_974
	v_lshl_add_u64 v[30:31], v[42:43], 2, s[8:9]
	global_load_dwordx4 v[34:37], v[30:31], off offset:528
	s_nop 0
	global_load_dwordx4 v[30:33], v[30:31], off offset:512
	s_waitcnt vmcnt(0)
	s_cbranch_execnz .LBB0_956
.LBB0_955:
	v_lshlrev_b32_e32 v30, 16, v82
	v_and_b32_e32 v31, 0xffff0000, v82
	v_lshlrev_b32_e32 v32, 16, v83
	v_and_b32_e32 v33, 0xffff0000, v83
	v_lshlrev_b32_e32 v34, 16, v84
	v_and_b32_e32 v35, 0xffff0000, v84
	v_lshlrev_b32_e32 v36, 16, v85
	v_and_b32_e32 v37, 0xffff0000, v85
.LBB0_956:
	v_lshlrev_b32_e32 v40, 16, v26
	v_and_b32_e32 v26, 0xffff0000, v26
	v_lshlrev_b32_e32 v41, 16, v27
	v_and_b32_e32 v27, 0xffff0000, v27
	v_mul_f32_e32 v26, v26, v26
	v_mul_f32_e32 v27, v27, v27
	v_lshlrev_b32_e32 v42, 16, v28
	v_and_b32_e32 v28, 0xffff0000, v28
	v_lshlrev_b32_e32 v43, 16, v29
	v_and_b32_e32 v29, 0xffff0000, v29
	v_fmac_f32_e32 v26, v40, v40
	v_fmac_f32_e32 v27, v41, v41
	v_add_f32_e32 v26, v26, v27
	v_mul_f32_e32 v27, v28, v28
	v_mul_f32_e32 v28, v29, v29
	v_fmac_f32_e32 v27, v42, v42
	v_fmac_f32_e32 v28, v43, v43
	v_add_f32_e32 v27, v27, v28
	v_pk_add_f32 v[22:23], v[22:23], v[30:31]
	v_pk_add_f32 v[18:19], v[18:19], v[34:35]
	v_add_f32_e32 v28, v26, v27
	v_pk_add_f32 v[24:25], v[24:25], v[32:33]
	v_pk_add_f32 v[26:27], v[20:21], v[36:37]
	v_cvt_pk_bf16_f32 v20, v22, v23
	v_cvt_pk_bf16_f32 v21, v24, v25
	v_cvt_pk_bf16_f32 v22, v18, v19
	s_nop 0
	v_and_b32_e32 v19, 0xffff0000, v20
	v_lshlrev_b32_e32 v18, 16, v20
	v_and_b32_e32 v25, 0xffff0000, v21
	v_mul_f32_e32 v19, v19, v19
	v_lshlrev_b32_e32 v24, 16, v21
	v_fmac_f32_e32 v19, v18, v18
	v_mul_f32_e32 v18, v25, v25
	v_cvt_pk_bf16_f32 v23, v26, v27
	v_and_b32_e32 v27, 0xffff0000, v22
	v_and_b32_e32 v30, 0xffff0000, v23
	v_fmac_f32_e32 v18, v24, v24
	v_lshlrev_b32_e32 v26, 16, v22
	v_lshlrev_b32_e32 v29, 16, v23
	v_add_f32_e32 v18, v19, v18
	v_mul_f32_e32 v19, v27, v27
	v_mul_f32_e32 v24, v30, v30
	v_fmac_f32_e32 v19, v26, v26
	v_fmac_f32_e32 v24, v29, v29
	v_add_f32_e32 v19, v19, v24
	v_add_f32_e32 v18, v18, v19
	v_add_f32_e32 v18, v28, v18
	ds_bpermute_b32 v19, v162, v18
	global_store_dwordx4 v[38:39], v[20:23], off offset:256
	s_waitcnt lgkmcnt(0)
	v_add_f32_e32 v18, v18, v19
	ds_bpermute_b32 v19, v163, v18
	s_and_saveexec_b64 s[30:31], s[4:5]
	s_cbranch_execz .LBB0_958
	v_lshl_add_u32 v20, v44, 4, s48
	s_waitcnt lgkmcnt(0)
	v_add_f32_e32 v18, v18, v19
	ds_write_b32 v20, v18
; __device__ __forceinline__ unsigned cvt_pk_bf16(float lo, float hi) { unsigned r; asm volatile("v_cvt_pk_bf16_f32 %0, %1, %2" : "=v"(r) : "v"(lo), "v"(hi)); return r; }
;     __device__ __forceinline__ void operator()(const f32x4 (&acc)[2][2][4][2], const Unit& u, int wr, int wc, int fr_in, int fq_in) const {
;     ...
;             for (int m = 0; m < 4; ++m) { const int rl = ai * HALF + wr * 64 + m * 16 + fr; const size_t off = (size_t)(u.pm * BM + rl) * ldc + col0;
;                 float ss = 0.f;
; #pragma unroll
;                 for (int bj = 0; bj < 2; ++bj) {
;                     f32x4 b0, b1;
;                     if (base32) { b0 = *(const f32x4*)(base32 + off + bj * HALF); b1 = *(const f32x4*)(base32 + off + bj * HALF + 4); }
;                     else { const u32x4 r = pre[ai][m][bj];
;                         b0 = (f32x4){__uint_as_float(r.x << 16), __uint_as_float(r.x & 0xFFFF0000u), __uint_as_float(r.y << 16), __uint_as_float(r.y & 0xFFFF0000u)};
;                         b1 = (f32x4){__uint_as_float(r.z << 16), __uint_as_float(r.z & 0xFFFF0000u), __uint_as_float(r.w << 16), __uint_as_float(r.w & 0xFFFF0000u)}; }
;                     const f32x4 v0 = b0 + acc[ai][bj][m][0], v1 = b1 + acc[ai][bj][m][1];
;                     if (out32) { *(f32x4*)(out32 + off + bj * HALF) = v0; *(f32x4*)(out32 + off + bj * HALF + 4) = v1; }
;                     if (XB) { u32x4 w; w.x = cvt_pk_bf16(v0[0], v0[1]); w.y = cvt_pk_bf16(v0[2], v0[3]); w.z = cvt_pk_bf16(v1[0], v1[1]); w.w = cvt_pk_bf16(v1[2], v1[3]); *(u32x4*)(XB + off + bj * HALF) = w;
;                         const f32x4 q0 = (f32x4){__uint_as_float(w.x << 16), __uint_as_float(w.x & 0xFFFF0000u), __uint_as_float(w.y << 16), __uint_as_float(w.y & 0xFFFF0000u)};
;                         const f32x4 q1 = (f32x4){__uint_as_float(w.z << 16), __uint_as_float(w.z & 0xFFFF0000u), __uint_as_float(w.w << 16), __uint_as_float(w.w & 0xFFFF0000u)};
;                         ss += ((q0[0] * q0[0] + q0[1] * q0[1]) + (q0[2] * q0[2] + q0[3] * q0[3])) + ((q1[0] * q1[0] + q1[1] * q1[1]) + (q1[2] * q1[2] + q1[3] * q1[3])); } }
;                 ss += __shfl_xor(ss, 16); ss += __shfl_xor(ss, 32);
;                 if (fq == 0) part[rl * 4 + wc] = ss;
.LBB0_958:
	s_or_b64 exec, exec, s[30:31]
	v_add_u32_e32 v30, 0xb0, v234
	v_add_u32_e32 v18, s21, v30
	s_waitcnt lgkmcnt(0)
	v_ashrrev_i32_e32 v19, 31, v18
	v_lshlrev_b64 v[18:19], 10, v[18:19]
	v_lshl_add_u64 v[28:29], v[222:223], 0, v[18:19]
	s_and_b64 vcc, exec, s[2:3]
	v_lshl_add_u64 v[26:27], v[28:29], 2, s[8:9]
	s_cbranch_vccnz .LBB0_975
	global_load_dwordx4 v[22:25], v[26:27], off offset:16
	global_load_dwordx4 v[18:21], v[26:27], off
	s_waitcnt vmcnt(0)
	s_cbranch_execnz .LBB0_961
.LBB0_960:
	v_lshlrev_b32_e32 v18, 16, v70
	v_and_b32_e32 v19, 0xffff0000, v70
	v_lshlrev_b32_e32 v20, 16, v71
	v_and_b32_e32 v21, 0xffff0000, v71
	v_lshlrev_b32_e32 v22, 16, v72
	v_and_b32_e32 v23, 0xffff0000, v72
	v_lshlrev_b32_e32 v24, 16, v73
	v_and_b32_e32 v25, 0xffff0000, v73
.LBB0_961:
	v_pk_add_f32 v[14:15], v[14:15], v[18:19]
	v_pk_add_f32 v[18:19], v[12:13], v[24:25]
	v_pk_add_f32 v[12:13], v[10:11], v[22:23]
	v_lshl_add_u64 v[22:23], v[28:29], 1, s[12:13]
	s_and_b64 vcc, exec, s[2:3]
	v_pk_add_f32 v[16:17], v[16:17], v[20:21]
	v_cvt_pk_bf16_f32 v10, v14, v15
	s_nop 0
	v_cvt_pk_bf16_f32 v11, v16, v17
	v_cvt_pk_bf16_f32 v12, v12, v13
	v_cvt_pk_bf16_f32 v13, v18, v19
	global_store_dwordx4 v[22:23], v[10:13], off
	s_cbranch_vccnz .LBB0_976
	global_load_dwordx4 v[18:21], v[26:27], off offset:528
	global_load_dwordx4 v[14:17], v[26:27], off offset:512
	s_waitcnt vmcnt(0)
	s_cbranch_execnz .LBB0_964
.LBB0_963:
	v_lshlrev_b32_e32 v14, 16, v66
	v_and_b32_e32 v15, 0xffff0000, v66
	v_lshlrev_b32_e32 v16, 16, v67
	v_and_b32_e32 v17, 0xffff0000, v67
	v_lshlrev_b32_e32 v18, 16, v68
	v_and_b32_e32 v19, 0xffff0000, v68
	v_lshlrev_b32_e32 v20, 16, v69
	v_and_b32_e32 v21, 0xffff0000, v69
.LBB0_964:
	v_lshlrev_b32_e32 v24, 16, v10
	v_and_b32_e32 v10, 0xffff0000, v10
	v_lshlrev_b32_e32 v25, 16, v11
	v_and_b32_e32 v11, 0xffff0000, v11
	v_mul_f32_e32 v10, v10, v10
	v_mul_f32_e32 v11, v11, v11
	v_lshlrev_b32_e32 v26, 16, v12
	v_and_b32_e32 v12, 0xffff0000, v12
	v_lshlrev_b32_e32 v27, 16, v13
	v_and_b32_e32 v13, 0xffff0000, v13
	v_fmac_f32_e32 v10, v24, v24
	v_fmac_f32_e32 v11, v25, v25
	v_add_f32_e32 v10, v10, v11
	v_mul_f32_e32 v11, v12, v12
	v_mul_f32_e32 v12, v13, v13
	v_fmac_f32_e32 v11, v26, v26
	v_fmac_f32_e32 v12, v27, v27
	v_add_f32_e32 v11, v11, v12
	v_pk_add_f32 v[6:7], v[6:7], v[14:15]
	v_pk_add_f32 v[2:3], v[2:3], v[18:19]
	v_add_f32_e32 v12, v10, v11
	v_pk_add_f32 v[8:9], v[8:9], v[16:17]
	v_pk_add_f32 v[10:11], v[4:5], v[20:21]
	v_cvt_pk_bf16_f32 v4, v6, v7
	v_cvt_pk_bf16_f32 v5, v8, v9
	v_cvt_pk_bf16_f32 v6, v2, v3
	s_nop 0
	v_and_b32_e32 v3, 0xffff0000, v4
	v_lshlrev_b32_e32 v2, 16, v4
	v_and_b32_e32 v9, 0xffff0000, v5
	v_mul_f32_e32 v3, v3, v3
	v_lshlrev_b32_e32 v8, 16, v5
	v_fmac_f32_e32 v3, v2, v2
	v_mul_f32_e32 v2, v9, v9
	v_cvt_pk_bf16_f32 v7, v10, v11
	v_and_b32_e32 v11, 0xffff0000, v6
	v_and_b32_e32 v14, 0xffff0000, v7
	v_fmac_f32_e32 v2, v8, v8
	v_lshlrev_b32_e32 v10, 16, v6
	v_lshlrev_b32_e32 v13, 16, v7
	v_add_f32_e32 v2, v3, v2
	v_mul_f32_e32 v3, v11, v11
	v_mul_f32_e32 v8, v14, v14
	v_fmac_f32_e32 v3, v10, v10
	v_fmac_f32_e32 v8, v13, v13
	v_add_f32_e32 v3, v3, v8
	v_add_f32_e32 v2, v2, v3
	v_add_f32_e32 v2, v12, v2
	ds_bpermute_b32 v3, v162, v2
	global_store_dwordx4 v[22:23], v[4:7], off offset:256
	s_waitcnt lgkmcnt(0)
	v_add_f32_e32 v2, v2, v3
	ds_bpermute_b32 v3, v163, v2
	s_and_saveexec_b64 s[30:31], s[4:5]
	s_cbranch_execz .LBB0_966
	v_lshl_add_u32 v4, v30, 4, s48
	s_waitcnt lgkmcnt(0)
	v_add_f32_e32 v2, v2, v3
	ds_write_b32 v4, v2

; #define PG8_STAGE(bufoff, gbase, voff) do { _Pragma("unroll") for (int _i = 0; _i < 2; ++_i) \
;         __builtin_amdgcn_global_load_lds((const unsigned*)((const char*)(gbase) + (voff)[_i]), (PG8_LAS unsigned*)(lds + (bufoff) + ldsw + _i * 8192), 16, 0, 0); } while (0)
; #define PG8_LDA(dst, b, h) do { _Pragma("unroll") for (int m = 0; m < 4; ++m) _Pragma("unroll") for (int k = 0; k < 2; ++k) dst[m][k] = *(const PG8_LAS bf16x8*)(lds + PG8_SA(b, h) + aoff + m * 2048 + k * 1024); } while (0)
; #define PG8_LDB(dst, b, h) do { _Pragma("unroll") for (int n = 0; n < 2; ++n) _Pragma("unroll") for (int k = 0; k < 2; ++k) dst[n][k] = *(const PG8_LAS bf16x8*)(lds + PG8_SB(b, h) + boff + n * 2048 + k * 1024); } while (0)
; #define PG8_MMA(ai, bj, At, Bt) do { __builtin_amdgcn_s_setprio(1); _Pragma("unroll") for (int m = 0; m < 4; ++m) _Pragma("unroll") for (int n = 0; n < 2; ++n) _Pragma("unroll") for (int k = 0; k < 2; ++k) \
;         acc[ai][bj][m][n] = __builtin_amdgcn_mfma_f32_16x16x32_bf16(Bt[n][k], At[m][k], acc[ai][bj][m][n], 0, 0, 0); __builtin_amdgcn_s_setprio(0); } while (0)
; template <class Epi, class Sched, bool ALIGN_EPI = false, bool SP2 = false>
; __device__ __forceinline__ void gemm_phase(PG8_LAS unsigned char* lds, const Gemm g, const Sched& S, const Epi& E, const int wave_s) {
;     ...
;             if constexpr (SP2) {
;             PG8_LDB(B0, 0, 0); PG8_LDB(B1, 0, 1); PG8_SCHED; PG8_LDA(At, 0, 0); PG8_STAGE(PG8_SA(1, 1), a1 + hstep, voffA);
;             PG8_WAIT_V(8); PG8_WAIT_L(0); PG8_BAR; PG8_MMA(0, 0, At, B0); PG8_MMA(0, 1, At, B1); PG8_BAR; PG8_SCHED;
;             PG8_LDA(At, 0, 1); PG8_STAGE(PG8_SB(0, 0), b2, voffB); PG8_STAGE(PG8_SB(0, 1), b2 + hstep, voffB); PG8_STAGE(PG8_SA(0, 0), a2, voffA);
;             PG8_WAIT_V(8); PG8_WAIT_L(0); PG8_BAR; PG8_MMA(1, 0, At, B0); PG8_MMA(1, 1, At, B1); PG8_BAR; PG8_SCHED;
;             PG8_LDB(B0, 1, 0); PG8_LDB(B1, 1, 1); PG8_SCHED; PG8_LDA(At, 1, 0); PG8_STAGE(PG8_SA(0, 1), a2 + hstep, voffA);
;             PG8_WAIT_V(8); PG8_WAIT_L(0); PG8_BAR; PG8_MMA(0, 0, At, B0); PG8_MMA(0, 1, At, B1); PG8_BAR; PG8_SCHED;
;             PG8_LDA(At, 1, 1); PG8_STAGE(PG8_SB(1, 0), b3, voffB); PG8_STAGE(PG8_SB(1, 1), b3 + hstep, voffB); PG8_STAGE(PG8_SA(1, 0), a3, voffA);
;             PG8_WAIT_V(8); PG8_WAIT_L(0); PG8_BAR; PG8_MMA(1, 0, At, B0); PG8_MMA(1, 1, At, B1); PG8_BAR; PG8_SCHED;
.LBB0_1041:
	s_add_u32 s6, s4, 0xfffc0080
	s_addc_u32 s7, s5, -1
	s_add_i32 s43, 0, 0x10000
	s_cmp_eq_u32 s42, 12
	s_cselect_b32 s11, s12, s7
	s_cselect_b32 s10, s13, s6
	v_add_u32_e32 v0, s43, v243
	s_cselect_b32 s7, s31, s41
	s_cselect_b32 s6, s35, s40
	s_add_i32 s73, 0, 0x14000
	ds_read_b128 v[82:85], v0
	ds_read_b128 v[86:89], v0 offset:1024
	ds_read_b128 v[90:93], v0 offset:2048
	ds_read_b128 v[94:97], v0 offset:3072
	v_add_u32_e32 v0, s73, v243
	ds_read_b128 v[98:101], v0
	ds_read_b128 v[102:105], v0 offset:1024
	ds_read_b128 v[106:109], v0 offset:2048
	ds_read_b128 v[110:113], v0 offset:3072
	v_lshl_add_u64 v[202:203], s[4:5], 0, v[190:191]
	s_add_i32 m0, s50, 0xc000
	ds_read_b128 v[154:157], v244
	ds_read_b128 v[166:169], v244 offset:1024
	ds_read_b128 v[170:173], v244 offset:2048
	ds_read_b128 v[174:177], v244 offset:3072
	ds_read_b128 v[178:181], v244 offset:4096
	ds_read_b128 v[194:197], v244 offset:5120
	ds_read_b128 v[198:201], v244 offset:6144
	ds_read_b128 v[204:207], v244 offset:7168
	global_load_lds_dwordx4 v[202:203], off
	v_lshl_add_u64 v[202:203], s[4:5], 0, v[192:193]
	s_add_i32 m0, s50, 0xe000
	s_nop 0
	global_load_lds_dwordx4 v[202:203], off
	s_waitcnt vmcnt(8)
	s_waitcnt lgkmcnt(0)
	s_setprio 1
	s_barrier
	v_mfma_f32_16x16x32_bf16 v[162:165], v[82:85], v[154:157], v[162:165]
	v_mfma_f32_16x16x32_bf16 v[158:161], v[90:93], v[154:157], v[158:161]
	v_mfma_f32_16x16x32_bf16 v[134:137], v[82:85], v[170:173], v[134:137]
	v_mfma_f32_16x16x32_bf16 v[38:41], v[90:93], v[170:173], v[38:41]
	v_mfma_f32_16x16x32_bf16 v[130:133], v[82:85], v[178:181], v[130:133]
	v_mfma_f32_16x16x32_bf16 v[34:37], v[90:93], v[178:181], v[34:37]
	v_mfma_f32_16x16x32_bf16 v[150:153], v[82:85], v[198:201], v[150:153]
	v_mfma_f32_16x16x32_bf16 v[54:57], v[90:93], v[198:201], v[54:57]
	v_mfma_f32_16x16x32_bf16 v[162:165], v[86:89], v[166:169], v[162:165]
	v_mfma_f32_16x16x32_bf16 v[158:161], v[94:97], v[166:169], v[158:161]
	v_mfma_f32_16x16x32_bf16 v[134:137], v[86:89], v[174:177], v[134:137]
	v_mfma_f32_16x16x32_bf16 v[38:41], v[94:97], v[174:177], v[38:41]
	v_mfma_f32_16x16x32_bf16 v[130:133], v[86:89], v[194:197], v[130:133]
	v_mfma_f32_16x16x32_bf16 v[34:37], v[94:97], v[194:197], v[34:37]
	v_mfma_f32_16x16x32_bf16 v[150:153], v[86:89], v[204:207], v[150:153]
	v_mfma_f32_16x16x32_bf16 v[54:57], v[94:97], v[204:207], v[54:57]
	v_mfma_f32_16x16x32_bf16 v[146:149], v[98:101], v[154:157], v[146:149]
	v_mfma_f32_16x16x32_bf16 v[114:117], v[106:109], v[154:157], v[114:117]
	v_mfma_f32_16x16x32_bf16 v[126:129], v[98:101], v[170:173], v[126:129]
	v_mfma_f32_16x16x32_bf16 v[30:33], v[106:109], v[170:173], v[30:33]
	v_mfma_f32_16x16x32_bf16 v[122:125], v[98:101], v[178:181], v[122:125]
	v_mfma_f32_16x16x32_bf16 v[26:29], v[106:109], v[178:181], v[26:29]
	v_mfma_f32_16x16x32_bf16 v[142:145], v[98:101], v[198:201], v[142:145]
	v_mfma_f32_16x16x32_bf16 v[50:53], v[106:109], v[198:201], v[50:53]
	v_mfma_f32_16x16x32_bf16 v[146:149], v[102:105], v[166:169], v[146:149]
	v_mfma_f32_16x16x32_bf16 v[114:117], v[110:113], v[166:169], v[114:117]
	v_mfma_f32_16x16x32_bf16 v[126:129], v[102:105], v[174:177], v[126:129]
	v_mfma_f32_16x16x32_bf16 v[30:33], v[110:113], v[174:177], v[30:33]
	v_mfma_f32_16x16x32_bf16 v[122:125], v[102:105], v[194:197], v[122:125]
	v_mfma_f32_16x16x32_bf16 v[26:29], v[110:113], v[194:197], v[26:29]
	v_mfma_f32_16x16x32_bf16 v[142:145], v[102:105], v[204:207], v[142:145]
	v_mfma_f32_16x16x32_bf16 v[50:53], v[110:113], v[204:207], v[50:53]
	s_barrier
	s_setprio 0
	s_add_i32 s43, s43, s47
	v_lshl_add_u64 v[202:203], s[6:7], 0, v[186:187]
	s_mov_b32 m0, s43
	ds_read_b128 v[154:157], v244 offset:16384
	ds_read_b128 v[166:169], v244 offset:17408
	ds_read_b128 v[170:173], v244 offset:18432
	ds_read_b128 v[174:177], v244 offset:19456
	ds_read_b128 v[178:181], v244 offset:20480
	ds_read_b128 v[194:197], v244 offset:21504
	ds_read_b128 v[198:201], v244 offset:22528
	ds_read_b128 v[204:207], v244 offset:23552
	global_load_lds_dwordx4 v[202:203], off
	s_add_i32 m0, s43, 0x2000
	s_add_u32 s44, s6, 0x40000
	v_lshl_add_u64 v[212:213], s[6:7], 0, v[182:183]
	s_addc_u32 s45, s7, 0
	s_add_i32 s43, s73, s47
	global_load_lds_dwordx4 v[212:213], off
	v_lshl_add_u64 v[208:209], s[44:45], 0, v[186:187]
	s_mov_b32 m0, s43
	v_lshl_add_u64 v[214:215], s[10:11], 0, v[188:189]
	global_load_lds_dwordx4 v[208:209], off
	v_lshl_add_u64 v[208:209], s[44:45], 0, v[182:183]
	s_add_i32 m0, s43, 0x2000
	v_lshl_add_u64 v[216:217], s[10:11], 0, v[184:185]
	global_load_lds_dwordx4 v[208:209], off
	s_mov_b32 m0, s50
	s_nop 0
	global_load_lds_dwordx4 v[214:215], off
	s_mov_b32 m0, s51
	s_nop 0
	global_load_lds_dwordx4 v[216:217], off
	s_waitcnt vmcnt(8)
	s_waitcnt lgkmcnt(0)
	s_setprio 1
	s_barrier
; #define PG8_STAGE(bufoff, gbase, voff) do { _Pragma("unroll") for (int _i = 0; _i < 2; ++_i) \
;         __builtin_amdgcn_global_load_lds((const unsigned*)((const char*)(gbase) + (voff)[_i]), (PG8_LAS unsigned*)(lds + (bufoff) + ldsw + _i * 8192), 16, 0, 0); } while (0)
; #define PG8_LDA(dst, b, h) do { _Pragma("unroll") for (int m = 0; m < 4; ++m) _Pragma("unroll") for (int k = 0; k < 2; ++k) dst[m][k] = *(const PG8_LAS bf16x8*)(lds + PG8_SA(b, h) + aoff + m * 2048 + k * 1024); } while (0)
; #define PG8_LDB(dst, b, h) do { _Pragma("unroll") for (int n = 0; n < 2; ++n) _Pragma("unroll") for (int k = 0; k < 2; ++k) dst[n][k] = *(const PG8_LAS bf16x8*)(lds + PG8_SB(b, h) + boff + n * 2048 + k * 1024); } while (0)
; #define PG8_MMA(ai, bj, At, Bt) do { __builtin_amdgcn_s_setprio(1); _Pragma("unroll") for (int m = 0; m < 4; ++m) _Pragma("unroll") for (int n = 0; n < 2; ++n) _Pragma("unroll") for (int k = 0; k < 2; ++k) \
;         acc[ai][bj][m][n] = __builtin_amdgcn_mfma_f32_16x16x32_bf16(Bt[n][k], At[m][k], acc[ai][bj][m][n], 0, 0, 0); __builtin_amdgcn_s_setprio(0); } while (0)
; template <class Epi, class Sched, bool ALIGN_EPI = false, bool SP2 = false>
; __device__ __forceinline__ void gemm_phase(PG8_LAS unsigned char* lds, const Gemm g, const Sched& S, const Epi& E, const int wave_s) {
;     ...
;             if constexpr (SP2) {
;             PG8_LDB(B0, 0, 0); PG8_LDB(B1, 0, 1); PG8_SCHED; PG8_LDA(At, 0, 0); PG8_STAGE(PG8_SA(1, 1), a1 + hstep, voffA);
;             PG8_WAIT_V(8); PG8_WAIT_L(0); PG8_BAR; PG8_MMA(0, 0, At, B0); PG8_MMA(0, 1, At, B1); PG8_BAR; PG8_SCHED;
;             PG8_LDA(At, 0, 1); PG8_STAGE(PG8_SB(0, 0), b2, voffB); PG8_STAGE(PG8_SB(0, 1), b2 + hstep, voffB); PG8_STAGE(PG8_SA(0, 0), a2, voffA);
;             PG8_WAIT_V(8); PG8_WAIT_L(0); PG8_BAR; PG8_MMA(1, 0, At, B0); PG8_MMA(1, 1, At, B1); PG8_BAR; PG8_SCHED;
;             PG8_LDB(B0, 1, 0); PG8_LDB(B1, 1, 1); PG8_SCHED; PG8_LDA(At, 1, 0); PG8_STAGE(PG8_SA(0, 1), a2 + hstep, voffA);
;             PG8_WAIT_V(8); PG8_WAIT_L(0); PG8_BAR; PG8_MMA(0, 0, At, B0); PG8_MMA(0, 1, At, B1); PG8_BAR; PG8_SCHED;
;             PG8_LDA(At, 1, 1); PG8_STAGE(PG8_SB(1, 0), b3, voffB); PG8_STAGE(PG8_SB(1, 1), b3 + hstep, voffB); PG8_STAGE(PG8_SA(1, 0), a3, voffA);
;             PG8_WAIT_V(8); PG8_WAIT_L(0); PG8_BAR; PG8_MMA(1, 0, At, B0); PG8_MMA(1, 1, At, B1); PG8_BAR; PG8_SCHED;
	v_mfma_f32_16x16x32_bf16 v[78:81], v[82:85], v[154:157], v[78:81]
	v_mfma_f32_16x16x32_bf16 v[22:25], v[90:93], v[154:157], v[22:25]
	v_mfma_f32_16x16x32_bf16 v[74:77], v[82:85], v[170:173], v[74:77]
	v_mfma_f32_16x16x32_bf16 v[18:21], v[90:93], v[170:173], v[18:21]
	v_mfma_f32_16x16x32_bf16 v[66:69], v[82:85], v[178:181], v[66:69]
	v_mfma_f32_16x16x32_bf16 v[14:17], v[90:93], v[178:181], v[14:17]
	v_mfma_f32_16x16x32_bf16 v[46:49], v[90:93], v[198:201], v[46:49]
	v_mfma_f32_16x16x32_bf16 v[78:81], v[86:89], v[166:169], v[78:81]
	v_mfma_f32_16x16x32_bf16 v[22:25], v[94:97], v[166:169], v[22:25]
	v_mfma_f32_16x16x32_bf16 v[74:77], v[86:89], v[174:177], v[74:77]
	v_mfma_f32_16x16x32_bf16 v[18:21], v[94:97], v[174:177], v[18:21]
	v_mfma_f32_16x16x32_bf16 v[66:69], v[86:89], v[194:197], v[66:69]
	v_mfma_f32_16x16x32_bf16 v[14:17], v[94:97], v[194:197], v[14:17]
	v_mfma_f32_16x16x32_bf16 v[82:85], v[82:85], v[198:201], v[138:141]
	v_mfma_f32_16x16x32_bf16 v[46:49], v[94:97], v[204:207], v[46:49]
	v_mfma_f32_16x16x32_bf16 v[82:85], v[86:89], v[204:207], v[82:85]
	v_mfma_f32_16x16x32_bf16 v[70:73], v[98:101], v[154:157], v[70:73]
	v_mfma_f32_16x16x32_bf16 v[10:13], v[106:109], v[154:157], v[10:13]
	v_mfma_f32_16x16x32_bf16 v[62:65], v[98:101], v[170:173], v[62:65]
	v_mfma_f32_16x16x32_bf16 v[6:9], v[106:109], v[170:173], v[6:9]
	v_mfma_f32_16x16x32_bf16 v[58:61], v[98:101], v[178:181], v[58:61]
	v_mfma_f32_16x16x32_bf16 v[2:5], v[106:109], v[178:181], v[2:5]
	v_mfma_f32_16x16x32_bf16 v[42:45], v[106:109], v[198:201], v[42:45]
	v_mfma_f32_16x16x32_bf16 v[70:73], v[102:105], v[166:169], v[70:73]
	v_mfma_f32_16x16x32_bf16 v[10:13], v[110:113], v[166:169], v[10:13]
	v_mfma_f32_16x16x32_bf16 v[62:65], v[102:105], v[174:177], v[62:65]
	v_mfma_f32_16x16x32_bf16 v[6:9], v[110:113], v[174:177], v[6:9]
	v_mfma_f32_16x16x32_bf16 v[58:61], v[102:105], v[194:197], v[58:61]
	v_mfma_f32_16x16x32_bf16 v[2:5], v[110:113], v[194:197], v[2:5]
	v_mfma_f32_16x16x32_bf16 v[86:89], v[98:101], v[198:201], v[118:121]
	v_mfma_f32_16x16x32_bf16 v[42:45], v[110:113], v[204:207], v[42:45]
	v_mfma_f32_16x16x32_bf16 v[86:89], v[102:105], v[204:207], v[86:89]
	s_barrier
	s_setprio 0
	s_add_i32 s43, 0, 0x18000
	v_add_u32_e32 v0, s43, v243
	s_add_i32 s44, 0, 0x1c000
	ds_read_b128 v[90:93], v0
	ds_read_b128 v[94:97], v0 offset:1024
	ds_read_b128 v[98:101], v0 offset:2048
	ds_read_b128 v[102:105], v0 offset:3072
	v_add_u32_e32 v0, s44, v243
	ds_read_b128 v[106:109], v0
	ds_read_b128 v[110:113], v0 offset:1024
	ds_read_b128 v[154:157], v0 offset:2048
	ds_read_b128 v[166:169], v0 offset:3072
	s_add_u32 s10, s10, 0x40000
	s_addc_u32 s11, s11, 0
	s_mov_b32 m0, s52
	v_lshl_add_u64 v[208:209], s[10:11], 0, v[188:189]
	ds_read_b128 v[118:121], v244 offset:32768
	ds_read_b128 v[138:141], v244 offset:33792
	ds_read_b128 v[170:173], v244 offset:34816
	ds_read_b128 v[174:177], v244 offset:35840
	ds_read_b128 v[178:181], v244 offset:36864
	ds_read_b128 v[194:197], v244 offset:37888
	ds_read_b128 v[198:201], v244 offset:38912
	ds_read_b128 v[204:207], v244 offset:39936
	global_load_lds_dwordx4 v[208:209], off
	v_lshl_add_u64 v[208:209], s[10:11], 0, v[184:185]
	s_mov_b32 m0, s53
	s_nop 0
	global_load_lds_dwordx4 v[208:209], off
	s_waitcnt vmcnt(8)
	s_waitcnt lgkmcnt(0)
	s_setprio 1
	s_barrier
	v_mfma_f32_16x16x32_bf16 v[162:165], v[90:93], v[118:121], v[162:165]
	v_mfma_f32_16x16x32_bf16 v[158:161], v[98:101], v[118:121], v[158:161]
	v_mfma_f32_16x16x32_bf16 v[134:137], v[90:93], v[170:173], v[134:137]
	v_mfma_f32_16x16x32_bf16 v[38:41], v[98:101], v[170:173], v[38:41]
	v_mfma_f32_16x16x32_bf16 v[130:133], v[90:93], v[178:181], v[130:133]
	v_mfma_f32_16x16x32_bf16 v[34:37], v[98:101], v[178:181], v[34:37]
	v_mfma_f32_16x16x32_bf16 v[150:153], v[90:93], v[198:201], v[150:153]
	v_mfma_f32_16x16x32_bf16 v[54:57], v[98:101], v[198:201], v[54:57]
	v_mfma_f32_16x16x32_bf16 v[162:165], v[94:97], v[138:141], v[162:165]
	v_mfma_f32_16x16x32_bf16 v[158:161], v[102:105], v[138:141], v[158:161]
	v_mfma_f32_16x16x32_bf16 v[134:137], v[94:97], v[174:177], v[134:137]
	v_mfma_f32_16x16x32_bf16 v[38:41], v[102:105], v[174:177], v[38:41]
	v_mfma_f32_16x16x32_bf16 v[130:133], v[94:97], v[194:197], v[130:133]
	v_mfma_f32_16x16x32_bf16 v[34:37], v[102:105], v[194:197], v[34:37]
	v_mfma_f32_16x16x32_bf16 v[150:153], v[94:97], v[204:207], v[150:153]
	v_mfma_f32_16x16x32_bf16 v[54:57], v[102:105], v[204:207], v[54:57]
	v_mfma_f32_16x16x32_bf16 v[146:149], v[106:109], v[118:121], v[146:149]
	v_mfma_f32_16x16x32_bf16 v[114:117], v[154:157], v[118:121], v[114:117]
	v_mfma_f32_16x16x32_bf16 v[118:121], v[106:109], v[170:173], v[126:129]
	v_mfma_f32_16x16x32_bf16 v[126:129], v[110:113], v[174:177], v[118:121]
	v_mfma_f32_16x16x32_bf16 v[118:121], v[106:109], v[178:181], v[122:125]
	v_mfma_f32_16x16x32_bf16 v[30:33], v[154:157], v[170:173], v[30:33]
	v_mfma_f32_16x16x32_bf16 v[122:125], v[110:113], v[194:197], v[118:121]
	v_mfma_f32_16x16x32_bf16 v[26:29], v[154:157], v[178:181], v[26:29]
	v_mfma_f32_16x16x32_bf16 v[118:121], v[106:109], v[198:201], v[142:145]
	v_mfma_f32_16x16x32_bf16 v[50:53], v[154:157], v[198:201], v[50:53]
	v_mfma_f32_16x16x32_bf16 v[146:149], v[110:113], v[138:141], v[146:149]
	v_mfma_f32_16x16x32_bf16 v[114:117], v[166:169], v[138:141], v[114:117]
	v_mfma_f32_16x16x32_bf16 v[30:33], v[166:169], v[174:177], v[30:33]
	v_mfma_f32_16x16x32_bf16 v[26:29], v[166:169], v[194:197], v[26:29]
	v_mfma_f32_16x16x32_bf16 v[142:145], v[110:113], v[204:207], v[118:121]
	v_mfma_f32_16x16x32_bf16 v[50:53], v[166:169], v[204:207], v[50:53]
	s_barrier
; #define PG8_STAGE(bufoff, gbase, voff) do { _Pragma("unroll") for (int _i = 0; _i < 2; ++_i) \
;         __builtin_amdgcn_global_load_lds((const unsigned*)((const char*)(gbase) + (voff)[_i]), (PG8_LAS unsigned*)(lds + (bufoff) + ldsw + _i * 8192), 16, 0, 0); } while (0)
; #define PG8_LDA(dst, b, h) do { _Pragma("unroll") for (int m = 0; m < 4; ++m) _Pragma("unroll") for (int k = 0; k < 2; ++k) dst[m][k] = *(const PG8_LAS bf16x8*)(lds + PG8_SA(b, h) + aoff + m * 2048 + k * 1024); } while (0)
; #define PG8_LDB(dst, b, h) do { _Pragma("unroll") for (int n = 0; n < 2; ++n) _Pragma("unroll") for (int k = 0; k < 2; ++k) dst[n][k] = *(const PG8_LAS bf16x8*)(lds + PG8_SB(b, h) + boff + n * 2048 + k * 1024); } while (0)
; #define PG8_MMA(ai, bj, At, Bt) do { __builtin_amdgcn_s_setprio(1); _Pragma("unroll") for (int m = 0; m < 4; ++m) _Pragma("unroll") for (int n = 0; n < 2; ++n) _Pragma("unroll") for (int k = 0; k < 2; ++k) \
;         acc[ai][bj][m][n] = __builtin_amdgcn_mfma_f32_16x16x32_bf16(Bt[n][k], At[m][k], acc[ai][bj][m][n], 0, 0, 0); __builtin_amdgcn_s_setprio(0); } while (0)
; template <class Epi, class Sched, bool ALIGN_EPI = false, bool SP2 = false>
; __device__ __forceinline__ void gemm_phase(PG8_LAS unsigned char* lds, const Gemm g, const Sched& S, const Epi& E, const int wave_s) {
;     ...
;             if constexpr (SP2) {
;             PG8_LDB(B0, 0, 0); PG8_LDB(B1, 0, 1); PG8_SCHED; PG8_LDA(At, 0, 0); PG8_STAGE(PG8_SA(1, 1), a1 + hstep, voffA);
;             PG8_WAIT_V(8); PG8_WAIT_L(0); PG8_BAR; PG8_MMA(0, 0, At, B0); PG8_MMA(0, 1, At, B1); PG8_BAR; PG8_SCHED;
;             PG8_LDA(At, 0, 1); PG8_STAGE(PG8_SB(0, 0), b2, voffB); PG8_STAGE(PG8_SB(0, 1), b2 + hstep, voffB); PG8_STAGE(PG8_SA(0, 0), a2, voffA);
;             PG8_WAIT_V(8); PG8_WAIT_L(0); PG8_BAR; PG8_MMA(1, 0, At, B0); PG8_MMA(1, 1, At, B1); PG8_BAR; PG8_SCHED;
;             PG8_LDB(B0, 1, 0); PG8_LDB(B1, 1, 1); PG8_SCHED; PG8_LDA(At, 1, 0); PG8_STAGE(PG8_SA(0, 1), a2 + hstep, voffA);
;             PG8_WAIT_V(8); PG8_WAIT_L(0); PG8_BAR; PG8_MMA(0, 0, At, B0); PG8_MMA(0, 1, At, B1); PG8_BAR; PG8_SCHED;
;             PG8_LDA(At, 1, 1); PG8_STAGE(PG8_SB(1, 0), b3, voffB); PG8_STAGE(PG8_SB(1, 1), b3 + hstep, voffB); PG8_STAGE(PG8_SA(1, 0), a3, voffA);
;             PG8_WAIT_V(8); PG8_WAIT_L(0); PG8_BAR; PG8_MMA(1, 0, At, B0); PG8_MMA(1, 1, At, B1); PG8_BAR; PG8_SCHED;
	s_setprio 0
	s_add_i32 s10, s43, s47
	v_lshl_add_u64 v[138:139], v[202:203], 0, s[86:87]
	s_mov_b32 m0, s10
	ds_read_b128 v[118:121], v244 offset:49152
	ds_read_b128 v[170:173], v244 offset:50176
	ds_read_b128 v[174:177], v244 offset:51200
	ds_read_b128 v[178:181], v244 offset:52224
	ds_read_b128 v[194:197], v244 offset:53248
	ds_read_b128 v[198:201], v244 offset:54272
	ds_read_b128 v[204:207], v244 offset:55296
	ds_read_b128 v[208:211], v244 offset:56320
	global_load_lds_dwordx4 v[138:139], off
	s_add_i32 m0, s10, 0x2000
	s_add_u32 s6, s6, 0x40080
	v_lshl_add_u64 v[138:139], v[212:213], 0, s[86:87]
	s_addc_u32 s7, s7, 0
	s_add_i32 s10, s44, s47
	global_load_lds_dwordx4 v[138:139], off
	v_lshl_add_u64 v[138:139], s[6:7], 0, v[186:187]
	s_mov_b32 m0, s10
	s_nop 0
	global_load_lds_dwordx4 v[138:139], off
	v_lshl_add_u64 v[138:139], s[6:7], 0, v[182:183]
	s_add_i32 m0, s10, 0x2000
	s_nop 0
	global_load_lds_dwordx4 v[138:139], off
	v_lshl_add_u64 v[138:139], v[214:215], 0, s[86:87]
	s_mov_b32 m0, s57
	s_nop 0
	global_load_lds_dwordx4 v[138:139], off
	v_lshl_add_u64 v[138:139], v[216:217], 0, s[86:87]
	s_mov_b32 m0, s58
	s_nop 0
	global_load_lds_dwordx4 v[138:139], off
	s_waitcnt vmcnt(8)
	s_waitcnt lgkmcnt(0)
	s_setprio 1
	s_barrier
	v_mfma_f32_16x16x32_bf16 v[78:81], v[90:93], v[118:121], v[78:81]
	v_mfma_f32_16x16x32_bf16 v[22:25], v[98:101], v[118:121], v[22:25]
	v_mfma_f32_16x16x32_bf16 v[74:77], v[90:93], v[174:177], v[74:77]
	v_mfma_f32_16x16x32_bf16 v[18:21], v[98:101], v[174:177], v[18:21]
	v_mfma_f32_16x16x32_bf16 v[66:69], v[90:93], v[194:197], v[66:69]
	v_mfma_f32_16x16x32_bf16 v[14:17], v[98:101], v[194:197], v[14:17]
	v_mfma_f32_16x16x32_bf16 v[82:85], v[90:93], v[204:207], v[82:85]
	v_mfma_f32_16x16x32_bf16 v[46:49], v[98:101], v[204:207], v[46:49]
	v_mfma_f32_16x16x32_bf16 v[78:81], v[94:97], v[170:173], v[78:81]
	v_mfma_f32_16x16x32_bf16 v[22:25], v[102:105], v[170:173], v[22:25]
	v_mfma_f32_16x16x32_bf16 v[74:77], v[94:97], v[178:181], v[74:77]
	v_mfma_f32_16x16x32_bf16 v[18:21], v[102:105], v[178:181], v[18:21]
	v_mfma_f32_16x16x32_bf16 v[66:69], v[94:97], v[198:201], v[66:69]
	v_mfma_f32_16x16x32_bf16 v[14:17], v[102:105], v[198:201], v[14:17]
	v_mfma_f32_16x16x32_bf16 v[138:141], v[94:97], v[208:211], v[82:85]
	v_mfma_f32_16x16x32_bf16 v[46:49], v[102:105], v[208:211], v[46:49]
	v_mfma_f32_16x16x32_bf16 v[70:73], v[106:109], v[118:121], v[70:73]
	v_mfma_f32_16x16x32_bf16 v[10:13], v[154:157], v[118:121], v[10:13]
	v_mfma_f32_16x16x32_bf16 v[62:65], v[106:109], v[174:177], v[62:65]
	v_mfma_f32_16x16x32_bf16 v[6:9], v[154:157], v[174:177], v[6:9]
	v_mfma_f32_16x16x32_bf16 v[58:61], v[106:109], v[194:197], v[58:61]
	v_mfma_f32_16x16x32_bf16 v[2:5], v[154:157], v[194:197], v[2:5]
	v_mfma_f32_16x16x32_bf16 v[82:85], v[106:109], v[204:207], v[86:89]
	v_mfma_f32_16x16x32_bf16 v[42:45], v[154:157], v[204:207], v[42:45]
	v_mfma_f32_16x16x32_bf16 v[70:73], v[110:113], v[170:173], v[70:73]
	v_mfma_f32_16x16x32_bf16 v[10:13], v[166:169], v[170:173], v[10:13]
	v_mfma_f32_16x16x32_bf16 v[62:65], v[110:113], v[178:181], v[62:65]
	v_mfma_f32_16x16x32_bf16 v[6:9], v[166:169], v[178:181], v[6:9]
	v_mfma_f32_16x16x32_bf16 v[58:61], v[110:113], v[198:201], v[58:61]
	v_mfma_f32_16x16x32_bf16 v[2:5], v[166:169], v[198:201], v[2:5]
	v_mfma_f32_16x16x32_bf16 v[118:121], v[110:113], v[208:211], v[82:85]
	v_mfma_f32_16x16x32_bf16 v[42:45], v[166:169], v[208:211], v[42:45]
	s_barrier
	s_setprio 0
	s_add_i32 s42, s42, 2
	s_add_u32 s4, s4, 0x100
	s_addc_u32 s5, s5, 0
	s_add_u32 s40, s40, 0x100
	s_addc_u32 s41, s41, 0
	s_cmp_gt_u32 s42, 13
	s_cbranch_scc0 .LBB0_1041
	s_and_b64 vcc, exec, s[28:29]
	s_cbranch_vccz .LBB0_1044
	s_barrier

; #define PG8_STAGE(bufoff, gbase, voff) do { _Pragma("unroll") for (int _i = 0; _i < 2; ++_i) \
;         __builtin_amdgcn_global_load_lds((const unsigned*)((const char*)(gbase) + (voff)[_i]), (PG8_LAS unsigned*)(lds + (bufoff) + ldsw + _i * 8192), 16, 0, 0); } while (0)
; #define PG8_LDA(dst, b, h) do { _Pragma("unroll") for (int m = 0; m < 4; ++m) _Pragma("unroll") for (int k = 0; k < 2; ++k) dst[m][k] = *(const PG8_LAS bf16x8*)(lds + PG8_SA(b, h) + aoff + m * 2048 + k * 1024); } while (0)
; #define PG8_LDB(dst, b, h) do { _Pragma("unroll") for (int n = 0; n < 2; ++n) _Pragma("unroll") for (int k = 0; k < 2; ++k) dst[n][k] = *(const PG8_LAS bf16x8*)(lds + PG8_SB(b, h) + boff + n * 2048 + k * 1024); } while (0)
; #define PG8_MMA(ai, bj, At, Bt) do { __builtin_amdgcn_s_setprio(1); _Pragma("unroll") for (int m = 0; m < 4; ++m) _Pragma("unroll") for (int n = 0; n < 2; ++n) _Pragma("unroll") for (int k = 0; k < 2; ++k) \
;         acc[ai][bj][m][n] = __builtin_amdgcn_mfma_f32_16x16x32_bf16(Bt[n][k], At[m][k], acc[ai][bj][m][n], 0, 0, 0); __builtin_amdgcn_s_setprio(0); } while (0)
; template <class Epi, class Sched, bool ALIGN_EPI = false, bool SP2 = false>
; __device__ __forceinline__ void gemm_phase(PG8_LAS unsigned char* lds, const Gemm g, const Sched& S, const Epi& E, const int wave_s) {
;     ...
;             if constexpr (SP2) {
;             PG8_LDB(B0, 0, 0); PG8_LDB(B1, 0, 1); PG8_SCHED; PG8_LDA(At, 0, 0); PG8_STAGE(PG8_SA(1, 1), a1 + hstep, voffA);
;             PG8_WAIT_V(8); PG8_WAIT_L(0); PG8_BAR; PG8_MMA(0, 0, At, B0); PG8_MMA(0, 1, At, B1); PG8_BAR; PG8_SCHED;
;             PG8_LDA(At, 0, 1); PG8_STAGE(PG8_SB(0, 0), b2, voffB); PG8_STAGE(PG8_SB(0, 1), b2 + hstep, voffB); PG8_STAGE(PG8_SA(0, 0), a2, voffA);
;             PG8_WAIT_V(8); PG8_WAIT_L(0); PG8_BAR; PG8_MMA(1, 0, At, B0); PG8_MMA(1, 1, At, B1); PG8_BAR; PG8_SCHED;
;             PG8_LDB(B0, 1, 0); PG8_LDB(B1, 1, 1); PG8_SCHED; PG8_LDA(At, 1, 0); PG8_STAGE(PG8_SA(0, 1), a2 + hstep, voffA);
;             PG8_WAIT_V(8); PG8_WAIT_L(0); PG8_BAR; PG8_MMA(0, 0, At, B0); PG8_MMA(0, 1, At, B1); PG8_BAR; PG8_SCHED;
;             PG8_LDA(At, 1, 1); PG8_STAGE(PG8_SB(1, 0), b3, voffB); PG8_STAGE(PG8_SB(1, 1), b3 + hstep, voffB); PG8_STAGE(PG8_SA(1, 0), a3, voffA);
;             PG8_WAIT_V(8); PG8_WAIT_L(0); PG8_BAR; PG8_MMA(1, 0, At, B0); PG8_MMA(1, 1, At, B1); PG8_BAR; PG8_SCHED;
.LBB0_1174:
	s_add_u32 s4, s6, 0x100
	s_addc_u32 s5, s7, 0
	s_add_i32 s60, 0, 0x10000
	s_cmp_eq_u32 s59, 40
	s_cselect_b32 s39, s35, s5
	s_cselect_b32 s38, s34, s4
	s_cselect_b32 s9, s37, s58
	s_cselect_b32 s8, s36, s57
	s_add_i32 s61, 0, 0x14000
	v_add_u32_e32 v106, s60, v218
	v_add_u32_e32 v150, s61, v218
	ds_read_b128 v[74:77], v106
	ds_read_b128 v[86:89], v106 offset:1024
	ds_read_b128 v[98:101], v106 offset:2048
	ds_read_b128 v[106:109], v106 offset:3072
	ds_read_b128 v[122:125], v150
	ds_read_b128 v[126:129], v150 offset:1024
	ds_read_b128 v[142:145], v150 offset:2048
	ds_read_b128 v[150:153], v150 offset:3072
	v_lshl_add_u64 v[200:201], s[6:7], 0, v[196:197]
	s_add_i32 m0, s44, 0xc000
	ds_read_b128 v[162:165], v219
	ds_read_b128 v[166:169], v219 offset:1024
	ds_read_b128 v[170:173], v219 offset:2048
	ds_read_b128 v[174:177], v219 offset:3072
	ds_read_b128 v[178:181], v219 offset:4096
	ds_read_b128 v[182:185], v219 offset:5120
	ds_read_b128 v[186:189], v219 offset:6144
	ds_read_b128 v[204:207], v219 offset:7168
	global_load_lds_dwordx4 v[200:201], off
	v_lshl_add_u64 v[200:201], s[6:7], 0, v[198:199]
	s_add_i32 m0, s44, 0xe000
	s_nop 0
	global_load_lds_dwordx4 v[200:201], off
	s_waitcnt vmcnt(8)
	s_waitcnt lgkmcnt(0)
	s_setprio 1
	s_barrier
	v_mfma_f32_16x16x32_bf16 v[158:161], v[74:77], v[162:165], v[158:161]
	v_mfma_f32_16x16x32_bf16 v[154:157], v[98:101], v[162:165], v[154:157]
	v_mfma_f32_16x16x32_bf16 v[134:137], v[74:77], v[170:173], v[134:137]
	v_mfma_f32_16x16x32_bf16 v[130:133], v[98:101], v[170:173], v[130:133]
	v_mfma_f32_16x16x32_bf16 v[110:113], v[74:77], v[178:181], v[110:113]
	v_mfma_f32_16x16x32_bf16 v[102:105], v[98:101], v[178:181], v[102:105]
	v_mfma_f32_16x16x32_bf16 v[82:85], v[74:77], v[186:189], v[82:85]
	v_mfma_f32_16x16x32_bf16 v[78:81], v[98:101], v[186:189], v[78:81]
	v_mfma_f32_16x16x32_bf16 v[158:161], v[86:89], v[166:169], v[158:161]
	v_mfma_f32_16x16x32_bf16 v[154:157], v[106:109], v[166:169], v[154:157]
	v_mfma_f32_16x16x32_bf16 v[134:137], v[86:89], v[174:177], v[134:137]
	v_mfma_f32_16x16x32_bf16 v[130:133], v[106:109], v[174:177], v[130:133]
	v_mfma_f32_16x16x32_bf16 v[110:113], v[86:89], v[182:185], v[110:113]
	v_mfma_f32_16x16x32_bf16 v[102:105], v[106:109], v[182:185], v[102:105]
	v_mfma_f32_16x16x32_bf16 v[82:85], v[86:89], v[204:207], v[82:85]
	v_mfma_f32_16x16x32_bf16 v[78:81], v[106:109], v[204:207], v[78:81]
	v_mfma_f32_16x16x32_bf16 v[146:149], v[122:125], v[162:165], v[146:149]
	v_mfma_f32_16x16x32_bf16 v[138:141], v[142:145], v[162:165], v[138:141]
	v_mfma_f32_16x16x32_bf16 v[118:121], v[122:125], v[170:173], v[118:121]
	v_mfma_f32_16x16x32_bf16 v[114:117], v[142:145], v[170:173], v[114:117]
	v_mfma_f32_16x16x32_bf16 v[94:97], v[122:125], v[178:181], v[94:97]
	v_mfma_f32_16x16x32_bf16 v[90:93], v[142:145], v[178:181], v[90:93]
	v_mfma_f32_16x16x32_bf16 v[70:73], v[122:125], v[186:189], v[70:73]
	v_mfma_f32_16x16x32_bf16 v[66:69], v[142:145], v[186:189], v[66:69]
	v_mfma_f32_16x16x32_bf16 v[146:149], v[126:129], v[166:169], v[146:149]
	v_mfma_f32_16x16x32_bf16 v[138:141], v[150:153], v[166:169], v[138:141]
	v_mfma_f32_16x16x32_bf16 v[118:121], v[126:129], v[174:177], v[118:121]
	v_mfma_f32_16x16x32_bf16 v[114:117], v[150:153], v[174:177], v[114:117]
	v_mfma_f32_16x16x32_bf16 v[94:97], v[126:129], v[182:185], v[94:97]
	v_mfma_f32_16x16x32_bf16 v[90:93], v[150:153], v[182:185], v[90:93]
	v_mfma_f32_16x16x32_bf16 v[70:73], v[126:129], v[204:207], v[70:73]
	v_mfma_f32_16x16x32_bf16 v[66:69], v[150:153], v[204:207], v[66:69]
	s_barrier
	s_setprio 0
	s_add_i32 s6, s60, s33
	v_lshl_add_u64 v[200:201], s[8:9], 0, v[0:1]
	s_mov_b32 m0, s6
	ds_read_b128 v[162:165], v219 offset:16384
	ds_read_b128 v[166:169], v219 offset:17408
	ds_read_b128 v[170:173], v219 offset:18432
	ds_read_b128 v[174:177], v219 offset:19456
	ds_read_b128 v[178:181], v219 offset:20480
	ds_read_b128 v[182:185], v219 offset:21504
	ds_read_b128 v[186:189], v219 offset:22528
	ds_read_b128 v[204:207], v219 offset:23552
	global_load_lds_dwordx4 v[200:201], off
	s_add_i32 m0, s6, 0x2000
	s_add_u32 s6, s8, 0xb0000
	v_lshl_add_u64 v[202:203], s[8:9], 0, v[190:191]
	s_addc_u32 s7, s9, 0
	s_add_i32 s60, s61, s33
	global_load_lds_dwordx4 v[202:203], off
	v_lshl_add_u64 v[208:209], s[6:7], 0, v[0:1]
	s_mov_b32 m0, s60
	v_lshl_add_u64 v[210:211], s[38:39], 0, v[192:193]
	global_load_lds_dwordx4 v[208:209], off
	v_lshl_add_u64 v[208:209], s[6:7], 0, v[190:191]
	s_add_i32 m0, s60, 0x2000
	s_nop 0
	global_load_lds_dwordx4 v[208:209], off
	v_lshl_add_u64 v[208:209], s[38:39], 0, v[194:195]
	s_mov_b32 m0, s44
	s_nop 0
	global_load_lds_dwordx4 v[208:209], off
	s_mov_b32 m0, s45
	s_nop 0
	global_load_lds_dwordx4 v[210:211], off
	s_waitcnt vmcnt(8)
	s_waitcnt lgkmcnt(0)
	s_setprio 1
	s_barrier
; #define PG8_STAGE(bufoff, gbase, voff) do { _Pragma("unroll") for (int _i = 0; _i < 2; ++_i) \
;         __builtin_amdgcn_global_load_lds((const unsigned*)((const char*)(gbase) + (voff)[_i]), (PG8_LAS unsigned*)(lds + (bufoff) + ldsw + _i * 8192), 16, 0, 0); } while (0)
; #define PG8_LDA(dst, b, h) do { _Pragma("unroll") for (int m = 0; m < 4; ++m) _Pragma("unroll") for (int k = 0; k < 2; ++k) dst[m][k] = *(const PG8_LAS bf16x8*)(lds + PG8_SA(b, h) + aoff + m * 2048 + k * 1024); } while (0)
; #define PG8_LDB(dst, b, h) do { _Pragma("unroll") for (int n = 0; n < 2; ++n) _Pragma("unroll") for (int k = 0; k < 2; ++k) dst[n][k] = *(const PG8_LAS bf16x8*)(lds + PG8_SB(b, h) + boff + n * 2048 + k * 1024); } while (0)
; #define PG8_MMA(ai, bj, At, Bt) do { __builtin_amdgcn_s_setprio(1); _Pragma("unroll") for (int m = 0; m < 4; ++m) _Pragma("unroll") for (int n = 0; n < 2; ++n) _Pragma("unroll") for (int k = 0; k < 2; ++k) \
;         acc[ai][bj][m][n] = __builtin_amdgcn_mfma_f32_16x16x32_bf16(Bt[n][k], At[m][k], acc[ai][bj][m][n], 0, 0, 0); __builtin_amdgcn_s_setprio(0); } while (0)
; template <class Epi, class Sched, bool ALIGN_EPI = false, bool SP2 = false>
; __device__ __forceinline__ void gemm_phase(PG8_LAS unsigned char* lds, const Gemm g, const Sched& S, const Epi& E, const int wave_s) {
;     ...
;             if constexpr (SP2) {
;             PG8_LDB(B0, 0, 0); PG8_LDB(B1, 0, 1); PG8_SCHED; PG8_LDA(At, 0, 0); PG8_STAGE(PG8_SA(1, 1), a1 + hstep, voffA);
;             PG8_WAIT_V(8); PG8_WAIT_L(0); PG8_BAR; PG8_MMA(0, 0, At, B0); PG8_MMA(0, 1, At, B1); PG8_BAR; PG8_SCHED;
;             PG8_LDA(At, 0, 1); PG8_STAGE(PG8_SB(0, 0), b2, voffB); PG8_STAGE(PG8_SB(0, 1), b2 + hstep, voffB); PG8_STAGE(PG8_SA(0, 0), a2, voffA);
;             PG8_WAIT_V(8); PG8_WAIT_L(0); PG8_BAR; PG8_MMA(1, 0, At, B0); PG8_MMA(1, 1, At, B1); PG8_BAR; PG8_SCHED;
;             PG8_LDB(B0, 1, 0); PG8_LDB(B1, 1, 1); PG8_SCHED; PG8_LDA(At, 1, 0); PG8_STAGE(PG8_SA(0, 1), a2 + hstep, voffA);
;             PG8_WAIT_V(8); PG8_WAIT_L(0); PG8_BAR; PG8_MMA(0, 0, At, B0); PG8_MMA(0, 1, At, B1); PG8_BAR; PG8_SCHED;
;             PG8_LDA(At, 1, 1); PG8_STAGE(PG8_SB(1, 0), b3, voffB); PG8_STAGE(PG8_SB(1, 1), b3 + hstep, voffB); PG8_STAGE(PG8_SA(1, 0), a3, voffA);
;             PG8_WAIT_V(8); PG8_WAIT_L(0); PG8_BAR; PG8_MMA(1, 0, At, B0); PG8_MMA(1, 1, At, B1); PG8_BAR; PG8_SCHED;
	v_mfma_f32_16x16x32_bf16 v[62:65], v[74:77], v[162:165], v[62:65]
	v_mfma_f32_16x16x32_bf16 v[58:61], v[98:101], v[162:165], v[58:61]
	v_mfma_f32_16x16x32_bf16 v[46:49], v[74:77], v[170:173], v[46:49]
	v_mfma_f32_16x16x32_bf16 v[42:45], v[98:101], v[170:173], v[42:45]
	v_mfma_f32_16x16x32_bf16 v[30:33], v[74:77], v[178:181], v[30:33]
	v_mfma_f32_16x16x32_bf16 v[26:29], v[98:101], v[178:181], v[26:29]
	v_mfma_f32_16x16x32_bf16 v[14:17], v[74:77], v[186:189], v[14:17]
	v_mfma_f32_16x16x32_bf16 v[10:13], v[98:101], v[186:189], v[10:13]
	v_mfma_f32_16x16x32_bf16 v[62:65], v[86:89], v[166:169], v[62:65]
	v_mfma_f32_16x16x32_bf16 v[58:61], v[106:109], v[166:169], v[58:61]
	v_mfma_f32_16x16x32_bf16 v[46:49], v[86:89], v[174:177], v[46:49]
	v_mfma_f32_16x16x32_bf16 v[42:45], v[106:109], v[174:177], v[42:45]
	v_mfma_f32_16x16x32_bf16 v[30:33], v[86:89], v[182:185], v[30:33]
	v_mfma_f32_16x16x32_bf16 v[26:29], v[106:109], v[182:185], v[26:29]
	v_mfma_f32_16x16x32_bf16 v[14:17], v[86:89], v[204:207], v[14:17]
	v_mfma_f32_16x16x32_bf16 v[10:13], v[106:109], v[204:207], v[10:13]
	v_mfma_f32_16x16x32_bf16 v[54:57], v[122:125], v[162:165], v[54:57]
	v_mfma_f32_16x16x32_bf16 v[50:53], v[142:145], v[162:165], v[50:53]
	v_mfma_f32_16x16x32_bf16 v[38:41], v[122:125], v[170:173], v[38:41]
	v_mfma_f32_16x16x32_bf16 v[34:37], v[142:145], v[170:173], v[34:37]
	v_mfma_f32_16x16x32_bf16 v[22:25], v[122:125], v[178:181], v[22:25]
	v_mfma_f32_16x16x32_bf16 v[18:21], v[142:145], v[178:181], v[18:21]
	v_mfma_f32_16x16x32_bf16 v[6:9], v[122:125], v[186:189], v[6:9]
	v_mfma_f32_16x16x32_bf16 v[2:5], v[142:145], v[186:189], v[2:5]
	v_mfma_f32_16x16x32_bf16 v[54:57], v[126:129], v[166:169], v[54:57]
	v_mfma_f32_16x16x32_bf16 v[50:53], v[150:153], v[166:169], v[50:53]
	v_mfma_f32_16x16x32_bf16 v[38:41], v[126:129], v[174:177], v[38:41]
	v_mfma_f32_16x16x32_bf16 v[34:37], v[150:153], v[174:177], v[34:37]
	v_mfma_f32_16x16x32_bf16 v[22:25], v[126:129], v[182:185], v[22:25]
	v_mfma_f32_16x16x32_bf16 v[18:21], v[150:153], v[182:185], v[18:21]
	v_mfma_f32_16x16x32_bf16 v[6:9], v[126:129], v[204:207], v[6:9]
	v_mfma_f32_16x16x32_bf16 v[2:5], v[150:153], v[204:207], v[2:5]
	s_barrier
	s_setprio 0
	s_add_i32 s60, 0, 0x18000
	s_add_i32 s61, 0, 0x1c000
	v_add_u32_e32 v106, s60, v218
	v_add_u32_e32 v150, s61, v218
	ds_read_b128 v[74:77], v106
	ds_read_b128 v[86:89], v106 offset:1024
	ds_read_b128 v[98:101], v106 offset:2048
	ds_read_b128 v[106:109], v106 offset:3072
	ds_read_b128 v[122:125], v150
	ds_read_b128 v[126:129], v150 offset:1024
	ds_read_b128 v[142:145], v150 offset:2048
	ds_read_b128 v[150:153], v150 offset:3072
	s_add_u32 s6, s38, 0xb0000
	s_addc_u32 s7, s39, 0
	s_mov_b32 m0, s46
	v_lshl_add_u64 v[212:213], s[6:7], 0, v[194:195]
	ds_read_b128 v[162:165], v219 offset:32768
	ds_read_b128 v[166:169], v219 offset:33792
	ds_read_b128 v[170:173], v219 offset:34816
	ds_read_b128 v[174:177], v219 offset:35840
	ds_read_b128 v[178:181], v219 offset:36864
	ds_read_b128 v[182:185], v219 offset:37888
	ds_read_b128 v[186:189], v219 offset:38912
	ds_read_b128 v[204:207], v219 offset:39936
	global_load_lds_dwordx4 v[212:213], off
	v_lshl_add_u64 v[212:213], s[6:7], 0, v[192:193]
	s_mov_b32 m0, s47
	s_nop 0
	global_load_lds_dwordx4 v[212:213], off
	s_waitcnt vmcnt(8)
	s_waitcnt lgkmcnt(0)
	s_setprio 1
	s_barrier
	v_mfma_f32_16x16x32_bf16 v[158:161], v[74:77], v[162:165], v[158:161]
	v_mfma_f32_16x16x32_bf16 v[154:157], v[98:101], v[162:165], v[154:157]
	v_mfma_f32_16x16x32_bf16 v[134:137], v[74:77], v[170:173], v[134:137]
	v_mfma_f32_16x16x32_bf16 v[130:133], v[98:101], v[170:173], v[130:133]
	v_mfma_f32_16x16x32_bf16 v[110:113], v[74:77], v[178:181], v[110:113]
	v_mfma_f32_16x16x32_bf16 v[102:105], v[98:101], v[178:181], v[102:105]
	v_mfma_f32_16x16x32_bf16 v[82:85], v[74:77], v[186:189], v[82:85]
	v_mfma_f32_16x16x32_bf16 v[78:81], v[98:101], v[186:189], v[78:81]
	v_mfma_f32_16x16x32_bf16 v[158:161], v[86:89], v[166:169], v[158:161]
	v_mfma_f32_16x16x32_bf16 v[154:157], v[106:109], v[166:169], v[154:157]
	v_mfma_f32_16x16x32_bf16 v[134:137], v[86:89], v[174:177], v[134:137]
	v_mfma_f32_16x16x32_bf16 v[130:133], v[106:109], v[174:177], v[130:133]
	v_mfma_f32_16x16x32_bf16 v[110:113], v[86:89], v[182:185], v[110:113]
	v_mfma_f32_16x16x32_bf16 v[102:105], v[106:109], v[182:185], v[102:105]
	v_mfma_f32_16x16x32_bf16 v[82:85], v[86:89], v[204:207], v[82:85]
	v_mfma_f32_16x16x32_bf16 v[78:81], v[106:109], v[204:207], v[78:81]
	v_mfma_f32_16x16x32_bf16 v[146:149], v[122:125], v[162:165], v[146:149]
	v_mfma_f32_16x16x32_bf16 v[138:141], v[142:145], v[162:165], v[138:141]
	v_mfma_f32_16x16x32_bf16 v[118:121], v[122:125], v[170:173], v[118:121]
	v_mfma_f32_16x16x32_bf16 v[114:117], v[142:145], v[170:173], v[114:117]
	v_mfma_f32_16x16x32_bf16 v[94:97], v[122:125], v[178:181], v[94:97]
	v_mfma_f32_16x16x32_bf16 v[90:93], v[142:145], v[178:181], v[90:93]
	v_mfma_f32_16x16x32_bf16 v[70:73], v[122:125], v[186:189], v[70:73]
	v_mfma_f32_16x16x32_bf16 v[66:69], v[142:145], v[186:189], v[66:69]
	v_mfma_f32_16x16x32_bf16 v[146:149], v[126:129], v[166:169], v[146:149]
	v_mfma_f32_16x16x32_bf16 v[138:141], v[150:153], v[166:169], v[138:141]
	v_mfma_f32_16x16x32_bf16 v[118:121], v[126:129], v[174:177], v[118:121]
	v_mfma_f32_16x16x32_bf16 v[114:117], v[150:153], v[174:177], v[114:117]
	v_mfma_f32_16x16x32_bf16 v[94:97], v[126:129], v[182:185], v[94:97]
	v_mfma_f32_16x16x32_bf16 v[90:93], v[150:153], v[182:185], v[90:93]
	v_mfma_f32_16x16x32_bf16 v[70:73], v[126:129], v[204:207], v[70:73]
	v_mfma_f32_16x16x32_bf16 v[66:69], v[150:153], v[204:207], v[66:69]
	s_barrier
; #define PG8_STAGE(bufoff, gbase, voff) do { _Pragma("unroll") for (int _i = 0; _i < 2; ++_i) \
;         __builtin_amdgcn_global_load_lds((const unsigned*)((const char*)(gbase) + (voff)[_i]), (PG8_LAS unsigned*)(lds + (bufoff) + ldsw + _i * 8192), 16, 0, 0); } while (0)
; #define PG8_LDA(dst, b, h) do { _Pragma("unroll") for (int m = 0; m < 4; ++m) _Pragma("unroll") for (int k = 0; k < 2; ++k) dst[m][k] = *(const PG8_LAS bf16x8*)(lds + PG8_SA(b, h) + aoff + m * 2048 + k * 1024); } while (0)
; #define PG8_LDB(dst, b, h) do { _Pragma("unroll") for (int n = 0; n < 2; ++n) _Pragma("unroll") for (int k = 0; k < 2; ++k) dst[n][k] = *(const PG8_LAS bf16x8*)(lds + PG8_SB(b, h) + boff + n * 2048 + k * 1024); } while (0)
; #define PG8_MMA(ai, bj, At, Bt) do { __builtin_amdgcn_s_setprio(1); _Pragma("unroll") for (int m = 0; m < 4; ++m) _Pragma("unroll") for (int n = 0; n < 2; ++n) _Pragma("unroll") for (int k = 0; k < 2; ++k) \
;         acc[ai][bj][m][n] = __builtin_amdgcn_mfma_f32_16x16x32_bf16(Bt[n][k], At[m][k], acc[ai][bj][m][n], 0, 0, 0); __builtin_amdgcn_s_setprio(0); } while (0)
; template <class Epi, class Sched, bool ALIGN_EPI = false, bool SP2 = false>
; __device__ __forceinline__ void gemm_phase(PG8_LAS unsigned char* lds, const Gemm g, const Sched& S, const Epi& E, const int wave_s) {
;     ...
;             if constexpr (SP2) {
;             PG8_LDB(B0, 0, 0); PG8_LDB(B1, 0, 1); PG8_SCHED; PG8_LDA(At, 0, 0); PG8_STAGE(PG8_SA(1, 1), a1 + hstep, voffA);
;             PG8_WAIT_V(8); PG8_WAIT_L(0); PG8_BAR; PG8_MMA(0, 0, At, B0); PG8_MMA(0, 1, At, B1); PG8_BAR; PG8_SCHED;
;             PG8_LDA(At, 0, 1); PG8_STAGE(PG8_SB(0, 0), b2, voffB); PG8_STAGE(PG8_SB(0, 1), b2 + hstep, voffB); PG8_STAGE(PG8_SA(0, 0), a2, voffA);
;             PG8_WAIT_V(8); PG8_WAIT_L(0); PG8_BAR; PG8_MMA(1, 0, At, B0); PG8_MMA(1, 1, At, B1); PG8_BAR; PG8_SCHED;
;             PG8_LDB(B0, 1, 0); PG8_LDB(B1, 1, 1); PG8_SCHED; PG8_LDA(At, 1, 0); PG8_STAGE(PG8_SA(0, 1), a2 + hstep, voffA);
;             PG8_WAIT_V(8); PG8_WAIT_L(0); PG8_BAR; PG8_MMA(0, 0, At, B0); PG8_MMA(0, 1, At, B1); PG8_BAR; PG8_SCHED;
;             PG8_LDA(At, 1, 1); PG8_STAGE(PG8_SB(1, 0), b3, voffB); PG8_STAGE(PG8_SB(1, 1), b3 + hstep, voffB); PG8_STAGE(PG8_SA(1, 0), a3, voffA);
;             PG8_WAIT_V(8); PG8_WAIT_L(0); PG8_BAR; PG8_MMA(1, 0, At, B0); PG8_MMA(1, 1, At, B1); PG8_BAR; PG8_SCHED;
	s_setprio 0
	s_add_i32 s6, s60, s33
	v_lshl_add_u64 v[200:201], v[200:201], 0, s[86:87]
	s_mov_b32 m0, s6
	ds_read_b128 v[162:165], v219 offset:49152
	ds_read_b128 v[166:169], v219 offset:50176
	ds_read_b128 v[170:173], v219 offset:51200
	ds_read_b128 v[174:177], v219 offset:52224
	ds_read_b128 v[178:181], v219 offset:53248
	ds_read_b128 v[182:185], v219 offset:54272
	ds_read_b128 v[186:189], v219 offset:55296
	ds_read_b128 v[204:207], v219 offset:56320
	global_load_lds_dwordx4 v[200:201], off
	s_add_i32 m0, s6, 0x2000
	s_add_u32 s6, s8, 0xb0080
	v_lshl_add_u64 v[200:201], v[202:203], 0, s[86:87]
	s_addc_u32 s7, s9, 0
	s_add_i32 s8, s61, s33
	global_load_lds_dwordx4 v[200:201], off
	v_lshl_add_u64 v[200:201], s[6:7], 0, v[0:1]
	s_mov_b32 m0, s8
	s_nop 0
	global_load_lds_dwordx4 v[200:201], off
	v_lshl_add_u64 v[200:201], s[6:7], 0, v[190:191]
	s_add_i32 m0, s8, 0x2000
	s_nop 0
	global_load_lds_dwordx4 v[200:201], off
	v_lshl_add_u64 v[200:201], v[208:209], 0, s[86:87]
	s_mov_b32 m0, s51
	s_nop 0
	global_load_lds_dwordx4 v[200:201], off
	v_lshl_add_u64 v[200:201], v[210:211], 0, s[86:87]
	s_mov_b32 m0, s52
	s_nop 0
	global_load_lds_dwordx4 v[200:201], off
	s_waitcnt vmcnt(8)
	s_waitcnt lgkmcnt(0)
	s_setprio 1
	s_barrier
	v_mfma_f32_16x16x32_bf16 v[62:65], v[74:77], v[162:165], v[62:65]
	v_mfma_f32_16x16x32_bf16 v[58:61], v[98:101], v[162:165], v[58:61]
	v_mfma_f32_16x16x32_bf16 v[46:49], v[74:77], v[170:173], v[46:49]
	v_mfma_f32_16x16x32_bf16 v[42:45], v[98:101], v[170:173], v[42:45]
	v_mfma_f32_16x16x32_bf16 v[30:33], v[74:77], v[178:181], v[30:33]
	v_mfma_f32_16x16x32_bf16 v[26:29], v[98:101], v[178:181], v[26:29]
	v_mfma_f32_16x16x32_bf16 v[14:17], v[74:77], v[186:189], v[14:17]
	v_mfma_f32_16x16x32_bf16 v[10:13], v[98:101], v[186:189], v[10:13]
	v_mfma_f32_16x16x32_bf16 v[62:65], v[86:89], v[166:169], v[62:65]
	v_mfma_f32_16x16x32_bf16 v[58:61], v[106:109], v[166:169], v[58:61]
	v_mfma_f32_16x16x32_bf16 v[46:49], v[86:89], v[174:177], v[46:49]
	v_mfma_f32_16x16x32_bf16 v[42:45], v[106:109], v[174:177], v[42:45]
	v_mfma_f32_16x16x32_bf16 v[30:33], v[86:89], v[182:185], v[30:33]
	v_mfma_f32_16x16x32_bf16 v[26:29], v[106:109], v[182:185], v[26:29]
	v_mfma_f32_16x16x32_bf16 v[14:17], v[86:89], v[204:207], v[14:17]
	v_mfma_f32_16x16x32_bf16 v[10:13], v[106:109], v[204:207], v[10:13]
	v_mfma_f32_16x16x32_bf16 v[54:57], v[122:125], v[162:165], v[54:57]
	v_mfma_f32_16x16x32_bf16 v[50:53], v[142:145], v[162:165], v[50:53]
	v_mfma_f32_16x16x32_bf16 v[38:41], v[122:125], v[170:173], v[38:41]
	v_mfma_f32_16x16x32_bf16 v[34:37], v[142:145], v[170:173], v[34:37]
	v_mfma_f32_16x16x32_bf16 v[22:25], v[122:125], v[178:181], v[22:25]
	v_mfma_f32_16x16x32_bf16 v[18:21], v[142:145], v[178:181], v[18:21]
	v_mfma_f32_16x16x32_bf16 v[6:9], v[122:125], v[186:189], v[6:9]
	v_mfma_f32_16x16x32_bf16 v[2:5], v[142:145], v[186:189], v[2:5]
	v_mfma_f32_16x16x32_bf16 v[54:57], v[126:129], v[166:169], v[54:57]
	v_mfma_f32_16x16x32_bf16 v[50:53], v[150:153], v[166:169], v[50:53]
	v_mfma_f32_16x16x32_bf16 v[38:41], v[126:129], v[174:177], v[38:41]
	v_mfma_f32_16x16x32_bf16 v[34:37], v[150:153], v[174:177], v[34:37]
	v_mfma_f32_16x16x32_bf16 v[22:25], v[126:129], v[182:185], v[22:25]
	v_mfma_f32_16x16x32_bf16 v[18:21], v[150:153], v[182:185], v[18:21]
	v_mfma_f32_16x16x32_bf16 v[6:9], v[126:129], v[204:207], v[6:9]
	v_mfma_f32_16x16x32_bf16 v[2:5], v[150:153], v[204:207], v[2:5]
	s_barrier
	s_setprio 0
	s_add_i32 s59, s59, 2
	s_add_u32 s57, s57, 0x100
	s_addc_u32 s58, s58, 0
	s_cmp_gt_u32 s59, 41
	s_mov_b64 s[6:7], s[4:5]
	s_cbranch_scc0 .LBB0_1174
	s_and_b64 vcc, exec, s[22:23]
	s_cbranch_vccz .LBB0_1177
	s_barrier
